# pipelined EpiRes epilogues (loads 2 batches ahead, stores not waited on) for G5/G3; G4 stores without nt; s_setprio removed from GEMM main loops
# speedup vs baseline: 1.0112x; 1.0112x over previous
; #define PG8_STAGE(bufoff, gbase, voff) do { _Pragma("unroll") for (int _i = 0; _i < 2; ++_i) \
;         __builtin_amdgcn_global_load_lds((const unsigned*)((const char*)(gbase) + (voff)[_i]), (LAS unsigned*)(lds + (bufoff) + ldsw + _i * 8192), 16, 0, 0); } while (0)
; #define PG8_LDA(dst, b, h) do { _Pragma("unroll") for (int m = 0; m < 4; ++m) _Pragma("unroll") for (int k = 0; k < 2; ++k) dst[m][k] = *(const LAS bf16x8*)(lds + PG8_SA(b, h) + aoff + m * 2048 + k * 1024); } while (0)
; #define PG8_LDB(dst, b, h) do { _Pragma("unroll") for (int n = 0; n < 2; ++n) _Pragma("unroll") for (int k = 0; k < 2; ++k) dst[n][k] = *(const LAS bf16x8*)(lds + PG8_SB(b, h) + boff + n * 2048 + k * 1024); } while (0)
; #define PG8_WAIT_V(n) asm volatile("s_waitcnt vmcnt(" #n ")" ::: "memory")
; #define PG8_BAR __builtin_amdgcn_s_barrier()
; template <class Epi, class Sched>
; __device__ __forceinline__ void gemm_phase(LAS unsigned char* lds, const Gemm g, const Sched& S, const Epi& E, const int tid) {
;     ...
;         for (int t = 0; t < nt; t += 2) {
;             const bool last = (t == nt - 2);
;             const char* a1 = cA + (size_t)(t + 1) * kstep;
;             const char* a2 = last ? nA : cA + (size_t)(t + 2) * kstep; const char* b2 = last ? nB : cB + (size_t)(t + 2) * kstep;
;             const char* a3 = a2 + kstep; const char* b3 = b2 + kstep;
;             PG8_LDB(B0, 0, 0); PG8_LDB(B1, 0, 1); PG8_SCHED; PG8_LDA(At, 0, 0); PG8_STAGE(PG8_SA(1, 1), a1 + hstepA, voffA);
;             PG8_WAIT_V(8); PG8_WAIT_L(0); PG8_BAR; PG8_MMA(0, 0, At, B0); PG8_MMA(0, 1, At, B1); PG8_BAR; PG8_SCHED;
;             PG8_LDA(At, 0, 1); PG8_STAGE(PG8_SB(0, 0), b2, voffB); PG8_STAGE(PG8_SB(0, 1), b2 + hstepB, voffB); PG8_STAGE(PG8_SA(0, 0), a2, voffA);
;             PG8_WAIT_V(8); PG8_WAIT_L(0); PG8_BAR; PG8_MMA(1, 0, At, B0); PG8_MMA(1, 1, At, B1); PG8_BAR; PG8_SCHED;
;             PG8_LDB(B0, 1, 0); PG8_LDB(B1, 1, 1); PG8_SCHED; PG8_LDA(At, 1, 0); PG8_STAGE(PG8_SA(0, 1), a2 + hstepA, voffA);
;             PG8_WAIT_V(8); PG8_WAIT_L(0); PG8_BAR; PG8_MMA(0, 0, At, B0); PG8_MMA(0, 1, At, B1); PG8_BAR; PG8_SCHED;
;             PG8_LDA(At, 1, 1); PG8_STAGE(PG8_SB(1, 0), b3, voffB); PG8_STAGE(PG8_SB(1, 1), b3 + hstepB, voffB); PG8_STAGE(PG8_SA(1, 0), a3, voffA);
;             PG8_WAIT_V(8); PG8_WAIT_L(0); PG8_BAR; PG8_MMA(1, 0, At, B0); PG8_MMA(1, 1, At, B1); PG8_BAR; PG8_SCHED;
.LBB0_182:
	s_add_u32 s86, s54, 0x100
	s_addc_u32 s87, s55, 0
	s_add_i32 s13, 0, 0x10000
	s_cmpk_eq_i32 s12, 0x5c
	s_cselect_b32 s91, s9, s87
	s_cselect_b32 s90, s8, s86
	s_cselect_b32 s89, s47, s17
	s_cselect_b32 s88, s46, s16
	s_add_i32 s74, 0, 0x14000
	v_add_u32_e32 v150, s13, v204
	v_add_u32_e32 v162, s74, v204
	ds_read_b128 v[138:141], v150
	ds_read_b128 v[142:145], v150 offset:1024
	ds_read_b128 v[146:149], v150 offset:2048
	ds_read_b128 v[150:153], v150 offset:3072
	ds_read_b128 v[154:157], v162
	ds_read_b128 v[158:161], v162 offset:1024
	ds_read_b128 v[174:177], v162 offset:2048
	ds_read_b128 v[178:181], v162 offset:3072
	v_lshl_add_u64 v[162:163], s[54:55], 0, v[134:135]
	s_add_i32 m0, s84, 0xc000
	ds_read_b128 v[182:185], v206
	ds_read_b128 v[186:189], v206 offset:1024
	ds_read_b128 v[190:193], v206 offset:2048
	ds_read_b128 v[194:197], v206 offset:3072
	ds_read_b128 v[198:201], v206 offset:4096
	ds_read_b128 v[210:213], v206 offset:5120
	ds_read_b128 v[220:223], v206 offset:6144
	ds_read_b128 v[234:237], v206 offset:7168
	global_load_lds_dwordx4 v[162:163], off
	v_lshl_add_u64 v[162:163], s[54:55], 0, v[136:137]
	s_add_i32 m0, s84, 0xe000
	s_nop 0
	global_load_lds_dwordx4 v[162:163], off
	s_waitcnt vmcnt(8)
	s_waitcnt lgkmcnt(0)
	s_barrier
	s_waitcnt lgkmcnt(0)
	v_mfma_f32_16x16x32_bf16 v[128:131], v[138:141], v[182:185], v[128:131]
	v_mfma_f32_16x16x32_bf16 v[96:99], v[146:149], v[182:185], v[96:99]
	v_mfma_f32_16x16x32_bf16 v[124:127], v[138:141], v[190:193], v[124:127]
	v_mfma_f32_16x16x32_bf16 v[92:95], v[146:149], v[190:193], v[92:95]
	v_mfma_f32_16x16x32_bf16 v[120:123], v[138:141], v[198:201], v[120:123]
	v_mfma_f32_16x16x32_bf16 v[88:91], v[146:149], v[198:201], v[88:91]
	v_mfma_f32_16x16x32_bf16 v[116:119], v[138:141], v[220:223], v[116:119]
	v_mfma_f32_16x16x32_bf16 v[84:87], v[146:149], v[220:223], v[84:87]
	v_mfma_f32_16x16x32_bf16 v[128:131], v[142:145], v[186:189], v[128:131]
	v_mfma_f32_16x16x32_bf16 v[96:99], v[150:153], v[186:189], v[96:99]
	v_mfma_f32_16x16x32_bf16 v[124:127], v[142:145], v[194:197], v[124:127]
	v_mfma_f32_16x16x32_bf16 v[92:95], v[150:153], v[194:197], v[92:95]
	v_mfma_f32_16x16x32_bf16 v[120:123], v[142:145], v[210:213], v[120:123]
	v_mfma_f32_16x16x32_bf16 v[88:91], v[150:153], v[210:213], v[88:91]
	v_mfma_f32_16x16x32_bf16 v[116:119], v[142:145], v[234:237], v[116:119]
	v_mfma_f32_16x16x32_bf16 v[84:87], v[150:153], v[234:237], v[84:87]
	v_mfma_f32_16x16x32_bf16 v[64:67], v[154:157], v[182:185], v[64:67]
	v_mfma_f32_16x16x32_bf16 v[32:35], v[174:177], v[182:185], v[32:35]
	v_mfma_f32_16x16x32_bf16 v[60:63], v[154:157], v[190:193], v[60:63]
	v_mfma_f32_16x16x32_bf16 v[28:31], v[174:177], v[190:193], v[28:31]
	v_mfma_f32_16x16x32_bf16 v[56:59], v[154:157], v[198:201], v[56:59]
	v_mfma_f32_16x16x32_bf16 v[24:27], v[174:177], v[198:201], v[24:27]
	v_mfma_f32_16x16x32_bf16 v[52:55], v[154:157], v[220:223], v[52:55]
	v_mfma_f32_16x16x32_bf16 v[20:23], v[174:177], v[220:223], v[20:23]
	v_mfma_f32_16x16x32_bf16 v[64:67], v[158:161], v[186:189], v[64:67]
	v_mfma_f32_16x16x32_bf16 v[32:35], v[178:181], v[186:189], v[32:35]
	v_mfma_f32_16x16x32_bf16 v[60:63], v[158:161], v[194:197], v[60:63]
	v_mfma_f32_16x16x32_bf16 v[28:31], v[178:181], v[194:197], v[28:31]
	v_mfma_f32_16x16x32_bf16 v[56:59], v[158:161], v[210:213], v[56:59]
	v_mfma_f32_16x16x32_bf16 v[24:27], v[178:181], v[210:213], v[24:27]
	v_mfma_f32_16x16x32_bf16 v[52:55], v[158:161], v[234:237], v[52:55]
	v_mfma_f32_16x16x32_bf16 v[20:23], v[178:181], v[234:237], v[20:23]
	s_barrier
	s_add_i32 s13, s13, s79
	v_lshl_add_u64 v[162:163], s[88:89], 0, v[164:165]
	s_mov_b32 m0, s13
	ds_read_b128 v[182:185], v206 offset:16384
	ds_read_b128 v[186:189], v206 offset:17408
	ds_read_b128 v[190:193], v206 offset:18432
	ds_read_b128 v[194:197], v206 offset:19456
	ds_read_b128 v[198:201], v206 offset:20480
	ds_read_b128 v[210:213], v206 offset:21504
	ds_read_b128 v[220:223], v206 offset:22528
	ds_read_b128 v[234:237], v206 offset:23552
	global_load_lds_dwordx4 v[162:163], off
	s_add_i32 m0, s13, 0x2000
	s_add_u32 s54, s88, 0x180000
	v_lshl_add_u64 v[202:203], s[88:89], 0, v[132:133]
	s_addc_u32 s55, s89, 0
	s_add_i32 s13, s74, s79
	global_load_lds_dwordx4 v[202:203], off
	v_lshl_add_u64 v[224:225], s[54:55], 0, v[164:165]
	s_mov_b32 m0, s13
	v_lshl_add_u64 v[226:227], s[90:91], 0, v[132:133]
	global_load_lds_dwordx4 v[224:225], off
	v_lshl_add_u64 v[224:225], s[54:55], 0, v[132:133]
	s_add_i32 m0, s13, 0x2000
	s_nop 0
	global_load_lds_dwordx4 v[224:225], off
	v_lshl_add_u64 v[224:225], s[90:91], 0, v[164:165]
	s_mov_b32 m0, s84
	s_nop 0
	global_load_lds_dwordx4 v[224:225], off
	s_mov_b32 m0, s85
	s_nop 0
	global_load_lds_dwordx4 v[226:227], off
	s_waitcnt vmcnt(8)
	s_waitcnt lgkmcnt(0)
	s_barrier
; #define PG8_STAGE(bufoff, gbase, voff) do { _Pragma("unroll") for (int _i = 0; _i < 2; ++_i) \
;         __builtin_amdgcn_global_load_lds((const unsigned*)((const char*)(gbase) + (voff)[_i]), (LAS unsigned*)(lds + (bufoff) + ldsw + _i * 8192), 16, 0, 0); } while (0)
; #define PG8_LDA(dst, b, h) do { _Pragma("unroll") for (int m = 0; m < 4; ++m) _Pragma("unroll") for (int k = 0; k < 2; ++k) dst[m][k] = *(const LAS bf16x8*)(lds + PG8_SA(b, h) + aoff + m * 2048 + k * 1024); } while (0)
; #define PG8_LDB(dst, b, h) do { _Pragma("unroll") for (int n = 0; n < 2; ++n) _Pragma("unroll") for (int k = 0; k < 2; ++k) dst[n][k] = *(const LAS bf16x8*)(lds + PG8_SB(b, h) + boff + n * 2048 + k * 1024); } while (0)
; #define PG8_MMA(ai, bj, At, Bt) do { __builtin_amdgcn_s_setprio(1); _Pragma("unroll") for (int m = 0; m < 4; ++m) _Pragma("unroll") for (int n = 0; n < 2; ++n) _Pragma("unroll") for (int k = 0; k < 2; ++k) \
;         acc[ai][bj][m][n] = __builtin_amdgcn_mfma_f32_16x16x32_bf16(Bt[n][k], At[m][k], acc[ai][bj][m][n], 0, 0, 0); __builtin_amdgcn_s_setprio(0); } while (0)
; #define PG8_WAIT_V(n) asm volatile("s_waitcnt vmcnt(" #n ")" ::: "memory")
; template <class Epi, class Sched>
; __device__ __forceinline__ void gemm_phase(LAS unsigned char* lds, const Gemm g, const Sched& S, const Epi& E, const int tid) {
;     ...
;             PG8_LDB(B0, 0, 0); PG8_LDB(B1, 0, 1); PG8_SCHED; PG8_LDA(At, 0, 0); PG8_STAGE(PG8_SA(1, 1), a1 + hstepA, voffA);
;             PG8_WAIT_V(8); PG8_WAIT_L(0); PG8_BAR; PG8_MMA(0, 0, At, B0); PG8_MMA(0, 1, At, B1); PG8_BAR; PG8_SCHED;
;             PG8_LDA(At, 0, 1); PG8_STAGE(PG8_SB(0, 0), b2, voffB); PG8_STAGE(PG8_SB(0, 1), b2 + hstepB, voffB); PG8_STAGE(PG8_SA(0, 0), a2, voffA);
;             PG8_WAIT_V(8); PG8_WAIT_L(0); PG8_BAR; PG8_MMA(1, 0, At, B0); PG8_MMA(1, 1, At, B1); PG8_BAR; PG8_SCHED;
;             PG8_LDB(B0, 1, 0); PG8_LDB(B1, 1, 1); PG8_SCHED; PG8_LDA(At, 1, 0); PG8_STAGE(PG8_SA(0, 1), a2 + hstepA, voffA);
;             PG8_WAIT_V(8); PG8_WAIT_L(0); PG8_BAR; PG8_MMA(0, 0, At, B0); PG8_MMA(0, 1, At, B1); PG8_BAR; PG8_SCHED;
;             PG8_LDA(At, 1, 1); PG8_STAGE(PG8_SB(1, 0), b3, voffB); PG8_STAGE(PG8_SB(1, 1), b3 + hstepB, voffB); PG8_STAGE(PG8_SA(1, 0), a3, voffA);
;             PG8_WAIT_V(8); PG8_WAIT_L(0); PG8_BAR; PG8_MMA(1, 0, At, B0); PG8_MMA(1, 1, At, B1); PG8_BAR; PG8_SCHED;
	s_waitcnt lgkmcnt(0)
	v_mfma_f32_16x16x32_bf16 v[112:115], v[138:141], v[182:185], v[112:115]
	v_mfma_f32_16x16x32_bf16 v[80:83], v[146:149], v[182:185], v[80:83]
	v_mfma_f32_16x16x32_bf16 v[108:111], v[138:141], v[190:193], v[108:111]
	v_mfma_f32_16x16x32_bf16 v[76:79], v[146:149], v[190:193], v[76:79]
	v_mfma_f32_16x16x32_bf16 v[104:107], v[138:141], v[198:201], v[104:107]
	v_mfma_f32_16x16x32_bf16 v[72:75], v[146:149], v[198:201], v[72:75]
	v_mfma_f32_16x16x32_bf16 v[100:103], v[138:141], v[220:223], v[100:103]
	v_mfma_f32_16x16x32_bf16 v[68:71], v[146:149], v[220:223], v[68:71]
	v_mfma_f32_16x16x32_bf16 v[112:115], v[142:145], v[186:189], v[112:115]
	v_mfma_f32_16x16x32_bf16 v[80:83], v[150:153], v[186:189], v[80:83]
	v_mfma_f32_16x16x32_bf16 v[108:111], v[142:145], v[194:197], v[108:111]
	v_mfma_f32_16x16x32_bf16 v[76:79], v[150:153], v[194:197], v[76:79]
	v_mfma_f32_16x16x32_bf16 v[104:107], v[142:145], v[210:213], v[104:107]
	v_mfma_f32_16x16x32_bf16 v[72:75], v[150:153], v[210:213], v[72:75]
	v_mfma_f32_16x16x32_bf16 v[100:103], v[142:145], v[234:237], v[100:103]
	v_mfma_f32_16x16x32_bf16 v[68:71], v[150:153], v[234:237], v[68:71]
	v_mfma_f32_16x16x32_bf16 v[48:51], v[154:157], v[182:185], v[48:51]
	v_mfma_f32_16x16x32_bf16 v[16:19], v[174:177], v[182:185], v[16:19]
	v_mfma_f32_16x16x32_bf16 v[44:47], v[154:157], v[190:193], v[44:47]
	v_mfma_f32_16x16x32_bf16 v[12:15], v[174:177], v[190:193], v[12:15]
	v_mfma_f32_16x16x32_bf16 v[40:43], v[154:157], v[198:201], v[40:43]
	v_mfma_f32_16x16x32_bf16 v[8:11], v[174:177], v[198:201], v[8:11]
	v_mfma_f32_16x16x32_bf16 v[36:39], v[154:157], v[220:223], v[36:39]
	v_mfma_f32_16x16x32_bf16 v[4:7], v[174:177], v[220:223], v[4:7]
	v_mfma_f32_16x16x32_bf16 v[48:51], v[158:161], v[186:189], v[48:51]
	v_mfma_f32_16x16x32_bf16 v[16:19], v[178:181], v[186:189], v[16:19]
	v_mfma_f32_16x16x32_bf16 v[44:47], v[158:161], v[194:197], v[44:47]
	v_mfma_f32_16x16x32_bf16 v[12:15], v[178:181], v[194:197], v[12:15]
	v_mfma_f32_16x16x32_bf16 v[40:43], v[158:161], v[210:213], v[40:43]
	v_mfma_f32_16x16x32_bf16 v[8:11], v[178:181], v[210:213], v[8:11]
	v_mfma_f32_16x16x32_bf16 v[36:39], v[158:161], v[234:237], v[36:39]
	v_mfma_f32_16x16x32_bf16 v[4:7], v[178:181], v[234:237], v[4:7]
	s_barrier
	s_add_i32 s13, 0, 0x18000
	s_add_i32 s74, 0, 0x1c000
	v_add_u32_e32 v150, s13, v204
	v_add_u32_e32 v178, s74, v204
	ds_read_b128 v[138:141], v150
	ds_read_b128 v[142:145], v150 offset:1024
	ds_read_b128 v[146:149], v150 offset:2048
	ds_read_b128 v[150:153], v150 offset:3072
	ds_read_b128 v[154:157], v178
	ds_read_b128 v[158:161], v178 offset:1024
	ds_read_b128 v[174:177], v178 offset:2048
	ds_read_b128 v[178:181], v178 offset:3072
	s_add_u32 s54, s90, 0x180000
	s_addc_u32 s55, s91, 0
	s_mov_b32 m0, s92
	v_lshl_add_u64 v[238:239], s[54:55], 0, v[164:165]
	ds_read_b128 v[182:185], v206 offset:32768
	ds_read_b128 v[186:189], v206 offset:33792
	ds_read_b128 v[190:193], v206 offset:34816
	ds_read_b128 v[194:197], v206 offset:35840
	ds_read_b128 v[198:201], v206 offset:36864
	ds_read_b128 v[210:213], v206 offset:37888
	ds_read_b128 v[220:223], v206 offset:38912
	ds_read_b128 v[234:237], v206 offset:39936
	global_load_lds_dwordx4 v[238:239], off
	v_lshl_add_u64 v[238:239], s[54:55], 0, v[132:133]
	s_mov_b32 m0, s93
	s_nop 0
	global_load_lds_dwordx4 v[238:239], off
	s_waitcnt vmcnt(8)
	s_waitcnt lgkmcnt(0)
	s_barrier
	s_waitcnt lgkmcnt(0)
	v_mfma_f32_16x16x32_bf16 v[128:131], v[138:141], v[182:185], v[128:131]
	v_mfma_f32_16x16x32_bf16 v[96:99], v[146:149], v[182:185], v[96:99]
	v_mfma_f32_16x16x32_bf16 v[124:127], v[138:141], v[190:193], v[124:127]
	v_mfma_f32_16x16x32_bf16 v[92:95], v[146:149], v[190:193], v[92:95]
	v_mfma_f32_16x16x32_bf16 v[120:123], v[138:141], v[198:201], v[120:123]
	v_mfma_f32_16x16x32_bf16 v[88:91], v[146:149], v[198:201], v[88:91]
	v_mfma_f32_16x16x32_bf16 v[116:119], v[138:141], v[220:223], v[116:119]
	v_mfma_f32_16x16x32_bf16 v[84:87], v[146:149], v[220:223], v[84:87]
	v_mfma_f32_16x16x32_bf16 v[128:131], v[142:145], v[186:189], v[128:131]
	v_mfma_f32_16x16x32_bf16 v[96:99], v[150:153], v[186:189], v[96:99]
	v_mfma_f32_16x16x32_bf16 v[124:127], v[142:145], v[194:197], v[124:127]
	v_mfma_f32_16x16x32_bf16 v[92:95], v[150:153], v[194:197], v[92:95]
	v_mfma_f32_16x16x32_bf16 v[120:123], v[142:145], v[210:213], v[120:123]
	v_mfma_f32_16x16x32_bf16 v[88:91], v[150:153], v[210:213], v[88:91]
	v_mfma_f32_16x16x32_bf16 v[116:119], v[142:145], v[234:237], v[116:119]
	v_mfma_f32_16x16x32_bf16 v[84:87], v[150:153], v[234:237], v[84:87]
	v_mfma_f32_16x16x32_bf16 v[64:67], v[154:157], v[182:185], v[64:67]
	v_mfma_f32_16x16x32_bf16 v[32:35], v[174:177], v[182:185], v[32:35]
	v_mfma_f32_16x16x32_bf16 v[60:63], v[154:157], v[190:193], v[60:63]
	v_mfma_f32_16x16x32_bf16 v[28:31], v[174:177], v[190:193], v[28:31]
	v_mfma_f32_16x16x32_bf16 v[56:59], v[154:157], v[198:201], v[56:59]
	v_mfma_f32_16x16x32_bf16 v[24:27], v[174:177], v[198:201], v[24:27]
	v_mfma_f32_16x16x32_bf16 v[52:55], v[154:157], v[220:223], v[52:55]
	v_mfma_f32_16x16x32_bf16 v[20:23], v[174:177], v[220:223], v[20:23]
	v_mfma_f32_16x16x32_bf16 v[64:67], v[158:161], v[186:189], v[64:67]
	v_mfma_f32_16x16x32_bf16 v[32:35], v[178:181], v[186:189], v[32:35]
	v_mfma_f32_16x16x32_bf16 v[60:63], v[158:161], v[194:197], v[60:63]
	v_mfma_f32_16x16x32_bf16 v[28:31], v[178:181], v[194:197], v[28:31]
	v_mfma_f32_16x16x32_bf16 v[56:59], v[158:161], v[210:213], v[56:59]
	v_mfma_f32_16x16x32_bf16 v[24:27], v[178:181], v[210:213], v[24:27]
	v_mfma_f32_16x16x32_bf16 v[52:55], v[158:161], v[234:237], v[52:55]
	v_mfma_f32_16x16x32_bf16 v[20:23], v[178:181], v[234:237], v[20:23]
	s_barrier
; #define PG8_STAGE(bufoff, gbase, voff) do { _Pragma("unroll") for (int _i = 0; _i < 2; ++_i) \
;         __builtin_amdgcn_global_load_lds((const unsigned*)((const char*)(gbase) + (voff)[_i]), (LAS unsigned*)(lds + (bufoff) + ldsw + _i * 8192), 16, 0, 0); } while (0)
; #define PG8_LDA(dst, b, h) do { _Pragma("unroll") for (int m = 0; m < 4; ++m) _Pragma("unroll") for (int k = 0; k < 2; ++k) dst[m][k] = *(const LAS bf16x8*)(lds + PG8_SA(b, h) + aoff + m * 2048 + k * 1024); } while (0)
; #define PG8_LDB(dst, b, h) do { _Pragma("unroll") for (int n = 0; n < 2; ++n) _Pragma("unroll") for (int k = 0; k < 2; ++k) dst[n][k] = *(const LAS bf16x8*)(lds + PG8_SB(b, h) + boff + n * 2048 + k * 1024); } while (0)
; template <class Epi, class Sched>
; __device__ __forceinline__ void gemm_phase(LAS unsigned char* lds, const Gemm g, const Sched& S, const Epi& E, const int tid) {
;     ...
;             PG8_LDB(B0, 1, 0); PG8_LDB(B1, 1, 1); PG8_SCHED; PG8_LDA(At, 1, 0); PG8_STAGE(PG8_SA(0, 1), a2 + hstepA, voffA);
;             PG8_WAIT_V(8); PG8_WAIT_L(0); PG8_BAR; PG8_MMA(0, 0, At, B0); PG8_MMA(0, 1, At, B1); PG8_BAR; PG8_SCHED;
;             PG8_LDA(At, 1, 1); PG8_STAGE(PG8_SB(1, 0), b3, voffB); PG8_STAGE(PG8_SB(1, 1), b3 + hstepB, voffB); PG8_STAGE(PG8_SA(1, 0), a3, voffA);
;             PG8_WAIT_V(8); PG8_WAIT_L(0); PG8_BAR; PG8_MMA(1, 0, At, B0); PG8_MMA(1, 1, At, B1); PG8_BAR; PG8_SCHED;
;         }
;         if (wr == 0) PG8_BAR;
;     __device__ __forceinline__ void operator()(const f32x4 (&acc)[2][2][4][2], const Unit& u, int wr, int wc, int fr, int fq) const {
;         const int row0 = u.pm * BM + wr * 64 + fr; const int col0 = u.pn * BM + wc * 32 + 4 * fq;
; #pragma unroll
;         for (int bj = 0; bj < 2; ++bj)
; #pragma unroll
;             for (int n = 0; n < 2; ++n) {
;                 const int col = col0 + bj * HALF + n * 16;
;                 f32x4 gg = {1.f, 1.f, 1.f, 1.f}, bb = {0.f, 0.f, 0.f, 0.f};
;                 if (NORM) { gg = *(const f32x4*)(gam + col); bb = *(const f32x4*)(bet + col); }
; #pragma unroll
;                 for (int ai = 0; ai < 2; ++ai) {
;                     f32x4 xv[4]; f32x2 st[4];
; #pragma unroll
;                     for (int m = 0; m < 4; ++m) { xv[m] = *(const f32x4*)(X + (size_t)(row0 + ai * HALF + m * 16) * D + col);
;                         if (NORM) st[m] = *(const f32x2*)(stats + 2 * (row0 + ai * HALF + m * 16)); }
	s_add_i32 s13, s13, s79
	v_lshl_add_u64 v[162:163], v[162:163], 0, s[28:29]
	s_mov_b32 m0, s13
	ds_read_b128 v[182:185], v206 offset:49152
	ds_read_b128 v[186:189], v206 offset:50176
	ds_read_b128 v[190:193], v206 offset:51200
	ds_read_b128 v[194:197], v206 offset:52224
	ds_read_b128 v[198:201], v206 offset:53248
	ds_read_b128 v[210:213], v206 offset:54272
	ds_read_b128 v[220:223], v206 offset:55296
	ds_read_b128 v[234:237], v206 offset:56320
	global_load_lds_dwordx4 v[162:163], off
	s_add_i32 m0, s13, 0x2000
	s_add_u32 s54, s88, 0x180080
	v_lshl_add_u64 v[162:163], v[202:203], 0, s[28:29]
	s_addc_u32 s55, s89, 0
	s_add_i32 s13, s74, s79
	global_load_lds_dwordx4 v[162:163], off
	v_lshl_add_u64 v[162:163], s[54:55], 0, v[164:165]
	s_mov_b32 m0, s13
	s_nop 0
	global_load_lds_dwordx4 v[162:163], off
	v_lshl_add_u64 v[162:163], s[54:55], 0, v[132:133]
	s_add_i32 m0, s13, 0x2000
	s_nop 0
	global_load_lds_dwordx4 v[162:163], off
	v_lshl_add_u64 v[162:163], v[224:225], 0, s[28:29]
	s_mov_b32 m0, s94
	s_nop 0
	global_load_lds_dwordx4 v[162:163], off
	v_lshl_add_u64 v[162:163], v[226:227], 0, s[28:29]
	s_mov_b32 m0, s95
	s_nop 0
	global_load_lds_dwordx4 v[162:163], off
	s_waitcnt vmcnt(8)
	s_waitcnt lgkmcnt(0)
	s_barrier
	s_waitcnt lgkmcnt(0)
	v_mfma_f32_16x16x32_bf16 v[112:115], v[138:141], v[182:185], v[112:115]
	v_mfma_f32_16x16x32_bf16 v[80:83], v[146:149], v[182:185], v[80:83]
	v_mfma_f32_16x16x32_bf16 v[108:111], v[138:141], v[190:193], v[108:111]
	v_mfma_f32_16x16x32_bf16 v[76:79], v[146:149], v[190:193], v[76:79]
	v_mfma_f32_16x16x32_bf16 v[104:107], v[138:141], v[198:201], v[104:107]
	v_mfma_f32_16x16x32_bf16 v[72:75], v[146:149], v[198:201], v[72:75]
	v_mfma_f32_16x16x32_bf16 v[100:103], v[138:141], v[220:223], v[100:103]
	v_mfma_f32_16x16x32_bf16 v[68:71], v[146:149], v[220:223], v[68:71]
	v_mfma_f32_16x16x32_bf16 v[112:115], v[142:145], v[186:189], v[112:115]
	v_mfma_f32_16x16x32_bf16 v[80:83], v[150:153], v[186:189], v[80:83]
	v_mfma_f32_16x16x32_bf16 v[108:111], v[142:145], v[194:197], v[108:111]
	v_mfma_f32_16x16x32_bf16 v[76:79], v[150:153], v[194:197], v[76:79]
	v_mfma_f32_16x16x32_bf16 v[104:107], v[142:145], v[210:213], v[104:107]
	v_mfma_f32_16x16x32_bf16 v[72:75], v[150:153], v[210:213], v[72:75]
	v_mfma_f32_16x16x32_bf16 v[100:103], v[142:145], v[234:237], v[100:103]
	v_mfma_f32_16x16x32_bf16 v[68:71], v[150:153], v[234:237], v[68:71]
	v_mfma_f32_16x16x32_bf16 v[48:51], v[154:157], v[182:185], v[48:51]
	v_mfma_f32_16x16x32_bf16 v[16:19], v[174:177], v[182:185], v[16:19]
	v_mfma_f32_16x16x32_bf16 v[44:47], v[154:157], v[190:193], v[44:47]
	v_mfma_f32_16x16x32_bf16 v[12:15], v[174:177], v[190:193], v[12:15]
	v_mfma_f32_16x16x32_bf16 v[40:43], v[154:157], v[198:201], v[40:43]
	v_mfma_f32_16x16x32_bf16 v[8:11], v[174:177], v[198:201], v[8:11]
	v_mfma_f32_16x16x32_bf16 v[36:39], v[154:157], v[220:223], v[36:39]
	v_mfma_f32_16x16x32_bf16 v[4:7], v[174:177], v[220:223], v[4:7]
	v_mfma_f32_16x16x32_bf16 v[48:51], v[158:161], v[186:189], v[48:51]
	v_mfma_f32_16x16x32_bf16 v[16:19], v[178:181], v[186:189], v[16:19]
	v_mfma_f32_16x16x32_bf16 v[44:47], v[158:161], v[194:197], v[44:47]
	v_mfma_f32_16x16x32_bf16 v[12:15], v[178:181], v[194:197], v[12:15]
	v_mfma_f32_16x16x32_bf16 v[40:43], v[158:161], v[210:213], v[40:43]
	v_mfma_f32_16x16x32_bf16 v[8:11], v[178:181], v[210:213], v[8:11]
	v_mfma_f32_16x16x32_bf16 v[36:39], v[158:161], v[234:237], v[36:39]
	v_mfma_f32_16x16x32_bf16 v[4:7], v[178:181], v[234:237], v[4:7]
	s_barrier
	s_add_i32 s12, s12, 2
	s_add_u32 s16, s16, 0x100
	s_addc_u32 s17, s17, 0
	s_cmpk_gt_u32 s12, 0x5d
	s_mov_b64 s[54:55], s[86:87]
	s_cbranch_scc0 .LBB0_182
	s_and_b64 vcc, exec, s[44:45]
	s_cbranch_vccz .LBB0_185
	s_barrier
.LBB0_185:
	v_lshl_add_u32 v225, s31, 8, v171
	v_lshl_or_b32 v226, s30, 8, v205
	v_lshlrev_b32_e32 v227, 3, v225
	v_lshlrev_b32_e32 v234, 2, v226
	v_lshl_add_u32 v224, v225, 13, v234
	global_load_dwordx2 v[162:163], v227, s[38:39]
	global_load_dwordx2 v[182:183], v227, s[38:39] offset:128
	global_load_dwordx2 v[184:185], v227, s[38:39] offset:256
	global_load_dwordx2 v[186:187], v227, s[38:39] offset:384
	global_load_dwordx2 v[188:189], v227, s[38:39] offset:1024
	global_load_dwordx2 v[190:191], v227, s[38:39] offset:1152
	global_load_dwordx2 v[192:193], v227, s[38:39] offset:1280
	global_load_dwordx2 v[194:195], v227, s[38:39] offset:1408
	global_load_dwordx4 v[196:199], v234, s[42:43]
	global_load_dwordx4 v[200:203], v234, s[10:11]
	global_load_dwordx4 v[210:213], v234, s[42:43] offset:64
	global_load_dwordx4 v[220:223], v234, s[10:11] offset:64
	global_load_dwordx4 v[138:141], v224, s[14:15]
	v_add_u32_e32 v226, 0x20000, v224
	global_load_dwordx4 v[142:145], v226, s[14:15]
	v_add_u32_e32 v225, 0x40000, v224
	global_load_dwordx4 v[146:149], v225, s[14:15]
	v_add_u32_e32 v226, 0x60000, v224
	global_load_dwordx4 v[150:153], v226, s[14:15]
	v_add_u32_e32 v225, 0x100000, v224
	global_load_dwordx4 v[154:157], v225, s[14:15]
	v_add_u32_e32 v226, 0x120000, v224
	global_load_dwordx4 v[158:161], v226, s[14:15]
	v_add_u32_e32 v225, 0x140000, v224
	global_load_dwordx4 v[174:177], v225, s[14:15]
	v_add_u32_e32 v226, 0x160000, v224
	global_load_dwordx4 v[178:181], v226, s[14:15]
	s_waitcnt vmcnt(4)
;     __device__ __forceinline__ void operator()(const f32x4 (&acc)[2][2][4][2], const Unit& u, int wr, int wc, int fr, int fq) const {
;     ...
;         for (int bj = 0; bj < 2; ++bj)
; #pragma unroll
;             for (int n = 0; n < 2; ++n) {
;                 const int col = col0 + bj * HALF + n * 16;
;                 f32x4 gg = {1.f, 1.f, 1.f, 1.f}, bb = {0.f, 0.f, 0.f, 0.f};
;                 if (NORM) { gg = *(const f32x4*)(gam + col); bb = *(const f32x4*)(bet + col); }
; #pragma unroll
;                 for (int ai = 0; ai < 2; ++ai) {
;                     f32x4 xv[4]; f32x2 st[4];
; #pragma unroll
;                     for (int m = 0; m < 4; ++m) { xv[m] = *(const f32x4*)(X + (size_t)(row0 + ai * HALF + m * 16) * D + col);
;                         if (NORM) st[m] = *(const f32x2*)(stats + 2 * (row0 + ai * HALF + m * 16)); }
; #pragma unroll
;                     for (int m = 0; m < 4; ++m) {
;                         f32x4 x = xv[m];
;                         if (NORM) x = (x - st[m].x) * st[m].y * gg + bb;
;                         if (!dry) *(f32x4*)(X + (size_t)(row0 + ai * HALF + m * 16) * D + col) = x * ALPHA + acc[ai][bj][m][n];
;                     }
;                 }
	v_sub_f32_e32 v139, v139, v162
	v_sub_f32_e32 v138, v138, v162
	v_sub_f32_e32 v141, v141, v162
	v_sub_f32_e32 v140, v140, v162
	v_pk_mul_f32 v[140:141], v[162:163], v[140:141] op_sel:[1,0]
	v_pk_mul_f32 v[138:139], v[162:163], v[138:139] op_sel:[1,0]
	v_pk_fma_f32 v[138:139], v[196:197], v[138:139], v[200:201]
	v_pk_fma_f32 v[140:141], v[198:199], v[140:141], v[202:203]
	v_pk_fma_f32 v[130:131], v[140:141], s[34:35], v[130:131] op_sel_hi:[1,0,1]
	v_pk_fma_f32 v[128:129], v[138:139], s[34:35], v[128:129] op_sel_hi:[1,0,1]
	v_sub_f32_e32 v143, v143, v182
	v_sub_f32_e32 v142, v142, v182
	v_sub_f32_e32 v145, v145, v182
	v_sub_f32_e32 v144, v144, v182
	v_pk_mul_f32 v[144:145], v[182:183], v[144:145] op_sel:[1,0]
	v_pk_mul_f32 v[142:143], v[182:183], v[142:143] op_sel:[1,0]
	v_pk_fma_f32 v[142:143], v[196:197], v[142:143], v[200:201]
	v_pk_fma_f32 v[144:145], v[198:199], v[144:145], v[202:203]
	v_pk_fma_f32 v[126:127], v[144:145], s[34:35], v[126:127] op_sel_hi:[1,0,1]
	v_pk_fma_f32 v[124:125], v[142:143], s[34:35], v[124:125] op_sel_hi:[1,0,1]
	v_sub_f32_e32 v147, v147, v184
	v_sub_f32_e32 v146, v146, v184
	v_sub_f32_e32 v149, v149, v184
	v_sub_f32_e32 v148, v148, v184
	v_pk_mul_f32 v[148:149], v[184:185], v[148:149] op_sel:[1,0]
	v_pk_mul_f32 v[146:147], v[184:185], v[146:147] op_sel:[1,0]
	v_pk_fma_f32 v[146:147], v[196:197], v[146:147], v[200:201]
	v_pk_fma_f32 v[148:149], v[198:199], v[148:149], v[202:203]
	v_pk_fma_f32 v[122:123], v[148:149], s[34:35], v[122:123] op_sel_hi:[1,0,1]
	v_pk_fma_f32 v[120:121], v[146:147], s[34:35], v[120:121] op_sel_hi:[1,0,1]
	v_sub_f32_e32 v151, v151, v186
	v_sub_f32_e32 v150, v150, v186
	v_sub_f32_e32 v153, v153, v186
	v_sub_f32_e32 v152, v152, v186
	v_pk_mul_f32 v[152:153], v[186:187], v[152:153] op_sel:[1,0]
	v_pk_mul_f32 v[150:151], v[186:187], v[150:151] op_sel:[1,0]
	v_pk_fma_f32 v[150:151], v[196:197], v[150:151], v[200:201]
	v_pk_fma_f32 v[152:153], v[198:199], v[152:153], v[202:203]
	v_pk_fma_f32 v[118:119], v[152:153], s[34:35], v[118:119] op_sel_hi:[1,0,1]
	v_pk_fma_f32 v[116:117], v[150:151], s[34:35], v[116:117] op_sel_hi:[1,0,1]
	global_load_dwordx4 v[138:141], v224, s[14:15] offset:64
	v_add_u32_e32 v226, 0x20000, v224
	global_load_dwordx4 v[142:145], v226, s[14:15] offset:64
	v_add_u32_e32 v225, 0x40000, v224
	global_load_dwordx4 v[146:149], v225, s[14:15] offset:64
	v_add_u32_e32 v226, 0x60000, v224
	global_load_dwordx4 v[150:153], v226, s[14:15] offset:64
	global_store_dwordx4 v224, v[128:131], s[14:15]
	v_add_u32_e32 v226, 0x20000, v224
	global_store_dwordx4 v226, v[124:127], s[14:15]
	v_add_u32_e32 v225, 0x40000, v224
	global_store_dwordx4 v225, v[120:123], s[14:15]
	v_add_u32_e32 v226, 0x60000, v224
	global_store_dwordx4 v226, v[116:119], s[14:15]
	s_waitcnt vmcnt(8)
	v_sub_f32_e32 v155, v155, v188
	v_sub_f32_e32 v154, v154, v188
	v_sub_f32_e32 v157, v157, v188
	v_sub_f32_e32 v156, v156, v188
	v_pk_mul_f32 v[156:157], v[188:189], v[156:157] op_sel:[1,0]
	v_pk_mul_f32 v[154:155], v[188:189], v[154:155] op_sel:[1,0]
	v_pk_fma_f32 v[154:155], v[196:197], v[154:155], v[200:201]
	v_pk_fma_f32 v[156:157], v[198:199], v[156:157], v[202:203]
	v_pk_fma_f32 v[114:115], v[156:157], s[34:35], v[114:115] op_sel_hi:[1,0,1]
	v_pk_fma_f32 v[112:113], v[154:155], s[34:35], v[112:113] op_sel_hi:[1,0,1]
	v_sub_f32_e32 v159, v159, v190
	v_sub_f32_e32 v158, v158, v190
	v_sub_f32_e32 v161, v161, v190
	v_sub_f32_e32 v160, v160, v190
	v_pk_mul_f32 v[160:161], v[190:191], v[160:161] op_sel:[1,0]
	v_pk_mul_f32 v[158:159], v[190:191], v[158:159] op_sel:[1,0]
	v_pk_fma_f32 v[158:159], v[196:197], v[158:159], v[200:201]
	v_pk_fma_f32 v[160:161], v[198:199], v[160:161], v[202:203]
	v_pk_fma_f32 v[110:111], v[160:161], s[34:35], v[110:111] op_sel_hi:[1,0,1]
	v_pk_fma_f32 v[108:109], v[158:159], s[34:35], v[108:109] op_sel_hi:[1,0,1]
	v_sub_f32_e32 v175, v175, v192
	v_sub_f32_e32 v174, v174, v192
	v_sub_f32_e32 v177, v177, v192
	v_sub_f32_e32 v176, v176, v192
	v_pk_mul_f32 v[176:177], v[192:193], v[176:177] op_sel:[1,0]
	v_pk_mul_f32 v[174:175], v[192:193], v[174:175] op_sel:[1,0]
	v_pk_fma_f32 v[174:175], v[196:197], v[174:175], v[200:201]
	v_pk_fma_f32 v[176:177], v[198:199], v[176:177], v[202:203]
	v_pk_fma_f32 v[106:107], v[176:177], s[34:35], v[106:107] op_sel_hi:[1,0,1]
	v_pk_fma_f32 v[104:105], v[174:175], s[34:35], v[104:105] op_sel_hi:[1,0,1]
	v_sub_f32_e32 v179, v179, v194
	v_sub_f32_e32 v178, v178, v194
	v_sub_f32_e32 v181, v181, v194
	v_sub_f32_e32 v180, v180, v194
	v_pk_mul_f32 v[180:181], v[194:195], v[180:181] op_sel:[1,0]
	v_pk_mul_f32 v[178:179], v[194:195], v[178:179] op_sel:[1,0]
	v_pk_fma_f32 v[178:179], v[196:197], v[178:179], v[200:201]
	v_pk_fma_f32 v[180:181], v[198:199], v[180:181], v[202:203]
	v_pk_fma_f32 v[102:103], v[180:181], s[34:35], v[102:103] op_sel_hi:[1,0,1]
	v_pk_fma_f32 v[100:101], v[178:179], s[34:35], v[100:101] op_sel_hi:[1,0,1]
	global_load_dwordx4 v[196:199], v234, s[42:43] offset:512
	global_load_dwordx4 v[200:203], v234, s[10:11] offset:512
	v_add_u32_e32 v225, 0x100000, v224
	global_load_dwordx4 v[154:157], v225, s[14:15] offset:64
	v_add_u32_e32 v226, 0x120000, v224
	global_load_dwordx4 v[158:161], v226, s[14:15] offset:64
	v_add_u32_e32 v225, 0x140000, v224
	global_load_dwordx4 v[174:177], v225, s[14:15] offset:64
	v_add_u32_e32 v226, 0x160000, v224
	global_load_dwordx4 v[178:181], v226, s[14:15] offset:64
	v_add_u32_e32 v225, 0x100000, v224
	global_store_dwordx4 v225, v[112:115], s[14:15]
	v_add_u32_e32 v226, 0x120000, v224
	global_store_dwordx4 v226, v[108:111], s[14:15]
	v_add_u32_e32 v225, 0x140000, v224
	global_store_dwordx4 v225, v[104:107], s[14:15]
	v_add_u32_e32 v226, 0x160000, v224
	global_store_dwordx4 v226, v[100:103], s[14:15]
	s_waitcnt vmcnt(14)
;     __device__ __forceinline__ void operator()(const f32x4 (&acc)[2][2][4][2], const Unit& u, int wr, int wc, int fr, int fq) const {
;     ...
;         for (int bj = 0; bj < 2; ++bj)
; #pragma unroll
;             for (int n = 0; n < 2; ++n) {
;                 const int col = col0 + bj * HALF + n * 16;
;                 f32x4 gg = {1.f, 1.f, 1.f, 1.f}, bb = {0.f, 0.f, 0.f, 0.f};
;                 if (NORM) { gg = *(const f32x4*)(gam + col); bb = *(const f32x4*)(bet + col); }
; #pragma unroll
;                 for (int ai = 0; ai < 2; ++ai) {
;                     f32x4 xv[4]; f32x2 st[4];
; #pragma unroll
;                     for (int m = 0; m < 4; ++m) { xv[m] = *(const f32x4*)(X + (size_t)(row0 + ai * HALF + m * 16) * D + col);
;                         if (NORM) st[m] = *(const f32x2*)(stats + 2 * (row0 + ai * HALF + m * 16)); }
; #pragma unroll
;                     for (int m = 0; m < 4; ++m) {
;                         f32x4 x = xv[m];
;                         if (NORM) x = (x - st[m].x) * st[m].y * gg + bb;
;                         if (!dry) *(f32x4*)(X + (size_t)(row0 + ai * HALF + m * 16) * D + col) = x * ALPHA + acc[ai][bj][m][n];
;                     }
;                 }
	v_sub_f32_e32 v139, v139, v162
	v_sub_f32_e32 v138, v138, v162
	v_sub_f32_e32 v141, v141, v162
	v_sub_f32_e32 v140, v140, v162
	v_pk_mul_f32 v[140:141], v[162:163], v[140:141] op_sel:[1,0]
	v_pk_mul_f32 v[138:139], v[162:163], v[138:139] op_sel:[1,0]
	v_pk_fma_f32 v[138:139], v[210:211], v[138:139], v[220:221]
	v_pk_fma_f32 v[140:141], v[212:213], v[140:141], v[222:223]
	v_pk_fma_f32 v[98:99], v[140:141], s[34:35], v[98:99] op_sel_hi:[1,0,1]
	v_pk_fma_f32 v[96:97], v[138:139], s[34:35], v[96:97] op_sel_hi:[1,0,1]
	v_sub_f32_e32 v143, v143, v182
	v_sub_f32_e32 v142, v142, v182
	v_sub_f32_e32 v145, v145, v182
	v_sub_f32_e32 v144, v144, v182
	v_pk_mul_f32 v[144:145], v[182:183], v[144:145] op_sel:[1,0]
	v_pk_mul_f32 v[142:143], v[182:183], v[142:143] op_sel:[1,0]
	v_pk_fma_f32 v[142:143], v[210:211], v[142:143], v[220:221]
	v_pk_fma_f32 v[144:145], v[212:213], v[144:145], v[222:223]
	v_pk_fma_f32 v[94:95], v[144:145], s[34:35], v[94:95] op_sel_hi:[1,0,1]
	v_pk_fma_f32 v[92:93], v[142:143], s[34:35], v[92:93] op_sel_hi:[1,0,1]
	v_sub_f32_e32 v147, v147, v184
	v_sub_f32_e32 v146, v146, v184
	v_sub_f32_e32 v149, v149, v184
	v_sub_f32_e32 v148, v148, v184
	v_pk_mul_f32 v[148:149], v[184:185], v[148:149] op_sel:[1,0]
	v_pk_mul_f32 v[146:147], v[184:185], v[146:147] op_sel:[1,0]
	v_pk_fma_f32 v[146:147], v[210:211], v[146:147], v[220:221]
	v_pk_fma_f32 v[148:149], v[212:213], v[148:149], v[222:223]
	v_pk_fma_f32 v[90:91], v[148:149], s[34:35], v[90:91] op_sel_hi:[1,0,1]
	v_pk_fma_f32 v[88:89], v[146:147], s[34:35], v[88:89] op_sel_hi:[1,0,1]
	v_sub_f32_e32 v151, v151, v186
	v_sub_f32_e32 v150, v150, v186
	v_sub_f32_e32 v153, v153, v186
	v_sub_f32_e32 v152, v152, v186
	v_pk_mul_f32 v[152:153], v[186:187], v[152:153] op_sel:[1,0]
	v_pk_mul_f32 v[150:151], v[186:187], v[150:151] op_sel:[1,0]
	v_pk_fma_f32 v[150:151], v[210:211], v[150:151], v[220:221]
	v_pk_fma_f32 v[152:153], v[212:213], v[152:153], v[222:223]
	v_pk_fma_f32 v[86:87], v[152:153], s[34:35], v[86:87] op_sel_hi:[1,0,1]
	v_pk_fma_f32 v[84:85], v[150:151], s[34:35], v[84:85] op_sel_hi:[1,0,1]
	global_load_dwordx4 v[138:141], v224, s[14:15] offset:512
	v_add_u32_e32 v226, 0x20000, v224
	global_load_dwordx4 v[142:145], v226, s[14:15] offset:512
	v_add_u32_e32 v225, 0x40000, v224
	global_load_dwordx4 v[146:149], v225, s[14:15] offset:512
	v_add_u32_e32 v226, 0x60000, v224
	global_load_dwordx4 v[150:153], v226, s[14:15] offset:512
	global_store_dwordx4 v224, v[96:99], s[14:15] offset:64
	v_add_u32_e32 v226, 0x20000, v224
	global_store_dwordx4 v226, v[92:95], s[14:15] offset:64
	v_add_u32_e32 v225, 0x40000, v224
	global_store_dwordx4 v225, v[88:91], s[14:15] offset:64
	v_add_u32_e32 v226, 0x60000, v224
	global_store_dwordx4 v226, v[84:87], s[14:15] offset:64
	s_waitcnt vmcnt(12)
	v_sub_f32_e32 v155, v155, v188
	v_sub_f32_e32 v154, v154, v188
	v_sub_f32_e32 v157, v157, v188
	v_sub_f32_e32 v156, v156, v188
	v_pk_mul_f32 v[156:157], v[188:189], v[156:157] op_sel:[1,0]
	v_pk_mul_f32 v[154:155], v[188:189], v[154:155] op_sel:[1,0]
	v_pk_fma_f32 v[154:155], v[210:211], v[154:155], v[220:221]
	v_pk_fma_f32 v[156:157], v[212:213], v[156:157], v[222:223]
	v_pk_fma_f32 v[82:83], v[156:157], s[34:35], v[82:83] op_sel_hi:[1,0,1]
	v_pk_fma_f32 v[80:81], v[154:155], s[34:35], v[80:81] op_sel_hi:[1,0,1]
	v_sub_f32_e32 v159, v159, v190
	v_sub_f32_e32 v158, v158, v190
	v_sub_f32_e32 v161, v161, v190
	v_sub_f32_e32 v160, v160, v190
	v_pk_mul_f32 v[160:161], v[190:191], v[160:161] op_sel:[1,0]
	v_pk_mul_f32 v[158:159], v[190:191], v[158:159] op_sel:[1,0]
	v_pk_fma_f32 v[158:159], v[210:211], v[158:159], v[220:221]
	v_pk_fma_f32 v[160:161], v[212:213], v[160:161], v[222:223]
	v_pk_fma_f32 v[78:79], v[160:161], s[34:35], v[78:79] op_sel_hi:[1,0,1]
	v_pk_fma_f32 v[76:77], v[158:159], s[34:35], v[76:77] op_sel_hi:[1,0,1]
	v_sub_f32_e32 v175, v175, v192
	v_sub_f32_e32 v174, v174, v192
	v_sub_f32_e32 v177, v177, v192
	v_sub_f32_e32 v176, v176, v192
	v_pk_mul_f32 v[176:177], v[192:193], v[176:177] op_sel:[1,0]
	v_pk_mul_f32 v[174:175], v[192:193], v[174:175] op_sel:[1,0]
	v_pk_fma_f32 v[174:175], v[210:211], v[174:175], v[220:221]
	v_pk_fma_f32 v[176:177], v[212:213], v[176:177], v[222:223]
	v_pk_fma_f32 v[74:75], v[176:177], s[34:35], v[74:75] op_sel_hi:[1,0,1]
	v_pk_fma_f32 v[72:73], v[174:175], s[34:35], v[72:73] op_sel_hi:[1,0,1]
	v_sub_f32_e32 v179, v179, v194
	v_sub_f32_e32 v178, v178, v194
	v_sub_f32_e32 v181, v181, v194
	v_sub_f32_e32 v180, v180, v194
	v_pk_mul_f32 v[180:181], v[194:195], v[180:181] op_sel:[1,0]
	v_pk_mul_f32 v[178:179], v[194:195], v[178:179] op_sel:[1,0]
	v_pk_fma_f32 v[178:179], v[210:211], v[178:179], v[220:221]
	v_pk_fma_f32 v[180:181], v[212:213], v[180:181], v[222:223]
	v_pk_fma_f32 v[70:71], v[180:181], s[34:35], v[70:71] op_sel_hi:[1,0,1]
	v_pk_fma_f32 v[68:69], v[178:179], s[34:35], v[68:69] op_sel_hi:[1,0,1]
	global_load_dwordx4 v[210:213], v234, s[42:43] offset:576
	global_load_dwordx4 v[220:223], v234, s[10:11] offset:576
	v_add_u32_e32 v225, 0x100000, v224
	global_load_dwordx4 v[154:157], v225, s[14:15] offset:512
	v_add_u32_e32 v226, 0x120000, v224
	global_load_dwordx4 v[158:161], v226, s[14:15] offset:512
	v_add_u32_e32 v225, 0x140000, v224
	global_load_dwordx4 v[174:177], v225, s[14:15] offset:512
	v_add_u32_e32 v226, 0x160000, v224
	global_load_dwordx4 v[178:181], v226, s[14:15] offset:512
	v_add_u32_e32 v225, 0x100000, v224
	global_store_dwordx4 v225, v[80:83], s[14:15] offset:64
	v_add_u32_e32 v226, 0x120000, v224
	global_store_dwordx4 v226, v[76:79], s[14:15] offset:64
	v_add_u32_e32 v225, 0x140000, v224
	global_store_dwordx4 v225, v[72:75], s[14:15] offset:64
	v_add_u32_e32 v226, 0x160000, v224
	global_store_dwordx4 v226, v[68:71], s[14:15] offset:64
	s_waitcnt vmcnt(14)
;     __device__ __forceinline__ void operator()(const f32x4 (&acc)[2][2][4][2], const Unit& u, int wr, int wc, int fr, int fq) const {
;     ...
;         for (int bj = 0; bj < 2; ++bj)
; #pragma unroll
;             for (int n = 0; n < 2; ++n) {
;                 const int col = col0 + bj * HALF + n * 16;
;                 f32x4 gg = {1.f, 1.f, 1.f, 1.f}, bb = {0.f, 0.f, 0.f, 0.f};
;                 if (NORM) { gg = *(const f32x4*)(gam + col); bb = *(const f32x4*)(bet + col); }
; #pragma unroll
;                 for (int ai = 0; ai < 2; ++ai) {
;                     f32x4 xv[4]; f32x2 st[4];
; #pragma unroll
;                     for (int m = 0; m < 4; ++m) { xv[m] = *(const f32x4*)(X + (size_t)(row0 + ai * HALF + m * 16) * D + col);
;                         if (NORM) st[m] = *(const f32x2*)(stats + 2 * (row0 + ai * HALF + m * 16)); }
; #pragma unroll
;                     for (int m = 0; m < 4; ++m) {
;                         f32x4 x = xv[m];
;                         if (NORM) x = (x - st[m].x) * st[m].y * gg + bb;
;                         if (!dry) *(f32x4*)(X + (size_t)(row0 + ai * HALF + m * 16) * D + col) = x * ALPHA + acc[ai][bj][m][n];
;                     }
;                 }
	v_sub_f32_e32 v139, v139, v162
	v_sub_f32_e32 v138, v138, v162
	v_sub_f32_e32 v141, v141, v162
	v_sub_f32_e32 v140, v140, v162
	v_pk_mul_f32 v[140:141], v[162:163], v[140:141] op_sel:[1,0]
	v_pk_mul_f32 v[138:139], v[162:163], v[138:139] op_sel:[1,0]
	v_pk_fma_f32 v[138:139], v[196:197], v[138:139], v[200:201]
	v_pk_fma_f32 v[140:141], v[198:199], v[140:141], v[202:203]
	v_pk_fma_f32 v[66:67], v[140:141], s[34:35], v[66:67] op_sel_hi:[1,0,1]
	v_pk_fma_f32 v[64:65], v[138:139], s[34:35], v[64:65] op_sel_hi:[1,0,1]
	v_sub_f32_e32 v143, v143, v182
	v_sub_f32_e32 v142, v142, v182
	v_sub_f32_e32 v145, v145, v182
	v_sub_f32_e32 v144, v144, v182
	v_pk_mul_f32 v[144:145], v[182:183], v[144:145] op_sel:[1,0]
	v_pk_mul_f32 v[142:143], v[182:183], v[142:143] op_sel:[1,0]
	v_pk_fma_f32 v[142:143], v[196:197], v[142:143], v[200:201]
	v_pk_fma_f32 v[144:145], v[198:199], v[144:145], v[202:203]
	v_pk_fma_f32 v[62:63], v[144:145], s[34:35], v[62:63] op_sel_hi:[1,0,1]
	v_pk_fma_f32 v[60:61], v[142:143], s[34:35], v[60:61] op_sel_hi:[1,0,1]
	v_sub_f32_e32 v147, v147, v184
	v_sub_f32_e32 v146, v146, v184
	v_sub_f32_e32 v149, v149, v184
	v_sub_f32_e32 v148, v148, v184
	v_pk_mul_f32 v[148:149], v[184:185], v[148:149] op_sel:[1,0]
	v_pk_mul_f32 v[146:147], v[184:185], v[146:147] op_sel:[1,0]
	v_pk_fma_f32 v[146:147], v[196:197], v[146:147], v[200:201]
	v_pk_fma_f32 v[148:149], v[198:199], v[148:149], v[202:203]
	v_pk_fma_f32 v[58:59], v[148:149], s[34:35], v[58:59] op_sel_hi:[1,0,1]
	v_pk_fma_f32 v[56:57], v[146:147], s[34:35], v[56:57] op_sel_hi:[1,0,1]
	v_sub_f32_e32 v151, v151, v186
	v_sub_f32_e32 v150, v150, v186
	v_sub_f32_e32 v153, v153, v186
	v_sub_f32_e32 v152, v152, v186
	v_pk_mul_f32 v[152:153], v[186:187], v[152:153] op_sel:[1,0]
	v_pk_mul_f32 v[150:151], v[186:187], v[150:151] op_sel:[1,0]
	v_pk_fma_f32 v[150:151], v[196:197], v[150:151], v[200:201]
	v_pk_fma_f32 v[152:153], v[198:199], v[152:153], v[202:203]
	v_pk_fma_f32 v[54:55], v[152:153], s[34:35], v[54:55] op_sel_hi:[1,0,1]
	v_pk_fma_f32 v[52:53], v[150:151], s[34:35], v[52:53] op_sel_hi:[1,0,1]
	global_load_dwordx4 v[138:141], v224, s[14:15] offset:576
	v_add_u32_e32 v226, 0x20000, v224
	global_load_dwordx4 v[142:145], v226, s[14:15] offset:576
	v_add_u32_e32 v225, 0x40000, v224
	global_load_dwordx4 v[146:149], v225, s[14:15] offset:576
	v_add_u32_e32 v226, 0x60000, v224
	global_load_dwordx4 v[150:153], v226, s[14:15] offset:576
	global_store_dwordx4 v224, v[64:67], s[14:15] offset:512
	v_add_u32_e32 v226, 0x20000, v224
	global_store_dwordx4 v226, v[60:63], s[14:15] offset:512
	v_add_u32_e32 v225, 0x40000, v224
	global_store_dwordx4 v225, v[56:59], s[14:15] offset:512
	v_add_u32_e32 v226, 0x60000, v224
	global_store_dwordx4 v226, v[52:55], s[14:15] offset:512
	s_waitcnt vmcnt(12)
	v_sub_f32_e32 v155, v155, v188
	v_sub_f32_e32 v154, v154, v188
	v_sub_f32_e32 v157, v157, v188
	v_sub_f32_e32 v156, v156, v188
	v_pk_mul_f32 v[156:157], v[188:189], v[156:157] op_sel:[1,0]
	v_pk_mul_f32 v[154:155], v[188:189], v[154:155] op_sel:[1,0]
	v_pk_fma_f32 v[154:155], v[196:197], v[154:155], v[200:201]
	v_pk_fma_f32 v[156:157], v[198:199], v[156:157], v[202:203]
	v_pk_fma_f32 v[50:51], v[156:157], s[34:35], v[50:51] op_sel_hi:[1,0,1]
	v_pk_fma_f32 v[48:49], v[154:155], s[34:35], v[48:49] op_sel_hi:[1,0,1]
	v_sub_f32_e32 v159, v159, v190
	v_sub_f32_e32 v158, v158, v190
	v_sub_f32_e32 v161, v161, v190
	v_sub_f32_e32 v160, v160, v190
	v_pk_mul_f32 v[160:161], v[190:191], v[160:161] op_sel:[1,0]
	v_pk_mul_f32 v[158:159], v[190:191], v[158:159] op_sel:[1,0]
	v_pk_fma_f32 v[158:159], v[196:197], v[158:159], v[200:201]
	v_pk_fma_f32 v[160:161], v[198:199], v[160:161], v[202:203]
	v_pk_fma_f32 v[46:47], v[160:161], s[34:35], v[46:47] op_sel_hi:[1,0,1]
	v_pk_fma_f32 v[44:45], v[158:159], s[34:35], v[44:45] op_sel_hi:[1,0,1]
	v_sub_f32_e32 v175, v175, v192
	v_sub_f32_e32 v174, v174, v192
	v_sub_f32_e32 v177, v177, v192
	v_sub_f32_e32 v176, v176, v192
	v_pk_mul_f32 v[176:177], v[192:193], v[176:177] op_sel:[1,0]
	v_pk_mul_f32 v[174:175], v[192:193], v[174:175] op_sel:[1,0]
	v_pk_fma_f32 v[174:175], v[196:197], v[174:175], v[200:201]
	v_pk_fma_f32 v[176:177], v[198:199], v[176:177], v[202:203]
	v_pk_fma_f32 v[42:43], v[176:177], s[34:35], v[42:43] op_sel_hi:[1,0,1]
	v_pk_fma_f32 v[40:41], v[174:175], s[34:35], v[40:41] op_sel_hi:[1,0,1]
	v_sub_f32_e32 v179, v179, v194
	v_sub_f32_e32 v178, v178, v194
	v_sub_f32_e32 v181, v181, v194
	v_sub_f32_e32 v180, v180, v194
	v_pk_mul_f32 v[180:181], v[194:195], v[180:181] op_sel:[1,0]
	v_pk_mul_f32 v[178:179], v[194:195], v[178:179] op_sel:[1,0]
	v_pk_fma_f32 v[178:179], v[196:197], v[178:179], v[200:201]
	v_pk_fma_f32 v[180:181], v[198:199], v[180:181], v[202:203]
	v_pk_fma_f32 v[38:39], v[180:181], s[34:35], v[38:39] op_sel_hi:[1,0,1]
	v_pk_fma_f32 v[36:37], v[178:179], s[34:35], v[36:37] op_sel_hi:[1,0,1]
	v_add_u32_e32 v225, 0x100000, v224
	global_load_dwordx4 v[154:157], v225, s[14:15] offset:576
	v_add_u32_e32 v226, 0x120000, v224
	global_load_dwordx4 v[158:161], v226, s[14:15] offset:576
	v_add_u32_e32 v225, 0x140000, v224
	global_load_dwordx4 v[174:177], v225, s[14:15] offset:576
	v_add_u32_e32 v226, 0x160000, v224
	global_load_dwordx4 v[178:181], v226, s[14:15] offset:576
	v_add_u32_e32 v225, 0x100000, v224
	global_store_dwordx4 v225, v[48:51], s[14:15] offset:512
	v_add_u32_e32 v226, 0x120000, v224
	global_store_dwordx4 v226, v[44:47], s[14:15] offset:512
	v_add_u32_e32 v225, 0x140000, v224
	global_store_dwordx4 v225, v[40:43], s[14:15] offset:512
	v_add_u32_e32 v226, 0x160000, v224
	global_store_dwordx4 v226, v[36:39], s[14:15] offset:512
	s_waitcnt vmcnt(12)
; #define PG8_BAR __builtin_amdgcn_s_barrier()
; template <class Epi, class Sched>
; __device__ __forceinline__ void gemm_phase(LAS unsigned char* lds, const Gemm g, const Sched& S, const Epi& E, const int tid) {
;     ...
;         if (!has_next) break;
; #pragma unroll
;         for (int a = 0; a < 2; ++a)
; #pragma unroll
;             for (int b = 0; b < 2; ++b)
; #pragma unroll
;                 for (int m = 0; m < 4; ++m)
; #pragma unroll
;                     for (int n = 0; n < 2; ++n) acc[a][b][m][n] = (f32x4){0.f, 0.f, 0.f, 0.f};
;         cur = nxt; cA = nA; cB = nB; ++ui;
;         if (wr == 1) PG8_BAR;
;     __device__ __forceinline__ void operator()(const f32x4 (&acc)[2][2][4][2], const Unit& u, int wr, int wc, int fr, int fq) const {
;     ...
;         for (int bj = 0; bj < 2; ++bj)
; #pragma unroll
;             for (int n = 0; n < 2; ++n) {
;                 const int col = col0 + bj * HALF + n * 16;
;                 f32x4 gg = {1.f, 1.f, 1.f, 1.f}, bb = {0.f, 0.f, 0.f, 0.f};
;                 if (NORM) { gg = *(const f32x4*)(gam + col); bb = *(const f32x4*)(bet + col); }
; #pragma unroll
;                 for (int ai = 0; ai < 2; ++ai) {
;                     f32x4 xv[4]; f32x2 st[4];
; #pragma unroll
;                     for (int m = 0; m < 4; ++m) { xv[m] = *(const f32x4*)(X + (size_t)(row0 + ai * HALF + m * 16) * D + col);
;                         if (NORM) st[m] = *(const f32x2*)(stats + 2 * (row0 + ai * HALF + m * 16)); }
; #pragma unroll
;                     for (int m = 0; m < 4; ++m) {
;                         f32x4 x = xv[m];
;                         if (NORM) x = (x - st[m].x) * st[m].y * gg + bb;
;                         if (!dry) *(f32x4*)(X + (size_t)(row0 + ai * HALF + m * 16) * D + col) = x * ALPHA + acc[ai][bj][m][n];
;                     }
;                 }
	v_sub_f32_e32 v139, v139, v162
	v_sub_f32_e32 v138, v138, v162
	v_sub_f32_e32 v141, v141, v162
	v_sub_f32_e32 v140, v140, v162
	v_pk_mul_f32 v[140:141], v[162:163], v[140:141] op_sel:[1,0]
	v_pk_mul_f32 v[138:139], v[162:163], v[138:139] op_sel:[1,0]
	v_pk_fma_f32 v[138:139], v[210:211], v[138:139], v[220:221]
	v_pk_fma_f32 v[140:141], v[212:213], v[140:141], v[222:223]
	v_pk_fma_f32 v[34:35], v[140:141], s[34:35], v[34:35] op_sel_hi:[1,0,1]
	v_pk_fma_f32 v[32:33], v[138:139], s[34:35], v[32:33] op_sel_hi:[1,0,1]
	v_sub_f32_e32 v143, v143, v182
	v_sub_f32_e32 v142, v142, v182
	v_sub_f32_e32 v145, v145, v182
	v_sub_f32_e32 v144, v144, v182
	v_pk_mul_f32 v[144:145], v[182:183], v[144:145] op_sel:[1,0]
	v_pk_mul_f32 v[142:143], v[182:183], v[142:143] op_sel:[1,0]
	v_pk_fma_f32 v[142:143], v[210:211], v[142:143], v[220:221]
	v_pk_fma_f32 v[144:145], v[212:213], v[144:145], v[222:223]
	v_pk_fma_f32 v[30:31], v[144:145], s[34:35], v[30:31] op_sel_hi:[1,0,1]
	v_pk_fma_f32 v[28:29], v[142:143], s[34:35], v[28:29] op_sel_hi:[1,0,1]
	v_sub_f32_e32 v147, v147, v184
	v_sub_f32_e32 v146, v146, v184
	v_sub_f32_e32 v149, v149, v184
	v_sub_f32_e32 v148, v148, v184
	v_pk_mul_f32 v[148:149], v[184:185], v[148:149] op_sel:[1,0]
	v_pk_mul_f32 v[146:147], v[184:185], v[146:147] op_sel:[1,0]
	v_pk_fma_f32 v[146:147], v[210:211], v[146:147], v[220:221]
	v_pk_fma_f32 v[148:149], v[212:213], v[148:149], v[222:223]
	v_pk_fma_f32 v[26:27], v[148:149], s[34:35], v[26:27] op_sel_hi:[1,0,1]
	v_pk_fma_f32 v[24:25], v[146:147], s[34:35], v[24:25] op_sel_hi:[1,0,1]
	v_sub_f32_e32 v151, v151, v186
	v_sub_f32_e32 v150, v150, v186
	v_sub_f32_e32 v153, v153, v186
	v_sub_f32_e32 v152, v152, v186
	v_pk_mul_f32 v[152:153], v[186:187], v[152:153] op_sel:[1,0]
	v_pk_mul_f32 v[150:151], v[186:187], v[150:151] op_sel:[1,0]
	v_pk_fma_f32 v[150:151], v[210:211], v[150:151], v[220:221]
	v_pk_fma_f32 v[152:153], v[212:213], v[152:153], v[222:223]
	v_pk_fma_f32 v[22:23], v[152:153], s[34:35], v[22:23] op_sel_hi:[1,0,1]
	v_pk_fma_f32 v[20:21], v[150:151], s[34:35], v[20:21] op_sel_hi:[1,0,1]
	global_store_dwordx4 v224, v[32:35], s[14:15] offset:576
	v_add_u32_e32 v226, 0x20000, v224
	global_store_dwordx4 v226, v[28:31], s[14:15] offset:576
	v_add_u32_e32 v225, 0x40000, v224
	global_store_dwordx4 v225, v[24:27], s[14:15] offset:576
	v_add_u32_e32 v226, 0x60000, v224
	global_store_dwordx4 v226, v[20:23], s[14:15] offset:576
	s_waitcnt vmcnt(8)
	v_sub_f32_e32 v155, v155, v188
	v_sub_f32_e32 v154, v154, v188
	v_sub_f32_e32 v157, v157, v188
	v_sub_f32_e32 v156, v156, v188
	v_pk_mul_f32 v[156:157], v[188:189], v[156:157] op_sel:[1,0]
	v_pk_mul_f32 v[154:155], v[188:189], v[154:155] op_sel:[1,0]
	v_pk_fma_f32 v[154:155], v[210:211], v[154:155], v[220:221]
	v_pk_fma_f32 v[156:157], v[212:213], v[156:157], v[222:223]
	v_pk_fma_f32 v[18:19], v[156:157], s[34:35], v[18:19] op_sel_hi:[1,0,1]
	v_pk_fma_f32 v[16:17], v[154:155], s[34:35], v[16:17] op_sel_hi:[1,0,1]
	v_sub_f32_e32 v159, v159, v190
	v_sub_f32_e32 v158, v158, v190
	v_sub_f32_e32 v161, v161, v190
	v_sub_f32_e32 v160, v160, v190
	v_pk_mul_f32 v[160:161], v[190:191], v[160:161] op_sel:[1,0]
	v_pk_mul_f32 v[158:159], v[190:191], v[158:159] op_sel:[1,0]
	v_pk_fma_f32 v[158:159], v[210:211], v[158:159], v[220:221]
	v_pk_fma_f32 v[160:161], v[212:213], v[160:161], v[222:223]
	v_pk_fma_f32 v[14:15], v[160:161], s[34:35], v[14:15] op_sel_hi:[1,0,1]
	v_pk_fma_f32 v[12:13], v[158:159], s[34:35], v[12:13] op_sel_hi:[1,0,1]
	v_sub_f32_e32 v175, v175, v192
	v_sub_f32_e32 v174, v174, v192
	v_sub_f32_e32 v177, v177, v192
	v_sub_f32_e32 v176, v176, v192
	v_pk_mul_f32 v[176:177], v[192:193], v[176:177] op_sel:[1,0]
	v_pk_mul_f32 v[174:175], v[192:193], v[174:175] op_sel:[1,0]
	v_pk_fma_f32 v[174:175], v[210:211], v[174:175], v[220:221]
	v_pk_fma_f32 v[176:177], v[212:213], v[176:177], v[222:223]
	v_pk_fma_f32 v[10:11], v[176:177], s[34:35], v[10:11] op_sel_hi:[1,0,1]
	v_pk_fma_f32 v[8:9], v[174:175], s[34:35], v[8:9] op_sel_hi:[1,0,1]
	v_sub_f32_e32 v179, v179, v194
	v_sub_f32_e32 v178, v178, v194
	v_sub_f32_e32 v181, v181, v194
	v_sub_f32_e32 v180, v180, v194
	v_pk_mul_f32 v[180:181], v[194:195], v[180:181] op_sel:[1,0]
	v_pk_mul_f32 v[178:179], v[194:195], v[178:179] op_sel:[1,0]
	v_pk_fma_f32 v[178:179], v[210:211], v[178:179], v[220:221]
	v_pk_fma_f32 v[180:181], v[212:213], v[180:181], v[222:223]
	v_pk_fma_f32 v[6:7], v[180:181], s[34:35], v[6:7] op_sel_hi:[1,0,1]
	v_pk_fma_f32 v[4:5], v[178:179], s[34:35], v[4:5] op_sel_hi:[1,0,1]
	v_add_u32_e32 v225, 0x100000, v224
	global_store_dwordx4 v225, v[16:19], s[14:15] offset:576
	v_add_u32_e32 v226, 0x120000, v224
	global_store_dwordx4 v226, v[12:15], s[14:15] offset:576
	v_add_u32_e32 v225, 0x140000, v224
	global_store_dwordx4 v225, v[8:11], s[14:15] offset:576
	v_add_u32_e32 v226, 0x160000, v224
	global_store_dwordx4 v226, v[4:7], s[14:15] offset:576
	s_and_b64 vcc, exec, s[6:7]
	s_mov_b64 s[6:7], -1
	s_cbranch_vccnz .LBB0_170
	v_readlane_b32 s6, v255, 37
	v_readlane_b32 s7, v255, 38
	s_andn2_b64 vcc, exec, s[6:7]
	s_cbranch_vccnz .LBB0_169
	s_barrier
	s_branch .LBB0_169

; #define PG8_STAGE(bufoff, gbase, voff) do { _Pragma("unroll") for (int _i = 0; _i < 2; ++_i) \
;         __builtin_amdgcn_global_load_lds((const unsigned*)((const char*)(gbase) + (voff)[_i]), (LAS unsigned*)(lds + (bufoff) + ldsw + _i * 8192), 16, 0, 0); } while (0)
; #define PG8_LDA(dst, b, h) do { _Pragma("unroll") for (int m = 0; m < 4; ++m) _Pragma("unroll") for (int k = 0; k < 2; ++k) dst[m][k] = *(const LAS bf16x8*)(lds + PG8_SA(b, h) + aoff + m * 2048 + k * 1024); } while (0)
; #define PG8_LDB(dst, b, h) do { _Pragma("unroll") for (int n = 0; n < 2; ++n) _Pragma("unroll") for (int k = 0; k < 2; ++k) dst[n][k] = *(const LAS bf16x8*)(lds + PG8_SB(b, h) + boff + n * 2048 + k * 1024); } while (0)
; #define PG8_WAIT_V(n) asm volatile("s_waitcnt vmcnt(" #n ")" ::: "memory")
; #define PG8_BAR __builtin_amdgcn_s_barrier()
; template <class Epi, class Sched>
; __device__ __forceinline__ void gemm_phase(LAS unsigned char* lds, const Gemm g, const Sched& S, const Epi& E, const int tid) {
;     ...
;         for (int t = 0; t < nt; t += 2) {
;             const bool last = (t == nt - 2);
;             const char* a1 = cA + (size_t)(t + 1) * kstep;
;             const char* a2 = last ? nA : cA + (size_t)(t + 2) * kstep; const char* b2 = last ? nB : cB + (size_t)(t + 2) * kstep;
;             const char* a3 = a2 + kstep; const char* b3 = b2 + kstep;
;             PG8_LDB(B0, 0, 0); PG8_LDB(B1, 0, 1); PG8_SCHED; PG8_LDA(At, 0, 0); PG8_STAGE(PG8_SA(1, 1), a1 + hstepA, voffA);
;             PG8_WAIT_V(8); PG8_WAIT_L(0); PG8_BAR; PG8_MMA(0, 0, At, B0); PG8_MMA(0, 1, At, B1); PG8_BAR; PG8_SCHED;
;             PG8_LDA(At, 0, 1); PG8_STAGE(PG8_SB(0, 0), b2, voffB); PG8_STAGE(PG8_SB(0, 1), b2 + hstepB, voffB); PG8_STAGE(PG8_SA(0, 0), a2, voffA);
;             PG8_WAIT_V(8); PG8_WAIT_L(0); PG8_BAR; PG8_MMA(1, 0, At, B0); PG8_MMA(1, 1, At, B1); PG8_BAR; PG8_SCHED;
;             PG8_LDB(B0, 1, 0); PG8_LDB(B1, 1, 1); PG8_SCHED; PG8_LDA(At, 1, 0); PG8_STAGE(PG8_SA(0, 1), a2 + hstepA, voffA);
;             PG8_WAIT_V(8); PG8_WAIT_L(0); PG8_BAR; PG8_MMA(0, 0, At, B0); PG8_MMA(0, 1, At, B1); PG8_BAR; PG8_SCHED;
;             PG8_LDA(At, 1, 1); PG8_STAGE(PG8_SB(1, 0), b3, voffB); PG8_STAGE(PG8_SB(1, 1), b3 + hstepB, voffB); PG8_STAGE(PG8_SA(1, 0), a3, voffA);
;             PG8_WAIT_V(8); PG8_WAIT_L(0); PG8_BAR; PG8_MMA(1, 0, At, B0); PG8_MMA(1, 1, At, B1); PG8_BAR; PG8_SCHED;
.LBB0_208:
	s_add_u32 s12, s54, 0xfff80080
	s_addc_u32 s13, s55, -1
	s_add_i32 s74, 0, 0x10000
	s_cmp_eq_u32 s95, 28
	s_cselect_b32 s89, s16, s13
	s_cselect_b32 s88, s17, s12
	s_cselect_b32 s87, s39, s94
	s_cselect_b32 s86, s43, s93
	s_add_i32 s96, 0, 0x14000
	v_add_u32_e32 v158, s74, v143
	v_add_u32_e32 v162, s96, v143
	ds_read_b128 v[146:149], v158
	ds_read_b128 v[150:153], v158 offset:1024
	ds_read_b128 v[154:157], v158 offset:2048
	ds_read_b128 v[158:161], v158 offset:3072
	ds_read_b128 v[174:177], v162
	ds_read_b128 v[178:181], v162 offset:1024
	ds_read_b128 v[182:185], v162 offset:2048
	ds_read_b128 v[186:189], v162 offset:3072
	v_lshl_add_u64 v[162:163], s[54:55], 0, v[138:139]
	s_add_i32 m0, s11, 0xc000
	ds_read_b128 v[190:193], v145
	ds_read_b128 v[194:197], v145 offset:1024
	ds_read_b128 v[198:201], v145 offset:2048
	ds_read_b128 v[202:205], v145 offset:3072
	ds_read_b128 v[210:213], v145 offset:4096
	ds_read_b128 v[220:223], v145 offset:5120
	ds_read_b128 v[234:237], v145 offset:6144
	ds_read_b128 v[238:241], v145 offset:7168
	global_load_lds_dwordx4 v[162:163], off
	v_lshl_add_u64 v[162:163], s[54:55], 0, v[140:141]
	s_add_i32 m0, s11, 0xe000
	s_nop 0
	global_load_lds_dwordx4 v[162:163], off
	s_waitcnt vmcnt(8)
	s_waitcnt lgkmcnt(0)
	s_barrier
	s_waitcnt lgkmcnt(0)
	v_mfma_f32_16x16x32_bf16 v[128:131], v[146:149], v[190:193], v[128:131]
	v_mfma_f32_16x16x32_bf16 v[124:127], v[154:157], v[190:193], v[124:127]
	v_mfma_f32_16x16x32_bf16 v[120:123], v[146:149], v[198:201], v[120:123]
	v_mfma_f32_16x16x32_bf16 v[116:119], v[154:157], v[198:201], v[116:119]
	v_mfma_f32_16x16x32_bf16 v[104:107], v[146:149], v[210:213], v[104:107]
	v_mfma_f32_16x16x32_bf16 v[100:103], v[154:157], v[210:213], v[100:103]
	v_mfma_f32_16x16x32_bf16 v[88:91], v[146:149], v[234:237], v[88:91]
	v_mfma_f32_16x16x32_bf16 v[84:87], v[154:157], v[234:237], v[84:87]
	v_mfma_f32_16x16x32_bf16 v[128:131], v[150:153], v[194:197], v[128:131]
	v_mfma_f32_16x16x32_bf16 v[124:127], v[158:161], v[194:197], v[124:127]
	v_mfma_f32_16x16x32_bf16 v[120:123], v[150:153], v[202:205], v[120:123]
	v_mfma_f32_16x16x32_bf16 v[116:119], v[158:161], v[202:205], v[116:119]
	v_mfma_f32_16x16x32_bf16 v[104:107], v[150:153], v[220:223], v[104:107]
	v_mfma_f32_16x16x32_bf16 v[100:103], v[158:161], v[220:223], v[100:103]
	v_mfma_f32_16x16x32_bf16 v[88:91], v[150:153], v[238:241], v[88:91]
	v_mfma_f32_16x16x32_bf16 v[84:87], v[158:161], v[238:241], v[84:87]
	v_mfma_f32_16x16x32_bf16 v[112:115], v[174:177], v[190:193], v[112:115]
	v_mfma_f32_16x16x32_bf16 v[108:111], v[182:185], v[190:193], v[108:111]
	v_mfma_f32_16x16x32_bf16 v[96:99], v[174:177], v[198:201], v[96:99]
	v_mfma_f32_16x16x32_bf16 v[92:95], v[182:185], v[198:201], v[92:95]
	v_mfma_f32_16x16x32_bf16 v[80:83], v[174:177], v[210:213], v[80:83]
	v_mfma_f32_16x16x32_bf16 v[76:79], v[182:185], v[210:213], v[76:79]
	v_mfma_f32_16x16x32_bf16 v[72:75], v[174:177], v[234:237], v[72:75]
	v_mfma_f32_16x16x32_bf16 v[68:71], v[182:185], v[234:237], v[68:71]
	v_mfma_f32_16x16x32_bf16 v[112:115], v[178:181], v[194:197], v[112:115]
	v_mfma_f32_16x16x32_bf16 v[108:111], v[186:189], v[194:197], v[108:111]
	v_mfma_f32_16x16x32_bf16 v[96:99], v[178:181], v[202:205], v[96:99]
	v_mfma_f32_16x16x32_bf16 v[92:95], v[186:189], v[202:205], v[92:95]
	v_mfma_f32_16x16x32_bf16 v[80:83], v[178:181], v[220:223], v[80:83]
	v_mfma_f32_16x16x32_bf16 v[76:79], v[186:189], v[220:223], v[76:79]
	v_mfma_f32_16x16x32_bf16 v[72:75], v[178:181], v[238:241], v[72:75]
	v_mfma_f32_16x16x32_bf16 v[68:71], v[186:189], v[238:241], v[68:71]
	s_barrier
	s_add_i32 s12, s74, s57
	v_lshl_add_u64 v[162:163], s[86:87], 0, v[164:165]
	s_mov_b32 m0, s12
	ds_read_b128 v[190:193], v145 offset:16384
	ds_read_b128 v[194:197], v145 offset:17408
	ds_read_b128 v[198:201], v145 offset:18432
	ds_read_b128 v[202:205], v145 offset:19456
	ds_read_b128 v[210:213], v145 offset:20480
	ds_read_b128 v[220:223], v145 offset:21504
	ds_read_b128 v[234:237], v145 offset:22528
	ds_read_b128 v[238:241], v145 offset:23552
	global_load_lds_dwordx4 v[162:163], off
	s_add_i32 m0, s12, 0x2000
	s_add_u32 s12, s86, 0x80000
	v_lshl_add_u64 v[206:207], s[86:87], 0, v[132:133]
	s_addc_u32 s13, s87, 0
	s_add_i32 s74, s96, s57
	global_load_lds_dwordx4 v[206:207], off
	v_lshl_add_u64 v[224:225], s[12:13], 0, v[164:165]
	s_mov_b32 m0, s74
	v_lshl_add_u64 v[226:227], s[88:89], 0, v[134:135]
	global_load_lds_dwordx4 v[224:225], off
	v_lshl_add_u64 v[224:225], s[12:13], 0, v[132:133]
	s_add_i32 m0, s74, 0x2000
	s_nop 0
	global_load_lds_dwordx4 v[224:225], off
	v_lshl_add_u64 v[224:225], s[88:89], 0, v[136:137]
	s_mov_b32 m0, s11
	s_nop 0
	global_load_lds_dwordx4 v[224:225], off
	s_mov_b32 m0, s59
	s_nop 0
	global_load_lds_dwordx4 v[226:227], off
	s_waitcnt vmcnt(8)
	s_waitcnt lgkmcnt(0)
	s_barrier
; #define PG8_STAGE(bufoff, gbase, voff) do { _Pragma("unroll") for (int _i = 0; _i < 2; ++_i) \
;         __builtin_amdgcn_global_load_lds((const unsigned*)((const char*)(gbase) + (voff)[_i]), (LAS unsigned*)(lds + (bufoff) + ldsw + _i * 8192), 16, 0, 0); } while (0)
; #define PG8_LDA(dst, b, h) do { _Pragma("unroll") for (int m = 0; m < 4; ++m) _Pragma("unroll") for (int k = 0; k < 2; ++k) dst[m][k] = *(const LAS bf16x8*)(lds + PG8_SA(b, h) + aoff + m * 2048 + k * 1024); } while (0)
; #define PG8_LDB(dst, b, h) do { _Pragma("unroll") for (int n = 0; n < 2; ++n) _Pragma("unroll") for (int k = 0; k < 2; ++k) dst[n][k] = *(const LAS bf16x8*)(lds + PG8_SB(b, h) + boff + n * 2048 + k * 1024); } while (0)
; #define PG8_MMA(ai, bj, At, Bt) do { __builtin_amdgcn_s_setprio(1); _Pragma("unroll") for (int m = 0; m < 4; ++m) _Pragma("unroll") for (int n = 0; n < 2; ++n) _Pragma("unroll") for (int k = 0; k < 2; ++k) \
;         acc[ai][bj][m][n] = __builtin_amdgcn_mfma_f32_16x16x32_bf16(Bt[n][k], At[m][k], acc[ai][bj][m][n], 0, 0, 0); __builtin_amdgcn_s_setprio(0); } while (0)
; #define PG8_WAIT_V(n) asm volatile("s_waitcnt vmcnt(" #n ")" ::: "memory")
; template <class Epi, class Sched>
; __device__ __forceinline__ void gemm_phase(LAS unsigned char* lds, const Gemm g, const Sched& S, const Epi& E, const int tid) {
;     ...
;             PG8_LDB(B0, 0, 0); PG8_LDB(B1, 0, 1); PG8_SCHED; PG8_LDA(At, 0, 0); PG8_STAGE(PG8_SA(1, 1), a1 + hstepA, voffA);
;             PG8_WAIT_V(8); PG8_WAIT_L(0); PG8_BAR; PG8_MMA(0, 0, At, B0); PG8_MMA(0, 1, At, B1); PG8_BAR; PG8_SCHED;
;             PG8_LDA(At, 0, 1); PG8_STAGE(PG8_SB(0, 0), b2, voffB); PG8_STAGE(PG8_SB(0, 1), b2 + hstepB, voffB); PG8_STAGE(PG8_SA(0, 0), a2, voffA);
;             PG8_WAIT_V(8); PG8_WAIT_L(0); PG8_BAR; PG8_MMA(1, 0, At, B0); PG8_MMA(1, 1, At, B1); PG8_BAR; PG8_SCHED;
;             PG8_LDB(B0, 1, 0); PG8_LDB(B1, 1, 1); PG8_SCHED; PG8_LDA(At, 1, 0); PG8_STAGE(PG8_SA(0, 1), a2 + hstepA, voffA);
;             PG8_WAIT_V(8); PG8_WAIT_L(0); PG8_BAR; PG8_MMA(0, 0, At, B0); PG8_MMA(0, 1, At, B1); PG8_BAR; PG8_SCHED;
;             PG8_LDA(At, 1, 1); PG8_STAGE(PG8_SB(1, 0), b3, voffB); PG8_STAGE(PG8_SB(1, 1), b3 + hstepB, voffB); PG8_STAGE(PG8_SA(1, 0), a3, voffA);
;             PG8_WAIT_V(8); PG8_WAIT_L(0); PG8_BAR; PG8_MMA(1, 0, At, B0); PG8_MMA(1, 1, At, B1); PG8_BAR; PG8_SCHED;
	s_waitcnt lgkmcnt(0)
	v_mfma_f32_16x16x32_bf16 v[64:67], v[146:149], v[190:193], v[64:67]
	v_mfma_f32_16x16x32_bf16 v[60:63], v[154:157], v[190:193], v[60:63]
	v_mfma_f32_16x16x32_bf16 v[56:59], v[146:149], v[198:201], v[56:59]
	v_mfma_f32_16x16x32_bf16 v[52:55], v[154:157], v[198:201], v[52:55]
	v_mfma_f32_16x16x32_bf16 v[40:43], v[146:149], v[210:213], v[40:43]
	v_mfma_f32_16x16x32_bf16 v[36:39], v[154:157], v[210:213], v[36:39]
	v_mfma_f32_16x16x32_bf16 v[24:27], v[146:149], v[234:237], v[24:27]
	v_mfma_f32_16x16x32_bf16 v[20:23], v[154:157], v[234:237], v[20:23]
	v_mfma_f32_16x16x32_bf16 v[64:67], v[150:153], v[194:197], v[64:67]
	v_mfma_f32_16x16x32_bf16 v[60:63], v[158:161], v[194:197], v[60:63]
	v_mfma_f32_16x16x32_bf16 v[56:59], v[150:153], v[202:205], v[56:59]
	v_mfma_f32_16x16x32_bf16 v[52:55], v[158:161], v[202:205], v[52:55]
	v_mfma_f32_16x16x32_bf16 v[40:43], v[150:153], v[220:223], v[40:43]
	v_mfma_f32_16x16x32_bf16 v[36:39], v[158:161], v[220:223], v[36:39]
	v_mfma_f32_16x16x32_bf16 v[24:27], v[150:153], v[238:241], v[24:27]
	v_mfma_f32_16x16x32_bf16 v[20:23], v[158:161], v[238:241], v[20:23]
	v_mfma_f32_16x16x32_bf16 v[48:51], v[174:177], v[190:193], v[48:51]
	v_mfma_f32_16x16x32_bf16 v[44:47], v[182:185], v[190:193], v[44:47]
	v_mfma_f32_16x16x32_bf16 v[32:35], v[174:177], v[198:201], v[32:35]
	v_mfma_f32_16x16x32_bf16 v[28:31], v[182:185], v[198:201], v[28:31]
	v_mfma_f32_16x16x32_bf16 v[16:19], v[174:177], v[210:213], v[16:19]
	v_mfma_f32_16x16x32_bf16 v[12:15], v[182:185], v[210:213], v[12:15]
	v_mfma_f32_16x16x32_bf16 v[8:11], v[174:177], v[234:237], v[8:11]
	v_mfma_f32_16x16x32_bf16 v[4:7], v[182:185], v[234:237], v[4:7]
	v_mfma_f32_16x16x32_bf16 v[48:51], v[178:181], v[194:197], v[48:51]
	v_mfma_f32_16x16x32_bf16 v[44:47], v[186:189], v[194:197], v[44:47]
	v_mfma_f32_16x16x32_bf16 v[32:35], v[178:181], v[202:205], v[32:35]
	v_mfma_f32_16x16x32_bf16 v[28:31], v[186:189], v[202:205], v[28:31]
	v_mfma_f32_16x16x32_bf16 v[16:19], v[178:181], v[220:223], v[16:19]
	v_mfma_f32_16x16x32_bf16 v[12:15], v[186:189], v[220:223], v[12:15]
	v_mfma_f32_16x16x32_bf16 v[8:11], v[178:181], v[238:241], v[8:11]
	v_mfma_f32_16x16x32_bf16 v[4:7], v[186:189], v[238:241], v[4:7]
	s_barrier
	s_add_i32 s74, 0, 0x18000
	s_add_i32 s96, 0, 0x1c000
	v_add_u32_e32 v158, s74, v143
	v_add_u32_e32 v171, s96, v143
	ds_read_b128 v[146:149], v158
	ds_read_b128 v[150:153], v158 offset:1024
	ds_read_b128 v[154:157], v158 offset:2048
	ds_read_b128 v[158:161], v158 offset:3072
	ds_read_b128 v[174:177], v171
	ds_read_b128 v[178:181], v171 offset:1024
	ds_read_b128 v[182:185], v171 offset:2048
	ds_read_b128 v[186:189], v171 offset:3072
	s_add_u32 s12, s88, 0x80000
	s_addc_u32 s13, s89, 0
	s_mov_b32 m0, s79
	v_lshl_add_u64 v[242:243], s[12:13], 0, v[136:137]
	ds_read_b128 v[190:193], v145 offset:32768
	ds_read_b128 v[194:197], v145 offset:33792
	ds_read_b128 v[198:201], v145 offset:34816
	ds_read_b128 v[202:205], v145 offset:35840
	ds_read_b128 v[210:213], v145 offset:36864
	ds_read_b128 v[220:223], v145 offset:37888
	ds_read_b128 v[234:237], v145 offset:38912
	ds_read_b128 v[238:241], v145 offset:39936
	global_load_lds_dwordx4 v[242:243], off
	v_lshl_add_u64 v[242:243], s[12:13], 0, v[134:135]
	s_mov_b32 m0, s84
	s_nop 0
	global_load_lds_dwordx4 v[242:243], off
	s_waitcnt vmcnt(8)
	s_waitcnt lgkmcnt(0)
	s_barrier
	s_waitcnt lgkmcnt(0)
	v_mfma_f32_16x16x32_bf16 v[128:131], v[146:149], v[190:193], v[128:131]
	v_mfma_f32_16x16x32_bf16 v[124:127], v[154:157], v[190:193], v[124:127]
	v_mfma_f32_16x16x32_bf16 v[120:123], v[146:149], v[198:201], v[120:123]
	v_mfma_f32_16x16x32_bf16 v[116:119], v[154:157], v[198:201], v[116:119]
	v_mfma_f32_16x16x32_bf16 v[104:107], v[146:149], v[210:213], v[104:107]
	v_mfma_f32_16x16x32_bf16 v[100:103], v[154:157], v[210:213], v[100:103]
	v_mfma_f32_16x16x32_bf16 v[88:91], v[146:149], v[234:237], v[88:91]
	v_mfma_f32_16x16x32_bf16 v[84:87], v[154:157], v[234:237], v[84:87]
	v_mfma_f32_16x16x32_bf16 v[128:131], v[150:153], v[194:197], v[128:131]
	v_mfma_f32_16x16x32_bf16 v[124:127], v[158:161], v[194:197], v[124:127]
	v_mfma_f32_16x16x32_bf16 v[120:123], v[150:153], v[202:205], v[120:123]
	v_mfma_f32_16x16x32_bf16 v[116:119], v[158:161], v[202:205], v[116:119]
	v_mfma_f32_16x16x32_bf16 v[104:107], v[150:153], v[220:223], v[104:107]
	v_mfma_f32_16x16x32_bf16 v[100:103], v[158:161], v[220:223], v[100:103]
	v_mfma_f32_16x16x32_bf16 v[88:91], v[150:153], v[238:241], v[88:91]
	v_mfma_f32_16x16x32_bf16 v[84:87], v[158:161], v[238:241], v[84:87]
	v_mfma_f32_16x16x32_bf16 v[112:115], v[174:177], v[190:193], v[112:115]
	v_mfma_f32_16x16x32_bf16 v[108:111], v[182:185], v[190:193], v[108:111]
	v_mfma_f32_16x16x32_bf16 v[96:99], v[174:177], v[198:201], v[96:99]
	v_mfma_f32_16x16x32_bf16 v[92:95], v[182:185], v[198:201], v[92:95]
	v_mfma_f32_16x16x32_bf16 v[80:83], v[174:177], v[210:213], v[80:83]
	v_mfma_f32_16x16x32_bf16 v[76:79], v[182:185], v[210:213], v[76:79]
	v_mfma_f32_16x16x32_bf16 v[72:75], v[174:177], v[234:237], v[72:75]
	v_mfma_f32_16x16x32_bf16 v[68:71], v[182:185], v[234:237], v[68:71]
	v_mfma_f32_16x16x32_bf16 v[112:115], v[178:181], v[194:197], v[112:115]
	v_mfma_f32_16x16x32_bf16 v[108:111], v[186:189], v[194:197], v[108:111]
	v_mfma_f32_16x16x32_bf16 v[96:99], v[178:181], v[202:205], v[96:99]
	v_mfma_f32_16x16x32_bf16 v[92:95], v[186:189], v[202:205], v[92:95]
	v_mfma_f32_16x16x32_bf16 v[80:83], v[178:181], v[220:223], v[80:83]
	v_mfma_f32_16x16x32_bf16 v[76:79], v[186:189], v[220:223], v[76:79]
	v_mfma_f32_16x16x32_bf16 v[72:75], v[178:181], v[238:241], v[72:75]
	v_mfma_f32_16x16x32_bf16 v[68:71], v[186:189], v[238:241], v[68:71]
	s_barrier
; #define PG8_STAGE(bufoff, gbase, voff) do { _Pragma("unroll") for (int _i = 0; _i < 2; ++_i) \
;         __builtin_amdgcn_global_load_lds((const unsigned*)((const char*)(gbase) + (voff)[_i]), (LAS unsigned*)(lds + (bufoff) + ldsw + _i * 8192), 16, 0, 0); } while (0)
; #define PG8_LDA(dst, b, h) do { _Pragma("unroll") for (int m = 0; m < 4; ++m) _Pragma("unroll") for (int k = 0; k < 2; ++k) dst[m][k] = *(const LAS bf16x8*)(lds + PG8_SA(b, h) + aoff + m * 2048 + k * 1024); } while (0)
; #define PG8_LDB(dst, b, h) do { _Pragma("unroll") for (int n = 0; n < 2; ++n) _Pragma("unroll") for (int k = 0; k < 2; ++k) dst[n][k] = *(const LAS bf16x8*)(lds + PG8_SB(b, h) + boff + n * 2048 + k * 1024); } while (0)
; #define PG8_MMA(ai, bj, At, Bt) do { __builtin_amdgcn_s_setprio(1); _Pragma("unroll") for (int m = 0; m < 4; ++m) _Pragma("unroll") for (int n = 0; n < 2; ++n) _Pragma("unroll") for (int k = 0; k < 2; ++k) \
;         acc[ai][bj][m][n] = __builtin_amdgcn_mfma_f32_16x16x32_bf16(Bt[n][k], At[m][k], acc[ai][bj][m][n], 0, 0, 0); __builtin_amdgcn_s_setprio(0); } while (0)
; #define PG8_WAIT_V(n) asm volatile("s_waitcnt vmcnt(" #n ")" ::: "memory")
; #define PG8_WAIT_L(n) asm volatile("s_waitcnt lgkmcnt(" #n ")" ::: "memory")
; #define PG8_BAR __builtin_amdgcn_s_barrier()
; #define PG8_SCHED __builtin_amdgcn_sched_barrier(0)
; template <class Epi, class Sched>
; __device__ __forceinline__ void gemm_phase(LAS unsigned char* lds, const Gemm g, const Sched& S, const Epi& E, const int tid) {
;     ...
;             PG8_LDB(B0, 1, 0); PG8_LDB(B1, 1, 1); PG8_SCHED; PG8_LDA(At, 1, 0); PG8_STAGE(PG8_SA(0, 1), a2 + hstepA, voffA);
;             PG8_WAIT_V(8); PG8_WAIT_L(0); PG8_BAR; PG8_MMA(0, 0, At, B0); PG8_MMA(0, 1, At, B1); PG8_BAR; PG8_SCHED;
;             PG8_LDA(At, 1, 1); PG8_STAGE(PG8_SB(1, 0), b3, voffB); PG8_STAGE(PG8_SB(1, 1), b3 + hstepB, voffB); PG8_STAGE(PG8_SA(1, 0), a3, voffA);
;             PG8_WAIT_V(8); PG8_WAIT_L(0); PG8_BAR; PG8_MMA(1, 0, At, B0); PG8_MMA(1, 1, At, B1); PG8_BAR; PG8_SCHED;
;         }
;         if (wr == 0) PG8_BAR;
	s_add_i32 s12, s74, s57
	v_lshl_add_u64 v[162:163], v[162:163], 0, s[28:29]
	s_mov_b32 m0, s12
	ds_read_b128 v[190:193], v145 offset:49152
	ds_read_b128 v[194:197], v145 offset:50176
	ds_read_b128 v[198:201], v145 offset:51200
	ds_read_b128 v[202:205], v145 offset:52224
	ds_read_b128 v[210:213], v145 offset:53248
	ds_read_b128 v[220:223], v145 offset:54272
	ds_read_b128 v[234:237], v145 offset:55296
	ds_read_b128 v[238:241], v145 offset:56320
	global_load_lds_dwordx4 v[162:163], off
	s_add_i32 m0, s12, 0x2000
	s_add_u32 s12, s86, 0x80080
	v_lshl_add_u64 v[162:163], v[206:207], 0, s[28:29]
	s_addc_u32 s13, s87, 0
	s_add_i32 s74, s96, s57
	global_load_lds_dwordx4 v[162:163], off
	v_lshl_add_u64 v[162:163], s[12:13], 0, v[164:165]
	s_mov_b32 m0, s74
	s_nop 0
	global_load_lds_dwordx4 v[162:163], off
	v_lshl_add_u64 v[162:163], s[12:13], 0, v[132:133]
	s_add_i32 m0, s74, 0x2000
	s_nop 0
	global_load_lds_dwordx4 v[162:163], off
	v_lshl_add_u64 v[162:163], v[224:225], 0, s[28:29]
	s_mov_b32 m0, s85
	s_nop 0
	global_load_lds_dwordx4 v[162:163], off
	v_lshl_add_u64 v[162:163], v[226:227], 0, s[28:29]
	s_mov_b32 m0, s90
	s_nop 0
	global_load_lds_dwordx4 v[162:163], off
	s_waitcnt vmcnt(8)
	s_waitcnt lgkmcnt(0)
	s_barrier
	s_waitcnt lgkmcnt(0)
	v_mfma_f32_16x16x32_bf16 v[64:67], v[146:149], v[190:193], v[64:67]
	v_mfma_f32_16x16x32_bf16 v[60:63], v[154:157], v[190:193], v[60:63]
	v_mfma_f32_16x16x32_bf16 v[56:59], v[146:149], v[198:201], v[56:59]
	v_mfma_f32_16x16x32_bf16 v[52:55], v[154:157], v[198:201], v[52:55]
	v_mfma_f32_16x16x32_bf16 v[40:43], v[146:149], v[210:213], v[40:43]
	v_mfma_f32_16x16x32_bf16 v[36:39], v[154:157], v[210:213], v[36:39]
	v_mfma_f32_16x16x32_bf16 v[24:27], v[146:149], v[234:237], v[24:27]
	v_mfma_f32_16x16x32_bf16 v[20:23], v[154:157], v[234:237], v[20:23]
	v_mfma_f32_16x16x32_bf16 v[64:67], v[150:153], v[194:197], v[64:67]
	v_mfma_f32_16x16x32_bf16 v[60:63], v[158:161], v[194:197], v[60:63]
	v_mfma_f32_16x16x32_bf16 v[56:59], v[150:153], v[202:205], v[56:59]
	v_mfma_f32_16x16x32_bf16 v[52:55], v[158:161], v[202:205], v[52:55]
	v_mfma_f32_16x16x32_bf16 v[40:43], v[150:153], v[220:223], v[40:43]
	v_mfma_f32_16x16x32_bf16 v[36:39], v[158:161], v[220:223], v[36:39]
	v_mfma_f32_16x16x32_bf16 v[24:27], v[150:153], v[238:241], v[24:27]
	v_mfma_f32_16x16x32_bf16 v[20:23], v[158:161], v[238:241], v[20:23]
	v_mfma_f32_16x16x32_bf16 v[48:51], v[174:177], v[190:193], v[48:51]
	v_mfma_f32_16x16x32_bf16 v[44:47], v[182:185], v[190:193], v[44:47]
	v_mfma_f32_16x16x32_bf16 v[32:35], v[174:177], v[198:201], v[32:35]
	v_mfma_f32_16x16x32_bf16 v[28:31], v[182:185], v[198:201], v[28:31]
	v_mfma_f32_16x16x32_bf16 v[16:19], v[174:177], v[210:213], v[16:19]
	v_mfma_f32_16x16x32_bf16 v[12:15], v[182:185], v[210:213], v[12:15]
	v_mfma_f32_16x16x32_bf16 v[8:11], v[174:177], v[234:237], v[8:11]
	v_mfma_f32_16x16x32_bf16 v[4:7], v[182:185], v[234:237], v[4:7]
	v_mfma_f32_16x16x32_bf16 v[48:51], v[178:181], v[194:197], v[48:51]
	v_mfma_f32_16x16x32_bf16 v[44:47], v[186:189], v[194:197], v[44:47]
	v_mfma_f32_16x16x32_bf16 v[32:35], v[178:181], v[202:205], v[32:35]
	v_mfma_f32_16x16x32_bf16 v[28:31], v[186:189], v[202:205], v[28:31]
	v_mfma_f32_16x16x32_bf16 v[16:19], v[178:181], v[220:223], v[16:19]
	v_mfma_f32_16x16x32_bf16 v[12:15], v[186:189], v[220:223], v[12:15]
	v_mfma_f32_16x16x32_bf16 v[8:11], v[178:181], v[238:241], v[8:11]
	v_mfma_f32_16x16x32_bf16 v[4:7], v[186:189], v[238:241], v[4:7]
	s_barrier
	s_add_i32 s95, s95, 2
	s_add_u32 s54, s54, 0x100
	s_addc_u32 s55, s55, 0
	s_add_u32 s93, s93, 0x100
	s_addc_u32 s94, s94, 0
	s_cmp_gt_u32 s95, 29
	s_cbranch_scc0 .LBB0_208
	s_and_b64 vcc, exec, s[30:31]
	s_cbranch_vccz .LBB0_211
	s_barrier
; __device__ __forceinline__ unsigned cvt_pk_bf16(float lo, float hi) { f32x2 v = {lo, hi}; bf16x2_t b = __builtin_convertvector(v, bf16x2_t); return __builtin_bit_cast(unsigned, b); }
;     __device__ __forceinline__ void operator()(const f32x4 (&acc)[2][2][4][2], const Unit& u, int wr, int wc, int fr, int fq) const {
;         const int row0 = u.pm * BM + wr * 64 + fr; const int col0 = u.pn * BM + wc * 32 + 8 * fq;
; #pragma unroll
;         for (int ai = 0; ai < 2; ++ai)
; #pragma unroll
;             for (int m = 0; m < 4; ++m)
; #pragma unroll
;                 for (int bj = 0; bj < 2; ++bj) {
;                     const f32x4 v0 = acc[ai][bj][m][0], v1 = acc[ai][bj][m][1];
;                     u32x4 w; w.x = cvt_pk_bf16(v0[0], v0[1]); w.y = cvt_pk_bf16(v0[2], v0[3]); w.z = cvt_pk_bf16(v1[0], v1[1]); w.w = cvt_pk_bf16(v1[2], v1[3]);
;                     __builtin_nontemporal_store(w, (u32x4*)(O + (size_t)(row0 + ai * HALF + m * 16) * ld + col0 + bj * HALF));
;                 }
.LBB0_211:
	v_lshl_add_u32 v148, s10, 8, v142
	v_lshl_or_b32 v146, s92, 8, v144
	v_ashrrev_i32_e32 v147, 31, v146
	v_cvt_pk_bf16_f32 v128, v128, v129
	v_cvt_pk_bf16_f32 v129, v130, v131
	v_cvt_pk_bf16_f32 v130, v124, v125
	v_mov_b64_e32 v[124:125], s[82:83]
	v_cvt_pk_bf16_f32 v72, v72, v73
	v_cvt_pk_bf16_f32 v73, v74, v75
	v_cvt_pk_bf16_f32 v74, v68, v69
	v_add_u32_e32 v68, 0x80, v148
	v_cvt_pk_bf16_f32 v131, v126, v127
	v_mad_i64_i32 v[126:127], s[12:13], v148, s60, v[124:125]
	v_lshlrev_b64 v[146:147], 1, v[146:147]
	v_cvt_pk_bf16_f32 v64, v64, v65
	v_cvt_pk_bf16_f32 v65, v66, v67
	v_cvt_pk_bf16_f32 v66, v60, v61
	v_mad_i64_i32 v[60:61], s[12:13], v68, s60, v[124:125]
	v_lshl_add_u64 v[126:127], v[126:127], 0, v[146:147]
	v_cvt_pk_bf16_f32 v112, v112, v113
	v_cvt_pk_bf16_f32 v113, v114, v115
	v_cvt_pk_bf16_f32 v114, v108, v109
	v_cvt_pk_bf16_f32 v115, v110, v111
	v_lshl_add_u64 v[60:61], v[60:61], 0, v[146:147]
	v_cvt_pk_bf16_f32 v48, v48, v49
	v_cvt_pk_bf16_f32 v49, v50, v51
	v_cvt_pk_bf16_f32 v50, v44, v45
	v_cvt_pk_bf16_f32 v51, v46, v47
	global_store_dwordx4 v[126:127], v[112:115], off offset:256
	global_store_dwordx4 v[60:61], v[48:51], off offset:256
	v_cvt_pk_bf16_f32 v96, v96, v97
	v_or_b32_e32 v112, 16, v148
	v_add_u32_e32 v48, 0x90, v148
	v_mad_i64_i32 v[112:113], s[12:13], v112, s60, v[124:125]
	v_mad_i64_i32 v[48:49], s[12:13], v48, s60, v[124:125]
	v_lshl_add_u64 v[112:113], v[112:113], 0, v[146:147]
	v_cvt_pk_bf16_f32 v97, v98, v99
	v_cvt_pk_bf16_f32 v98, v92, v93
	v_cvt_pk_bf16_f32 v99, v94, v95
	v_lshl_add_u64 v[48:49], v[48:49], 0, v[146:147]
	v_cvt_pk_bf16_f32 v32, v32, v33
	v_cvt_pk_bf16_f32 v33, v34, v35
	v_cvt_pk_bf16_f32 v34, v28, v29
	v_cvt_pk_bf16_f32 v35, v30, v31
	global_store_dwordx4 v[112:113], v[96:99], off offset:256
	global_store_dwordx4 v[48:49], v[32:35], off offset:256
	v_cvt_pk_bf16_f32 v80, v80, v81
	v_or_b32_e32 v96, 32, v148
	v_add_u32_e32 v32, 0xa0, v148
	v_mad_i64_i32 v[96:97], s[12:13], v96, s60, v[124:125]
	v_mad_i64_i32 v[32:33], s[12:13], v32, s60, v[124:125]
	v_lshl_add_u64 v[96:97], v[96:97], 0, v[146:147]
	v_cvt_pk_bf16_f32 v81, v82, v83
	v_cvt_pk_bf16_f32 v82, v76, v77
	v_cvt_pk_bf16_f32 v83, v78, v79
	v_lshl_add_u64 v[32:33], v[32:33], 0, v[146:147]
	v_cvt_pk_bf16_f32 v16, v16, v17
	v_cvt_pk_bf16_f32 v17, v18, v19
	v_cvt_pk_bf16_f32 v18, v12, v13
	v_cvt_pk_bf16_f32 v19, v14, v15
	global_store_dwordx4 v[96:97], v[80:83], off offset:256
	global_store_dwordx4 v[32:33], v[16:19], off offset:256
	v_cvt_pk_bf16_f32 v108, v120, v121
	v_or_b32_e32 v80, 48, v148
	v_add_u32_e32 v16, 0xb0, v148
	v_mad_i64_i32 v[80:81], s[12:13], v80, s60, v[124:125]
	v_mad_i64_i32 v[16:17], s[12:13], v16, s60, v[124:125]
	v_cvt_pk_bf16_f32 v109, v122, v123
	v_cvt_pk_bf16_f32 v110, v116, v117
	v_cvt_pk_bf16_f32 v111, v118, v119
	v_cvt_pk_bf16_f32 v92, v104, v105
	v_cvt_pk_bf16_f32 v93, v106, v107
	v_cvt_pk_bf16_f32 v94, v100, v101
	v_cvt_pk_bf16_f32 v95, v102, v103
	v_cvt_pk_bf16_f32 v76, v88, v89
	v_cvt_pk_bf16_f32 v77, v90, v91
	v_cvt_pk_bf16_f32 v78, v84, v85
	v_cvt_pk_bf16_f32 v79, v86, v87
	v_lshl_add_u64 v[80:81], v[80:81], 0, v[146:147]
	v_cvt_pk_bf16_f32 v75, v70, v71
	v_cvt_pk_bf16_f32 v67, v62, v63
	v_cvt_pk_bf16_f32 v44, v56, v57
	v_cvt_pk_bf16_f32 v45, v58, v59
	v_cvt_pk_bf16_f32 v46, v52, v53
	v_cvt_pk_bf16_f32 v47, v54, v55
	v_cvt_pk_bf16_f32 v28, v40, v41
	v_cvt_pk_bf16_f32 v29, v42, v43
	v_cvt_pk_bf16_f32 v30, v36, v37
	v_cvt_pk_bf16_f32 v31, v38, v39
	v_cvt_pk_bf16_f32 v12, v24, v25
	v_cvt_pk_bf16_f32 v13, v26, v27
	v_cvt_pk_bf16_f32 v14, v20, v21
	v_cvt_pk_bf16_f32 v15, v22, v23
	v_lshl_add_u64 v[16:17], v[16:17], 0, v[146:147]
	v_cvt_pk_bf16_f32 v8, v8, v9
	v_cvt_pk_bf16_f32 v9, v10, v11
	v_cvt_pk_bf16_f32 v10, v4, v5
	v_cvt_pk_bf16_f32 v11, v6, v7
	s_andn2_b64 vcc, exec, s[6:7]
	s_mov_b64 s[6:7], -1
	global_store_dwordx4 v[126:127], v[128:131], off
	global_store_dwordx4 v[112:113], v[108:111], off
	global_store_dwordx4 v[96:97], v[92:95], off
	global_store_dwordx4 v[80:81], v[76:79], off
	global_store_dwordx4 v[80:81], v[72:75], off offset:256
	global_store_dwordx4 v[60:61], v[64:67], off
	global_store_dwordx4 v[48:49], v[44:47], off
	global_store_dwordx4 v[32:33], v[28:31], off
	global_store_dwordx4 v[16:17], v[12:15], off
	global_store_dwordx4 v[16:17], v[8:11], off offset:256
	s_cbranch_vccnz .LBB0_204
	s_andn2_b64 vcc, exec, s[8:9]
	s_cbranch_vccnz .LBB0_203
	s_barrier
	s_branch .LBB0_203

; #define PG8_STAGE(bufoff, gbase, voff) do { _Pragma("unroll") for (int _i = 0; _i < 2; ++_i) \
;         __builtin_amdgcn_global_load_lds((const unsigned*)((const char*)(gbase) + (voff)[_i]), (LAS unsigned*)(lds + (bufoff) + ldsw + _i * 8192), 16, 0, 0); } while (0)
; #define PG8_LDA(dst, b, h) do { _Pragma("unroll") for (int m = 0; m < 4; ++m) _Pragma("unroll") for (int k = 0; k < 2; ++k) dst[m][k] = *(const LAS bf16x8*)(lds + PG8_SA(b, h) + aoff + m * 2048 + k * 1024); } while (0)
; #define PG8_LDB(dst, b, h) do { _Pragma("unroll") for (int n = 0; n < 2; ++n) _Pragma("unroll") for (int k = 0; k < 2; ++k) dst[n][k] = *(const LAS bf16x8*)(lds + PG8_SB(b, h) + boff + n * 2048 + k * 1024); } while (0)
; #define PG8_WAIT_V(n) asm volatile("s_waitcnt vmcnt(" #n ")" ::: "memory")
; #define PG8_BAR __builtin_amdgcn_s_barrier()
; template <class Epi, class Sched>
; __device__ __forceinline__ void gemm_phase(LAS unsigned char* lds, const Gemm g, const Sched& S, const Epi& E, const int tid) {
;     ...
;         for (int t = 0; t < nt; t += 2) {
;             const bool last = (t == nt - 2);
;             const char* a1 = cA + (size_t)(t + 1) * kstep;
;             const char* a2 = last ? nA : cA + (size_t)(t + 2) * kstep; const char* b2 = last ? nB : cB + (size_t)(t + 2) * kstep;
;             const char* a3 = a2 + kstep; const char* b3 = b2 + kstep;
;             PG8_LDB(B0, 0, 0); PG8_LDB(B1, 0, 1); PG8_SCHED; PG8_LDA(At, 0, 0); PG8_STAGE(PG8_SA(1, 1), a1 + hstepA, voffA);
;             PG8_WAIT_V(8); PG8_WAIT_L(0); PG8_BAR; PG8_MMA(0, 0, At, B0); PG8_MMA(0, 1, At, B1); PG8_BAR; PG8_SCHED;
;             PG8_LDA(At, 0, 1); PG8_STAGE(PG8_SB(0, 0), b2, voffB); PG8_STAGE(PG8_SB(0, 1), b2 + hstepB, voffB); PG8_STAGE(PG8_SA(0, 0), a2, voffA);
;             PG8_WAIT_V(8); PG8_WAIT_L(0); PG8_BAR; PG8_MMA(1, 0, At, B0); PG8_MMA(1, 1, At, B1); PG8_BAR; PG8_SCHED;
;             PG8_LDB(B0, 1, 0); PG8_LDB(B1, 1, 1); PG8_SCHED; PG8_LDA(At, 1, 0); PG8_STAGE(PG8_SA(0, 1), a2 + hstepA, voffA);
;             PG8_WAIT_V(8); PG8_WAIT_L(0); PG8_BAR; PG8_MMA(0, 0, At, B0); PG8_MMA(0, 1, At, B1); PG8_BAR; PG8_SCHED;
;             PG8_LDA(At, 1, 1); PG8_STAGE(PG8_SB(1, 0), b3, voffB); PG8_STAGE(PG8_SB(1, 1), b3 + hstepB, voffB); PG8_STAGE(PG8_SA(1, 0), a3, voffA);
;             PG8_WAIT_V(8); PG8_WAIT_L(0); PG8_BAR; PG8_MMA(1, 0, At, B0); PG8_MMA(1, 1, At, B1); PG8_BAR; PG8_SCHED;
.LBB0_251:
	s_add_u32 s8, s86, 0x100
	s_addc_u32 s9, s87, 0
	s_add_i32 s13, 0, 0x10000
	s_cmp_eq_u32 s12, 28
	s_cselect_b32 s91, s47, s9
	s_cselect_b32 s90, s46, s8
	s_cselect_b32 s89, s17, vcc_hi
	s_cselect_b32 s88, s45, vcc_lo
	s_add_i32 s74, 0, 0x14000
	v_add_u32_e32 v154, s13, v233
	v_add_u32_e32 v162, s74, v233
	ds_read_b128 v[142:145], v154
	ds_read_b128 v[146:149], v154 offset:1024
	ds_read_b128 v[150:153], v154 offset:2048
	ds_read_b128 v[154:157], v154 offset:3072
	ds_read_b128 v[158:161], v162
	ds_read_b128 v[174:177], v162 offset:1024
	ds_read_b128 v[178:181], v162 offset:2048
	ds_read_b128 v[182:185], v162 offset:3072
	v_lshl_add_u64 v[162:163], s[86:87], 0, v[138:139]
	s_add_i32 m0, s79, 0xc000
	ds_read_b128 v[186:189], v235
	ds_read_b128 v[190:193], v235 offset:1024
	ds_read_b128 v[194:197], v235 offset:2048
	ds_read_b128 v[198:201], v235 offset:3072
	ds_read_b128 v[202:205], v235 offset:4096
	ds_read_b128 v[210:213], v235 offset:5120
	ds_read_b128 v[220:223], v235 offset:6144
	ds_read_b128 v[236:239], v235 offset:7168
	global_load_lds_dwordx4 v[162:163], off
	v_lshl_add_u64 v[162:163], s[86:87], 0, v[140:141]
	s_add_i32 m0, s79, 0xe000
	s_nop 0
	global_load_lds_dwordx4 v[162:163], off
	s_waitcnt vmcnt(8)
	s_waitcnt lgkmcnt(0)
	s_barrier
	s_waitcnt lgkmcnt(0)
	v_mfma_f32_16x16x32_bf16 v[128:131], v[142:145], v[186:189], v[128:131]
	v_mfma_f32_16x16x32_bf16 v[96:99], v[150:153], v[186:189], v[96:99]
	v_mfma_f32_16x16x32_bf16 v[124:127], v[142:145], v[194:197], v[124:127]
	v_mfma_f32_16x16x32_bf16 v[92:95], v[150:153], v[194:197], v[92:95]
	v_mfma_f32_16x16x32_bf16 v[120:123], v[142:145], v[202:205], v[120:123]
	v_mfma_f32_16x16x32_bf16 v[88:91], v[150:153], v[202:205], v[88:91]
	v_mfma_f32_16x16x32_bf16 v[116:119], v[142:145], v[220:223], v[116:119]
	v_mfma_f32_16x16x32_bf16 v[84:87], v[150:153], v[220:223], v[84:87]
	v_mfma_f32_16x16x32_bf16 v[128:131], v[146:149], v[190:193], v[128:131]
	v_mfma_f32_16x16x32_bf16 v[96:99], v[154:157], v[190:193], v[96:99]
	v_mfma_f32_16x16x32_bf16 v[124:127], v[146:149], v[198:201], v[124:127]
	v_mfma_f32_16x16x32_bf16 v[92:95], v[154:157], v[198:201], v[92:95]
	v_mfma_f32_16x16x32_bf16 v[120:123], v[146:149], v[210:213], v[120:123]
	v_mfma_f32_16x16x32_bf16 v[88:91], v[154:157], v[210:213], v[88:91]
	v_mfma_f32_16x16x32_bf16 v[116:119], v[146:149], v[236:239], v[116:119]
	v_mfma_f32_16x16x32_bf16 v[84:87], v[154:157], v[236:239], v[84:87]
	v_mfma_f32_16x16x32_bf16 v[64:67], v[158:161], v[186:189], v[64:67]
	v_mfma_f32_16x16x32_bf16 v[32:35], v[178:181], v[186:189], v[32:35]
	v_mfma_f32_16x16x32_bf16 v[60:63], v[158:161], v[194:197], v[60:63]
	v_mfma_f32_16x16x32_bf16 v[28:31], v[178:181], v[194:197], v[28:31]
	v_mfma_f32_16x16x32_bf16 v[56:59], v[158:161], v[202:205], v[56:59]
	v_mfma_f32_16x16x32_bf16 v[24:27], v[178:181], v[202:205], v[24:27]
	v_mfma_f32_16x16x32_bf16 v[52:55], v[158:161], v[220:223], v[52:55]
	v_mfma_f32_16x16x32_bf16 v[20:23], v[178:181], v[220:223], v[20:23]
	v_mfma_f32_16x16x32_bf16 v[64:67], v[174:177], v[190:193], v[64:67]
	v_mfma_f32_16x16x32_bf16 v[32:35], v[182:185], v[190:193], v[32:35]
	v_mfma_f32_16x16x32_bf16 v[60:63], v[174:177], v[198:201], v[60:63]
	v_mfma_f32_16x16x32_bf16 v[28:31], v[182:185], v[198:201], v[28:31]
	v_mfma_f32_16x16x32_bf16 v[56:59], v[174:177], v[210:213], v[56:59]
	v_mfma_f32_16x16x32_bf16 v[24:27], v[182:185], v[210:213], v[24:27]
	v_mfma_f32_16x16x32_bf16 v[52:55], v[174:177], v[236:239], v[52:55]
	v_mfma_f32_16x16x32_bf16 v[20:23], v[182:185], v[236:239], v[20:23]
	s_barrier
	s_add_i32 s13, s13, s59
	v_lshl_add_u64 v[162:163], s[88:89], 0, v[164:165]
	s_mov_b32 m0, s13
	ds_read_b128 v[186:189], v235 offset:16384
	ds_read_b128 v[190:193], v235 offset:17408
	ds_read_b128 v[194:197], v235 offset:18432
	ds_read_b128 v[198:201], v235 offset:19456
	ds_read_b128 v[202:205], v235 offset:20480
	ds_read_b128 v[210:213], v235 offset:21504
	ds_read_b128 v[220:223], v235 offset:22528
	ds_read_b128 v[236:239], v235 offset:23552
	global_load_lds_dwordx4 v[162:163], off
	s_add_i32 m0, s13, 0x2000
	s_add_u32 s86, s88, 0x80000
	v_lshl_add_u64 v[206:207], s[88:89], 0, v[136:137]
	s_addc_u32 s87, s89, 0
	s_add_i32 s13, s74, s59
	global_load_lds_dwordx4 v[206:207], off
	v_lshl_add_u64 v[224:225], s[86:87], 0, v[164:165]
	s_mov_b32 m0, s13
	v_lshl_add_u64 v[226:227], s[90:91], 0, v[134:135]
	global_load_lds_dwordx4 v[224:225], off
	v_lshl_add_u64 v[224:225], s[86:87], 0, v[136:137]
	s_add_i32 m0, s13, 0x2000
	s_nop 0
	global_load_lds_dwordx4 v[224:225], off
	v_lshl_add_u64 v[224:225], s[90:91], 0, v[132:133]
	s_mov_b32 m0, s79
	s_nop 0
	global_load_lds_dwordx4 v[224:225], off
	s_mov_b32 m0, s84
	s_nop 0
	global_load_lds_dwordx4 v[226:227], off
	s_waitcnt vmcnt(8)
	s_waitcnt lgkmcnt(0)
	s_barrier
; #define PG8_STAGE(bufoff, gbase, voff) do { _Pragma("unroll") for (int _i = 0; _i < 2; ++_i) \
;         __builtin_amdgcn_global_load_lds((const unsigned*)((const char*)(gbase) + (voff)[_i]), (LAS unsigned*)(lds + (bufoff) + ldsw + _i * 8192), 16, 0, 0); } while (0)
; #define PG8_LDA(dst, b, h) do { _Pragma("unroll") for (int m = 0; m < 4; ++m) _Pragma("unroll") for (int k = 0; k < 2; ++k) dst[m][k] = *(const LAS bf16x8*)(lds + PG8_SA(b, h) + aoff + m * 2048 + k * 1024); } while (0)
; #define PG8_LDB(dst, b, h) do { _Pragma("unroll") for (int n = 0; n < 2; ++n) _Pragma("unroll") for (int k = 0; k < 2; ++k) dst[n][k] = *(const LAS bf16x8*)(lds + PG8_SB(b, h) + boff + n * 2048 + k * 1024); } while (0)
; #define PG8_MMA(ai, bj, At, Bt) do { __builtin_amdgcn_s_setprio(1); _Pragma("unroll") for (int m = 0; m < 4; ++m) _Pragma("unroll") for (int n = 0; n < 2; ++n) _Pragma("unroll") for (int k = 0; k < 2; ++k) \
;         acc[ai][bj][m][n] = __builtin_amdgcn_mfma_f32_16x16x32_bf16(Bt[n][k], At[m][k], acc[ai][bj][m][n], 0, 0, 0); __builtin_amdgcn_s_setprio(0); } while (0)
; #define PG8_WAIT_V(n) asm volatile("s_waitcnt vmcnt(" #n ")" ::: "memory")
; template <class Epi, class Sched>
; __device__ __forceinline__ void gemm_phase(LAS unsigned char* lds, const Gemm g, const Sched& S, const Epi& E, const int tid) {
;     ...
;             PG8_LDB(B0, 0, 0); PG8_LDB(B1, 0, 1); PG8_SCHED; PG8_LDA(At, 0, 0); PG8_STAGE(PG8_SA(1, 1), a1 + hstepA, voffA);
;             PG8_WAIT_V(8); PG8_WAIT_L(0); PG8_BAR; PG8_MMA(0, 0, At, B0); PG8_MMA(0, 1, At, B1); PG8_BAR; PG8_SCHED;
;             PG8_LDA(At, 0, 1); PG8_STAGE(PG8_SB(0, 0), b2, voffB); PG8_STAGE(PG8_SB(0, 1), b2 + hstepB, voffB); PG8_STAGE(PG8_SA(0, 0), a2, voffA);
;             PG8_WAIT_V(8); PG8_WAIT_L(0); PG8_BAR; PG8_MMA(1, 0, At, B0); PG8_MMA(1, 1, At, B1); PG8_BAR; PG8_SCHED;
;             PG8_LDB(B0, 1, 0); PG8_LDB(B1, 1, 1); PG8_SCHED; PG8_LDA(At, 1, 0); PG8_STAGE(PG8_SA(0, 1), a2 + hstepA, voffA);
;             PG8_WAIT_V(8); PG8_WAIT_L(0); PG8_BAR; PG8_MMA(0, 0, At, B0); PG8_MMA(0, 1, At, B1); PG8_BAR; PG8_SCHED;
;             PG8_LDA(At, 1, 1); PG8_STAGE(PG8_SB(1, 0), b3, voffB); PG8_STAGE(PG8_SB(1, 1), b3 + hstepB, voffB); PG8_STAGE(PG8_SA(1, 0), a3, voffA);
;             PG8_WAIT_V(8); PG8_WAIT_L(0); PG8_BAR; PG8_MMA(1, 0, At, B0); PG8_MMA(1, 1, At, B1); PG8_BAR; PG8_SCHED;
	s_waitcnt lgkmcnt(0)
	v_mfma_f32_16x16x32_bf16 v[112:115], v[142:145], v[186:189], v[112:115]
	v_mfma_f32_16x16x32_bf16 v[80:83], v[150:153], v[186:189], v[80:83]
	v_mfma_f32_16x16x32_bf16 v[108:111], v[142:145], v[194:197], v[108:111]
	v_mfma_f32_16x16x32_bf16 v[76:79], v[150:153], v[194:197], v[76:79]
	v_mfma_f32_16x16x32_bf16 v[104:107], v[142:145], v[202:205], v[104:107]
	v_mfma_f32_16x16x32_bf16 v[72:75], v[150:153], v[202:205], v[72:75]
	v_mfma_f32_16x16x32_bf16 v[100:103], v[142:145], v[220:223], v[100:103]
	v_mfma_f32_16x16x32_bf16 v[68:71], v[150:153], v[220:223], v[68:71]
	v_mfma_f32_16x16x32_bf16 v[112:115], v[146:149], v[190:193], v[112:115]
	v_mfma_f32_16x16x32_bf16 v[80:83], v[154:157], v[190:193], v[80:83]
	v_mfma_f32_16x16x32_bf16 v[108:111], v[146:149], v[198:201], v[108:111]
	v_mfma_f32_16x16x32_bf16 v[76:79], v[154:157], v[198:201], v[76:79]
	v_mfma_f32_16x16x32_bf16 v[104:107], v[146:149], v[210:213], v[104:107]
	v_mfma_f32_16x16x32_bf16 v[72:75], v[154:157], v[210:213], v[72:75]
	v_mfma_f32_16x16x32_bf16 v[100:103], v[146:149], v[236:239], v[100:103]
	v_mfma_f32_16x16x32_bf16 v[68:71], v[154:157], v[236:239], v[68:71]
	v_mfma_f32_16x16x32_bf16 v[48:51], v[158:161], v[186:189], v[48:51]
	v_mfma_f32_16x16x32_bf16 v[16:19], v[178:181], v[186:189], v[16:19]
	v_mfma_f32_16x16x32_bf16 v[44:47], v[158:161], v[194:197], v[44:47]
	v_mfma_f32_16x16x32_bf16 v[12:15], v[178:181], v[194:197], v[12:15]
	v_mfma_f32_16x16x32_bf16 v[40:43], v[158:161], v[202:205], v[40:43]
	v_mfma_f32_16x16x32_bf16 v[8:11], v[178:181], v[202:205], v[8:11]
	v_mfma_f32_16x16x32_bf16 v[36:39], v[158:161], v[220:223], v[36:39]
	v_mfma_f32_16x16x32_bf16 v[4:7], v[178:181], v[220:223], v[4:7]
	v_mfma_f32_16x16x32_bf16 v[48:51], v[174:177], v[190:193], v[48:51]
	v_mfma_f32_16x16x32_bf16 v[16:19], v[182:185], v[190:193], v[16:19]
	v_mfma_f32_16x16x32_bf16 v[44:47], v[174:177], v[198:201], v[44:47]
	v_mfma_f32_16x16x32_bf16 v[12:15], v[182:185], v[198:201], v[12:15]
	v_mfma_f32_16x16x32_bf16 v[40:43], v[174:177], v[210:213], v[40:43]
	v_mfma_f32_16x16x32_bf16 v[8:11], v[182:185], v[210:213], v[8:11]
	v_mfma_f32_16x16x32_bf16 v[36:39], v[174:177], v[236:239], v[36:39]
	v_mfma_f32_16x16x32_bf16 v[4:7], v[182:185], v[236:239], v[4:7]
	s_barrier
	s_add_i32 s13, 0, 0x18000
	s_add_i32 s74, 0, 0x1c000
	v_add_u32_e32 v154, s13, v233
	v_add_u32_e32 v182, s74, v233
	ds_read_b128 v[142:145], v154
	ds_read_b128 v[146:149], v154 offset:1024
	ds_read_b128 v[150:153], v154 offset:2048
	ds_read_b128 v[154:157], v154 offset:3072
	ds_read_b128 v[158:161], v182
	ds_read_b128 v[174:177], v182 offset:1024
	ds_read_b128 v[178:181], v182 offset:2048
	ds_read_b128 v[182:185], v182 offset:3072
	s_add_u32 s86, s90, 0x242000
	s_addc_u32 s87, s91, 0
	s_mov_b32 m0, s85
	v_lshl_add_u64 v[240:241], s[86:87], 0, v[132:133]
	ds_read_b128 v[186:189], v235 offset:32768
	ds_read_b128 v[190:193], v235 offset:33792
	ds_read_b128 v[194:197], v235 offset:34816
	ds_read_b128 v[198:201], v235 offset:35840
	ds_read_b128 v[202:205], v235 offset:36864
	ds_read_b128 v[210:213], v235 offset:37888
	ds_read_b128 v[220:223], v235 offset:38912
	ds_read_b128 v[236:239], v235 offset:39936
	global_load_lds_dwordx4 v[240:241], off
	v_lshl_add_u64 v[240:241], s[86:87], 0, v[134:135]
	s_mov_b32 m0, s92
	s_nop 0
	global_load_lds_dwordx4 v[240:241], off
	s_waitcnt vmcnt(8)
	s_waitcnt lgkmcnt(0)
	s_barrier
	s_waitcnt lgkmcnt(0)
	v_mfma_f32_16x16x32_bf16 v[128:131], v[142:145], v[186:189], v[128:131]
	v_mfma_f32_16x16x32_bf16 v[96:99], v[150:153], v[186:189], v[96:99]
	v_mfma_f32_16x16x32_bf16 v[124:127], v[142:145], v[194:197], v[124:127]
	v_mfma_f32_16x16x32_bf16 v[92:95], v[150:153], v[194:197], v[92:95]
	v_mfma_f32_16x16x32_bf16 v[120:123], v[142:145], v[202:205], v[120:123]
	v_mfma_f32_16x16x32_bf16 v[88:91], v[150:153], v[202:205], v[88:91]
	v_mfma_f32_16x16x32_bf16 v[116:119], v[142:145], v[220:223], v[116:119]
	v_mfma_f32_16x16x32_bf16 v[84:87], v[150:153], v[220:223], v[84:87]
	v_mfma_f32_16x16x32_bf16 v[128:131], v[146:149], v[190:193], v[128:131]
	v_mfma_f32_16x16x32_bf16 v[96:99], v[154:157], v[190:193], v[96:99]
	v_mfma_f32_16x16x32_bf16 v[124:127], v[146:149], v[198:201], v[124:127]
	v_mfma_f32_16x16x32_bf16 v[92:95], v[154:157], v[198:201], v[92:95]
	v_mfma_f32_16x16x32_bf16 v[120:123], v[146:149], v[210:213], v[120:123]
	v_mfma_f32_16x16x32_bf16 v[88:91], v[154:157], v[210:213], v[88:91]
	v_mfma_f32_16x16x32_bf16 v[116:119], v[146:149], v[236:239], v[116:119]
	v_mfma_f32_16x16x32_bf16 v[84:87], v[154:157], v[236:239], v[84:87]
	v_mfma_f32_16x16x32_bf16 v[64:67], v[158:161], v[186:189], v[64:67]
	v_mfma_f32_16x16x32_bf16 v[32:35], v[178:181], v[186:189], v[32:35]
	v_mfma_f32_16x16x32_bf16 v[60:63], v[158:161], v[194:197], v[60:63]
	v_mfma_f32_16x16x32_bf16 v[28:31], v[178:181], v[194:197], v[28:31]
	v_mfma_f32_16x16x32_bf16 v[56:59], v[158:161], v[202:205], v[56:59]
	v_mfma_f32_16x16x32_bf16 v[24:27], v[178:181], v[202:205], v[24:27]
	v_mfma_f32_16x16x32_bf16 v[52:55], v[158:161], v[220:223], v[52:55]
	v_mfma_f32_16x16x32_bf16 v[20:23], v[178:181], v[220:223], v[20:23]
	v_mfma_f32_16x16x32_bf16 v[64:67], v[174:177], v[190:193], v[64:67]
	v_mfma_f32_16x16x32_bf16 v[32:35], v[182:185], v[190:193], v[32:35]
	v_mfma_f32_16x16x32_bf16 v[60:63], v[174:177], v[198:201], v[60:63]
	v_mfma_f32_16x16x32_bf16 v[28:31], v[182:185], v[198:201], v[28:31]
	v_mfma_f32_16x16x32_bf16 v[56:59], v[174:177], v[210:213], v[56:59]
	v_mfma_f32_16x16x32_bf16 v[24:27], v[182:185], v[210:213], v[24:27]
	v_mfma_f32_16x16x32_bf16 v[52:55], v[174:177], v[236:239], v[52:55]
	v_mfma_f32_16x16x32_bf16 v[20:23], v[182:185], v[236:239], v[20:23]
	s_barrier
; #define PG8_STAGE(bufoff, gbase, voff) do { _Pragma("unroll") for (int _i = 0; _i < 2; ++_i) \
;         __builtin_amdgcn_global_load_lds((const unsigned*)((const char*)(gbase) + (voff)[_i]), (LAS unsigned*)(lds + (bufoff) + ldsw + _i * 8192), 16, 0, 0); } while (0)
; #define PG8_LDA(dst, b, h) do { _Pragma("unroll") for (int m = 0; m < 4; ++m) _Pragma("unroll") for (int k = 0; k < 2; ++k) dst[m][k] = *(const LAS bf16x8*)(lds + PG8_SA(b, h) + aoff + m * 2048 + k * 1024); } while (0)
; #define PG8_LDB(dst, b, h) do { _Pragma("unroll") for (int n = 0; n < 2; ++n) _Pragma("unroll") for (int k = 0; k < 2; ++k) dst[n][k] = *(const LAS bf16x8*)(lds + PG8_SB(b, h) + boff + n * 2048 + k * 1024); } while (0)
; template <class Epi, class Sched>
; __device__ __forceinline__ void gemm_phase(LAS unsigned char* lds, const Gemm g, const Sched& S, const Epi& E, const int tid) {
;     ...
;             PG8_LDB(B0, 1, 0); PG8_LDB(B1, 1, 1); PG8_SCHED; PG8_LDA(At, 1, 0); PG8_STAGE(PG8_SA(0, 1), a2 + hstepA, voffA);
;             PG8_WAIT_V(8); PG8_WAIT_L(0); PG8_BAR; PG8_MMA(0, 0, At, B0); PG8_MMA(0, 1, At, B1); PG8_BAR; PG8_SCHED;
;             PG8_LDA(At, 1, 1); PG8_STAGE(PG8_SB(1, 0), b3, voffB); PG8_STAGE(PG8_SB(1, 1), b3 + hstepB, voffB); PG8_STAGE(PG8_SA(1, 0), a3, voffA);
;             PG8_WAIT_V(8); PG8_WAIT_L(0); PG8_BAR; PG8_MMA(1, 0, At, B0); PG8_MMA(1, 1, At, B1); PG8_BAR; PG8_SCHED;
;         }
;         if (wr == 0) PG8_BAR;
;     __device__ __forceinline__ void operator()(const f32x4 (&acc)[2][2][4][2], const Unit& u, int wr, int wc, int fr, int fq) const {
;         const int row0 = u.pm * BM + wr * 64 + fr; const int col0 = u.pn * BM + wc * 32 + 4 * fq;
; #pragma unroll
;         for (int bj = 0; bj < 2; ++bj)
; #pragma unroll
;             for (int n = 0; n < 2; ++n) {
;                 const int col = col0 + bj * HALF + n * 16;
;                 f32x4 gg = {1.f, 1.f, 1.f, 1.f}, bb = {0.f, 0.f, 0.f, 0.f};
;                 if (NORM) { gg = *(const f32x4*)(gam + col); bb = *(const f32x4*)(bet + col); }
; #pragma unroll
;                 for (int ai = 0; ai < 2; ++ai) {
;                     f32x4 xv[4]; f32x2 st[4];
; #pragma unroll
;                     for (int m = 0; m < 4; ++m) { xv[m] = *(const f32x4*)(X + (size_t)(row0 + ai * HALF + m * 16) * D + col);
;                         if (NORM) st[m] = *(const f32x2*)(stats + 2 * (row0 + ai * HALF + m * 16)); }
	s_add_i32 s13, s13, s59
	v_lshl_add_u64 v[162:163], v[162:163], 0, s[28:29]
	s_mov_b32 m0, s13
	ds_read_b128 v[186:189], v235 offset:49152
	ds_read_b128 v[190:193], v235 offset:50176
	ds_read_b128 v[194:197], v235 offset:51200
	ds_read_b128 v[198:201], v235 offset:52224
	ds_read_b128 v[202:205], v235 offset:53248
	ds_read_b128 v[210:213], v235 offset:54272
	ds_read_b128 v[220:223], v235 offset:55296
	ds_read_b128 v[236:239], v235 offset:56320
	global_load_lds_dwordx4 v[162:163], off
	s_add_i32 m0, s13, 0x2000
	s_add_u32 s86, s88, 0x80080
	v_lshl_add_u64 v[162:163], v[206:207], 0, s[28:29]
	s_addc_u32 s87, s89, 0
	s_add_i32 s13, s74, s59
	global_load_lds_dwordx4 v[162:163], off
	v_lshl_add_u64 v[162:163], s[86:87], 0, v[164:165]
	s_mov_b32 m0, s13
	s_nop 0
	global_load_lds_dwordx4 v[162:163], off
	v_lshl_add_u64 v[162:163], s[86:87], 0, v[136:137]
	s_add_i32 m0, s13, 0x2000
	s_nop 0
	global_load_lds_dwordx4 v[162:163], off
	v_lshl_add_u64 v[162:163], v[224:225], 0, s[28:29]
	s_mov_b32 m0, s93
	s_nop 0
	global_load_lds_dwordx4 v[162:163], off
	v_lshl_add_u64 v[162:163], v[226:227], 0, s[28:29]
	s_mov_b32 m0, s94
	s_nop 0
	global_load_lds_dwordx4 v[162:163], off
	s_waitcnt vmcnt(8)
	s_waitcnt lgkmcnt(0)
	s_barrier
	s_waitcnt lgkmcnt(0)
	v_mfma_f32_16x16x32_bf16 v[112:115], v[142:145], v[186:189], v[112:115]
	v_mfma_f32_16x16x32_bf16 v[80:83], v[150:153], v[186:189], v[80:83]
	v_mfma_f32_16x16x32_bf16 v[108:111], v[142:145], v[194:197], v[108:111]
	v_mfma_f32_16x16x32_bf16 v[76:79], v[150:153], v[194:197], v[76:79]
	v_mfma_f32_16x16x32_bf16 v[104:107], v[142:145], v[202:205], v[104:107]
	v_mfma_f32_16x16x32_bf16 v[72:75], v[150:153], v[202:205], v[72:75]
	v_mfma_f32_16x16x32_bf16 v[100:103], v[142:145], v[220:223], v[100:103]
	v_mfma_f32_16x16x32_bf16 v[68:71], v[150:153], v[220:223], v[68:71]
	v_mfma_f32_16x16x32_bf16 v[112:115], v[146:149], v[190:193], v[112:115]
	v_mfma_f32_16x16x32_bf16 v[80:83], v[154:157], v[190:193], v[80:83]
	v_mfma_f32_16x16x32_bf16 v[108:111], v[146:149], v[198:201], v[108:111]
	v_mfma_f32_16x16x32_bf16 v[76:79], v[154:157], v[198:201], v[76:79]
	v_mfma_f32_16x16x32_bf16 v[104:107], v[146:149], v[210:213], v[104:107]
	v_mfma_f32_16x16x32_bf16 v[72:75], v[154:157], v[210:213], v[72:75]
	v_mfma_f32_16x16x32_bf16 v[100:103], v[146:149], v[236:239], v[100:103]
	v_mfma_f32_16x16x32_bf16 v[68:71], v[154:157], v[236:239], v[68:71]
	v_mfma_f32_16x16x32_bf16 v[48:51], v[158:161], v[186:189], v[48:51]
	v_mfma_f32_16x16x32_bf16 v[16:19], v[178:181], v[186:189], v[16:19]
	v_mfma_f32_16x16x32_bf16 v[44:47], v[158:161], v[194:197], v[44:47]
	v_mfma_f32_16x16x32_bf16 v[12:15], v[178:181], v[194:197], v[12:15]
	v_mfma_f32_16x16x32_bf16 v[40:43], v[158:161], v[202:205], v[40:43]
	v_mfma_f32_16x16x32_bf16 v[8:11], v[178:181], v[202:205], v[8:11]
	v_mfma_f32_16x16x32_bf16 v[36:39], v[158:161], v[220:223], v[36:39]
	v_mfma_f32_16x16x32_bf16 v[4:7], v[178:181], v[220:223], v[4:7]
	v_mfma_f32_16x16x32_bf16 v[48:51], v[174:177], v[190:193], v[48:51]
	v_mfma_f32_16x16x32_bf16 v[16:19], v[182:185], v[190:193], v[16:19]
	v_mfma_f32_16x16x32_bf16 v[44:47], v[174:177], v[198:201], v[44:47]
	v_mfma_f32_16x16x32_bf16 v[12:15], v[182:185], v[198:201], v[12:15]
	v_mfma_f32_16x16x32_bf16 v[40:43], v[174:177], v[210:213], v[40:43]
	v_mfma_f32_16x16x32_bf16 v[8:11], v[182:185], v[210:213], v[8:11]
	v_mfma_f32_16x16x32_bf16 v[36:39], v[174:177], v[236:239], v[36:39]
	v_mfma_f32_16x16x32_bf16 v[4:7], v[182:185], v[236:239], v[4:7]
	s_barrier
	s_add_i32 s12, s12, 2
	s_add_u32 vcc_lo, vcc_lo, 0x100
	s_addc_u32 vcc_hi, vcc_hi, 0
	s_cmp_gt_u32 s12, 29
	s_mov_b64 s[86:87], s[8:9]
	s_cbranch_scc0 .LBB0_251
	s_and_b64 vcc, exec, s[42:43]
	s_cbranch_vccz .LBB0_254
	s_barrier
.LBB0_254:
	v_lshl_add_u32 v225, s0, 8, v171
	v_lshl_or_b32 v226, s16, 8, v234
	v_lshlrev_b32_e32 v227, 3, v225
	v_lshlrev_b32_e32 v236, 2, v226
	v_lshl_add_u32 v224, v225, 13, v236
	global_load_dwordx2 v[162:163], v227, s[20:21]
	global_load_dwordx2 v[186:187], v227, s[20:21] offset:128
	global_load_dwordx2 v[188:189], v227, s[20:21] offset:256
	global_load_dwordx2 v[190:191], v227, s[20:21] offset:384
	global_load_dwordx2 v[192:193], v227, s[20:21] offset:1024
	global_load_dwordx2 v[194:195], v227, s[20:21] offset:1152
	global_load_dwordx2 v[196:197], v227, s[20:21] offset:1280
	global_load_dwordx2 v[198:199], v227, s[20:21] offset:1408
	global_load_dwordx4 v[200:203], v236, s[38:39]
	global_load_dwordx4 v[204:207], v236, s[10:11]
	global_load_dwordx4 v[210:213], v236, s[38:39] offset:64
	global_load_dwordx4 v[220:223], v236, s[10:11] offset:64
	global_load_dwordx4 v[142:145], v224, s[14:15]
	v_add_u32_e32 v226, 0x20000, v224
	global_load_dwordx4 v[146:149], v226, s[14:15]
	v_add_u32_e32 v225, 0x40000, v224
	global_load_dwordx4 v[150:153], v225, s[14:15]
	v_add_u32_e32 v226, 0x60000, v224
	global_load_dwordx4 v[154:157], v226, s[14:15]
	v_add_u32_e32 v225, 0x100000, v224
	global_load_dwordx4 v[158:161], v225, s[14:15]
	v_add_u32_e32 v226, 0x120000, v224
	global_load_dwordx4 v[174:177], v226, s[14:15]
	v_add_u32_e32 v225, 0x140000, v224
	global_load_dwordx4 v[178:181], v225, s[14:15]
	v_add_u32_e32 v226, 0x160000, v224
	global_load_dwordx4 v[182:185], v226, s[14:15]
	s_waitcnt vmcnt(4)
;     __device__ __forceinline__ void operator()(const f32x4 (&acc)[2][2][4][2], const Unit& u, int wr, int wc, int fr, int fq) const {
;     ...
;         for (int bj = 0; bj < 2; ++bj)
; #pragma unroll
;             for (int n = 0; n < 2; ++n) {
;                 const int col = col0 + bj * HALF + n * 16;
;                 f32x4 gg = {1.f, 1.f, 1.f, 1.f}, bb = {0.f, 0.f, 0.f, 0.f};
;                 if (NORM) { gg = *(const f32x4*)(gam + col); bb = *(const f32x4*)(bet + col); }
; #pragma unroll
;                 for (int ai = 0; ai < 2; ++ai) {
;                     f32x4 xv[4]; f32x2 st[4];
; #pragma unroll
;                     for (int m = 0; m < 4; ++m) { xv[m] = *(const f32x4*)(X + (size_t)(row0 + ai * HALF + m * 16) * D + col);
;                         if (NORM) st[m] = *(const f32x2*)(stats + 2 * (row0 + ai * HALF + m * 16)); }
; #pragma unroll
;                     for (int m = 0; m < 4; ++m) {
;                         f32x4 x = xv[m];
;                         if (NORM) x = (x - st[m].x) * st[m].y * gg + bb;
;                         if (!dry) *(f32x4*)(X + (size_t)(row0 + ai * HALF + m * 16) * D + col) = x * ALPHA + acc[ai][bj][m][n];
;                     }
;                 }
	v_sub_f32_e32 v143, v143, v162
	v_sub_f32_e32 v142, v142, v162
	v_sub_f32_e32 v145, v145, v162
	v_sub_f32_e32 v144, v144, v162
	v_pk_mul_f32 v[144:145], v[162:163], v[144:145] op_sel:[1,0]
	v_pk_mul_f32 v[142:143], v[162:163], v[142:143] op_sel:[1,0]
	v_pk_fma_f32 v[142:143], v[200:201], v[142:143], v[204:205]
	v_pk_fma_f32 v[144:145], v[202:203], v[144:145], v[206:207]
	v_pk_fma_f32 v[130:131], v[144:145], s[34:35], v[130:131] op_sel_hi:[1,0,1]
	v_pk_fma_f32 v[128:129], v[142:143], s[34:35], v[128:129] op_sel_hi:[1,0,1]
	v_sub_f32_e32 v147, v147, v186
	v_sub_f32_e32 v146, v146, v186
	v_sub_f32_e32 v149, v149, v186
	v_sub_f32_e32 v148, v148, v186
	v_pk_mul_f32 v[148:149], v[186:187], v[148:149] op_sel:[1,0]
	v_pk_mul_f32 v[146:147], v[186:187], v[146:147] op_sel:[1,0]
	v_pk_fma_f32 v[146:147], v[200:201], v[146:147], v[204:205]
	v_pk_fma_f32 v[148:149], v[202:203], v[148:149], v[206:207]
	v_pk_fma_f32 v[126:127], v[148:149], s[34:35], v[126:127] op_sel_hi:[1,0,1]
	v_pk_fma_f32 v[124:125], v[146:147], s[34:35], v[124:125] op_sel_hi:[1,0,1]
	v_sub_f32_e32 v151, v151, v188
	v_sub_f32_e32 v150, v150, v188
	v_sub_f32_e32 v153, v153, v188
	v_sub_f32_e32 v152, v152, v188
	v_pk_mul_f32 v[152:153], v[188:189], v[152:153] op_sel:[1,0]
	v_pk_mul_f32 v[150:151], v[188:189], v[150:151] op_sel:[1,0]
	v_pk_fma_f32 v[150:151], v[200:201], v[150:151], v[204:205]
	v_pk_fma_f32 v[152:153], v[202:203], v[152:153], v[206:207]
	v_pk_fma_f32 v[122:123], v[152:153], s[34:35], v[122:123] op_sel_hi:[1,0,1]
	v_pk_fma_f32 v[120:121], v[150:151], s[34:35], v[120:121] op_sel_hi:[1,0,1]
	v_sub_f32_e32 v155, v155, v190
	v_sub_f32_e32 v154, v154, v190
	v_sub_f32_e32 v157, v157, v190
	v_sub_f32_e32 v156, v156, v190
	v_pk_mul_f32 v[156:157], v[190:191], v[156:157] op_sel:[1,0]
	v_pk_mul_f32 v[154:155], v[190:191], v[154:155] op_sel:[1,0]
	v_pk_fma_f32 v[154:155], v[200:201], v[154:155], v[204:205]
	v_pk_fma_f32 v[156:157], v[202:203], v[156:157], v[206:207]
	v_pk_fma_f32 v[118:119], v[156:157], s[34:35], v[118:119] op_sel_hi:[1,0,1]
	v_pk_fma_f32 v[116:117], v[154:155], s[34:35], v[116:117] op_sel_hi:[1,0,1]
	global_load_dwordx4 v[142:145], v224, s[14:15] offset:64
	v_add_u32_e32 v226, 0x20000, v224
	global_load_dwordx4 v[146:149], v226, s[14:15] offset:64
	v_add_u32_e32 v225, 0x40000, v224
	global_load_dwordx4 v[150:153], v225, s[14:15] offset:64
	v_add_u32_e32 v226, 0x60000, v224
	global_load_dwordx4 v[154:157], v226, s[14:15] offset:64
	global_store_dwordx4 v224, v[128:131], s[14:15]
	v_add_u32_e32 v226, 0x20000, v224
	global_store_dwordx4 v226, v[124:127], s[14:15]
	v_add_u32_e32 v225, 0x40000, v224
	global_store_dwordx4 v225, v[120:123], s[14:15]
	v_add_u32_e32 v226, 0x60000, v224
	global_store_dwordx4 v226, v[116:119], s[14:15]
	s_waitcnt vmcnt(8)
	v_sub_f32_e32 v159, v159, v192
	v_sub_f32_e32 v158, v158, v192
	v_sub_f32_e32 v161, v161, v192
	v_sub_f32_e32 v160, v160, v192
	v_pk_mul_f32 v[160:161], v[192:193], v[160:161] op_sel:[1,0]
	v_pk_mul_f32 v[158:159], v[192:193], v[158:159] op_sel:[1,0]
	v_pk_fma_f32 v[158:159], v[200:201], v[158:159], v[204:205]
	v_pk_fma_f32 v[160:161], v[202:203], v[160:161], v[206:207]
	v_pk_fma_f32 v[114:115], v[160:161], s[34:35], v[114:115] op_sel_hi:[1,0,1]
	v_pk_fma_f32 v[112:113], v[158:159], s[34:35], v[112:113] op_sel_hi:[1,0,1]
	v_sub_f32_e32 v175, v175, v194
	v_sub_f32_e32 v174, v174, v194
	v_sub_f32_e32 v177, v177, v194
	v_sub_f32_e32 v176, v176, v194
	v_pk_mul_f32 v[176:177], v[194:195], v[176:177] op_sel:[1,0]
	v_pk_mul_f32 v[174:175], v[194:195], v[174:175] op_sel:[1,0]
	v_pk_fma_f32 v[174:175], v[200:201], v[174:175], v[204:205]
	v_pk_fma_f32 v[176:177], v[202:203], v[176:177], v[206:207]
	v_pk_fma_f32 v[110:111], v[176:177], s[34:35], v[110:111] op_sel_hi:[1,0,1]
	v_pk_fma_f32 v[108:109], v[174:175], s[34:35], v[108:109] op_sel_hi:[1,0,1]
	v_sub_f32_e32 v179, v179, v196
	v_sub_f32_e32 v178, v178, v196
	v_sub_f32_e32 v181, v181, v196
	v_sub_f32_e32 v180, v180, v196
	v_pk_mul_f32 v[180:181], v[196:197], v[180:181] op_sel:[1,0]
	v_pk_mul_f32 v[178:179], v[196:197], v[178:179] op_sel:[1,0]
	v_pk_fma_f32 v[178:179], v[200:201], v[178:179], v[204:205]
	v_pk_fma_f32 v[180:181], v[202:203], v[180:181], v[206:207]
	v_pk_fma_f32 v[106:107], v[180:181], s[34:35], v[106:107] op_sel_hi:[1,0,1]
	v_pk_fma_f32 v[104:105], v[178:179], s[34:35], v[104:105] op_sel_hi:[1,0,1]
	v_sub_f32_e32 v183, v183, v198
	v_sub_f32_e32 v182, v182, v198
	v_sub_f32_e32 v185, v185, v198
	v_sub_f32_e32 v184, v184, v198
	v_pk_mul_f32 v[184:185], v[198:199], v[184:185] op_sel:[1,0]
	v_pk_mul_f32 v[182:183], v[198:199], v[182:183] op_sel:[1,0]
	v_pk_fma_f32 v[182:183], v[200:201], v[182:183], v[204:205]
	v_pk_fma_f32 v[184:185], v[202:203], v[184:185], v[206:207]
	v_pk_fma_f32 v[102:103], v[184:185], s[34:35], v[102:103] op_sel_hi:[1,0,1]
	v_pk_fma_f32 v[100:101], v[182:183], s[34:35], v[100:101] op_sel_hi:[1,0,1]
	global_load_dwordx4 v[200:203], v236, s[38:39] offset:512
	global_load_dwordx4 v[204:207], v236, s[10:11] offset:512
	v_add_u32_e32 v225, 0x100000, v224
	global_load_dwordx4 v[158:161], v225, s[14:15] offset:64
	v_add_u32_e32 v226, 0x120000, v224
	global_load_dwordx4 v[174:177], v226, s[14:15] offset:64
	v_add_u32_e32 v225, 0x140000, v224
	global_load_dwordx4 v[178:181], v225, s[14:15] offset:64
	v_add_u32_e32 v226, 0x160000, v224
	global_load_dwordx4 v[182:185], v226, s[14:15] offset:64
	v_add_u32_e32 v225, 0x100000, v224
	global_store_dwordx4 v225, v[112:115], s[14:15]
	v_add_u32_e32 v226, 0x120000, v224
	global_store_dwordx4 v226, v[108:111], s[14:15]
	v_add_u32_e32 v225, 0x140000, v224
	global_store_dwordx4 v225, v[104:107], s[14:15]
	v_add_u32_e32 v226, 0x160000, v224
	global_store_dwordx4 v226, v[100:103], s[14:15]
	s_waitcnt vmcnt(14)
;     __device__ __forceinline__ void operator()(const f32x4 (&acc)[2][2][4][2], const Unit& u, int wr, int wc, int fr, int fq) const {
;     ...
;         for (int bj = 0; bj < 2; ++bj)
; #pragma unroll
;             for (int n = 0; n < 2; ++n) {
;                 const int col = col0 + bj * HALF + n * 16;
;                 f32x4 gg = {1.f, 1.f, 1.f, 1.f}, bb = {0.f, 0.f, 0.f, 0.f};
;                 if (NORM) { gg = *(const f32x4*)(gam + col); bb = *(const f32x4*)(bet + col); }
; #pragma unroll
;                 for (int ai = 0; ai < 2; ++ai) {
;                     f32x4 xv[4]; f32x2 st[4];
; #pragma unroll
;                     for (int m = 0; m < 4; ++m) { xv[m] = *(const f32x4*)(X + (size_t)(row0 + ai * HALF + m * 16) * D + col);
;                         if (NORM) st[m] = *(const f32x2*)(stats + 2 * (row0 + ai * HALF + m * 16)); }
; #pragma unroll
;                     for (int m = 0; m < 4; ++m) {
;                         f32x4 x = xv[m];
;                         if (NORM) x = (x - st[m].x) * st[m].y * gg + bb;
;                         if (!dry) *(f32x4*)(X + (size_t)(row0 + ai * HALF + m * 16) * D + col) = x * ALPHA + acc[ai][bj][m][n];
;                     }
;                 }
	v_sub_f32_e32 v143, v143, v162
	v_sub_f32_e32 v142, v142, v162
	v_sub_f32_e32 v145, v145, v162
	v_sub_f32_e32 v144, v144, v162
	v_pk_mul_f32 v[144:145], v[162:163], v[144:145] op_sel:[1,0]
	v_pk_mul_f32 v[142:143], v[162:163], v[142:143] op_sel:[1,0]
	v_pk_fma_f32 v[142:143], v[210:211], v[142:143], v[220:221]
	v_pk_fma_f32 v[144:145], v[212:213], v[144:145], v[222:223]
	v_pk_fma_f32 v[98:99], v[144:145], s[34:35], v[98:99] op_sel_hi:[1,0,1]
	v_pk_fma_f32 v[96:97], v[142:143], s[34:35], v[96:97] op_sel_hi:[1,0,1]
	v_sub_f32_e32 v147, v147, v186
	v_sub_f32_e32 v146, v146, v186
	v_sub_f32_e32 v149, v149, v186
	v_sub_f32_e32 v148, v148, v186
	v_pk_mul_f32 v[148:149], v[186:187], v[148:149] op_sel:[1,0]
	v_pk_mul_f32 v[146:147], v[186:187], v[146:147] op_sel:[1,0]
	v_pk_fma_f32 v[146:147], v[210:211], v[146:147], v[220:221]
	v_pk_fma_f32 v[148:149], v[212:213], v[148:149], v[222:223]
	v_pk_fma_f32 v[94:95], v[148:149], s[34:35], v[94:95] op_sel_hi:[1,0,1]
	v_pk_fma_f32 v[92:93], v[146:147], s[34:35], v[92:93] op_sel_hi:[1,0,1]
	v_sub_f32_e32 v151, v151, v188
	v_sub_f32_e32 v150, v150, v188
	v_sub_f32_e32 v153, v153, v188
	v_sub_f32_e32 v152, v152, v188
	v_pk_mul_f32 v[152:153], v[188:189], v[152:153] op_sel:[1,0]
	v_pk_mul_f32 v[150:151], v[188:189], v[150:151] op_sel:[1,0]
	v_pk_fma_f32 v[150:151], v[210:211], v[150:151], v[220:221]
	v_pk_fma_f32 v[152:153], v[212:213], v[152:153], v[222:223]
	v_pk_fma_f32 v[90:91], v[152:153], s[34:35], v[90:91] op_sel_hi:[1,0,1]
	v_pk_fma_f32 v[88:89], v[150:151], s[34:35], v[88:89] op_sel_hi:[1,0,1]
	v_sub_f32_e32 v155, v155, v190
	v_sub_f32_e32 v154, v154, v190
	v_sub_f32_e32 v157, v157, v190
	v_sub_f32_e32 v156, v156, v190
	v_pk_mul_f32 v[156:157], v[190:191], v[156:157] op_sel:[1,0]
	v_pk_mul_f32 v[154:155], v[190:191], v[154:155] op_sel:[1,0]
	v_pk_fma_f32 v[154:155], v[210:211], v[154:155], v[220:221]
	v_pk_fma_f32 v[156:157], v[212:213], v[156:157], v[222:223]
	v_pk_fma_f32 v[86:87], v[156:157], s[34:35], v[86:87] op_sel_hi:[1,0,1]
	v_pk_fma_f32 v[84:85], v[154:155], s[34:35], v[84:85] op_sel_hi:[1,0,1]
	global_load_dwordx4 v[142:145], v224, s[14:15] offset:512
	v_add_u32_e32 v226, 0x20000, v224
	global_load_dwordx4 v[146:149], v226, s[14:15] offset:512
	v_add_u32_e32 v225, 0x40000, v224
	global_load_dwordx4 v[150:153], v225, s[14:15] offset:512
	v_add_u32_e32 v226, 0x60000, v224
	global_load_dwordx4 v[154:157], v226, s[14:15] offset:512
	global_store_dwordx4 v224, v[96:99], s[14:15] offset:64
	v_add_u32_e32 v226, 0x20000, v224
	global_store_dwordx4 v226, v[92:95], s[14:15] offset:64
	v_add_u32_e32 v225, 0x40000, v224
	global_store_dwordx4 v225, v[88:91], s[14:15] offset:64
	v_add_u32_e32 v226, 0x60000, v224
	global_store_dwordx4 v226, v[84:87], s[14:15] offset:64
	s_waitcnt vmcnt(12)
	v_sub_f32_e32 v159, v159, v192
	v_sub_f32_e32 v158, v158, v192
	v_sub_f32_e32 v161, v161, v192
	v_sub_f32_e32 v160, v160, v192
	v_pk_mul_f32 v[160:161], v[192:193], v[160:161] op_sel:[1,0]
	v_pk_mul_f32 v[158:159], v[192:193], v[158:159] op_sel:[1,0]
	v_pk_fma_f32 v[158:159], v[210:211], v[158:159], v[220:221]
	v_pk_fma_f32 v[160:161], v[212:213], v[160:161], v[222:223]
	v_pk_fma_f32 v[82:83], v[160:161], s[34:35], v[82:83] op_sel_hi:[1,0,1]
	v_pk_fma_f32 v[80:81], v[158:159], s[34:35], v[80:81] op_sel_hi:[1,0,1]
	v_sub_f32_e32 v175, v175, v194
	v_sub_f32_e32 v174, v174, v194
	v_sub_f32_e32 v177, v177, v194
	v_sub_f32_e32 v176, v176, v194
	v_pk_mul_f32 v[176:177], v[194:195], v[176:177] op_sel:[1,0]
	v_pk_mul_f32 v[174:175], v[194:195], v[174:175] op_sel:[1,0]
	v_pk_fma_f32 v[174:175], v[210:211], v[174:175], v[220:221]
	v_pk_fma_f32 v[176:177], v[212:213], v[176:177], v[222:223]
	v_pk_fma_f32 v[78:79], v[176:177], s[34:35], v[78:79] op_sel_hi:[1,0,1]
	v_pk_fma_f32 v[76:77], v[174:175], s[34:35], v[76:77] op_sel_hi:[1,0,1]
	v_sub_f32_e32 v179, v179, v196
	v_sub_f32_e32 v178, v178, v196
	v_sub_f32_e32 v181, v181, v196
	v_sub_f32_e32 v180, v180, v196
	v_pk_mul_f32 v[180:181], v[196:197], v[180:181] op_sel:[1,0]
	v_pk_mul_f32 v[178:179], v[196:197], v[178:179] op_sel:[1,0]
	v_pk_fma_f32 v[178:179], v[210:211], v[178:179], v[220:221]
	v_pk_fma_f32 v[180:181], v[212:213], v[180:181], v[222:223]
	v_pk_fma_f32 v[74:75], v[180:181], s[34:35], v[74:75] op_sel_hi:[1,0,1]
	v_pk_fma_f32 v[72:73], v[178:179], s[34:35], v[72:73] op_sel_hi:[1,0,1]
	v_sub_f32_e32 v183, v183, v198
	v_sub_f32_e32 v182, v182, v198
	v_sub_f32_e32 v185, v185, v198
	v_sub_f32_e32 v184, v184, v198
	v_pk_mul_f32 v[184:185], v[198:199], v[184:185] op_sel:[1,0]
	v_pk_mul_f32 v[182:183], v[198:199], v[182:183] op_sel:[1,0]
	v_pk_fma_f32 v[182:183], v[210:211], v[182:183], v[220:221]
	v_pk_fma_f32 v[184:185], v[212:213], v[184:185], v[222:223]
	v_pk_fma_f32 v[70:71], v[184:185], s[34:35], v[70:71] op_sel_hi:[1,0,1]
	v_pk_fma_f32 v[68:69], v[182:183], s[34:35], v[68:69] op_sel_hi:[1,0,1]
	global_load_dwordx4 v[210:213], v236, s[38:39] offset:576
	global_load_dwordx4 v[220:223], v236, s[10:11] offset:576
	v_add_u32_e32 v225, 0x100000, v224
	global_load_dwordx4 v[158:161], v225, s[14:15] offset:512
	v_add_u32_e32 v226, 0x120000, v224
	global_load_dwordx4 v[174:177], v226, s[14:15] offset:512
	v_add_u32_e32 v225, 0x140000, v224
	global_load_dwordx4 v[178:181], v225, s[14:15] offset:512
	v_add_u32_e32 v226, 0x160000, v224
	global_load_dwordx4 v[182:185], v226, s[14:15] offset:512
	v_add_u32_e32 v225, 0x100000, v224
	global_store_dwordx4 v225, v[80:83], s[14:15] offset:64
	v_add_u32_e32 v226, 0x120000, v224
	global_store_dwordx4 v226, v[76:79], s[14:15] offset:64
	v_add_u32_e32 v225, 0x140000, v224
	global_store_dwordx4 v225, v[72:75], s[14:15] offset:64
	v_add_u32_e32 v226, 0x160000, v224
	global_store_dwordx4 v226, v[68:71], s[14:15] offset:64
	s_waitcnt vmcnt(14)
;     __device__ __forceinline__ void operator()(const f32x4 (&acc)[2][2][4][2], const Unit& u, int wr, int wc, int fr, int fq) const {
;     ...
;         for (int bj = 0; bj < 2; ++bj)
; #pragma unroll
;             for (int n = 0; n < 2; ++n) {
;                 const int col = col0 + bj * HALF + n * 16;
;                 f32x4 gg = {1.f, 1.f, 1.f, 1.f}, bb = {0.f, 0.f, 0.f, 0.f};
;                 if (NORM) { gg = *(const f32x4*)(gam + col); bb = *(const f32x4*)(bet + col); }
; #pragma unroll
;                 for (int ai = 0; ai < 2; ++ai) {
;                     f32x4 xv[4]; f32x2 st[4];
; #pragma unroll
;                     for (int m = 0; m < 4; ++m) { xv[m] = *(const f32x4*)(X + (size_t)(row0 + ai * HALF + m * 16) * D + col);
;                         if (NORM) st[m] = *(const f32x2*)(stats + 2 * (row0 + ai * HALF + m * 16)); }
; #pragma unroll
;                     for (int m = 0; m < 4; ++m) {
;                         f32x4 x = xv[m];
;                         if (NORM) x = (x - st[m].x) * st[m].y * gg + bb;
;                         if (!dry) *(f32x4*)(X + (size_t)(row0 + ai * HALF + m * 16) * D + col) = x * ALPHA + acc[ai][bj][m][n];
;                     }
;                 }
	v_sub_f32_e32 v143, v143, v162
	v_sub_f32_e32 v142, v142, v162
	v_sub_f32_e32 v145, v145, v162
	v_sub_f32_e32 v144, v144, v162
	v_pk_mul_f32 v[144:145], v[162:163], v[144:145] op_sel:[1,0]
	v_pk_mul_f32 v[142:143], v[162:163], v[142:143] op_sel:[1,0]
	v_pk_fma_f32 v[142:143], v[200:201], v[142:143], v[204:205]
	v_pk_fma_f32 v[144:145], v[202:203], v[144:145], v[206:207]
	v_pk_fma_f32 v[66:67], v[144:145], s[34:35], v[66:67] op_sel_hi:[1,0,1]
	v_pk_fma_f32 v[64:65], v[142:143], s[34:35], v[64:65] op_sel_hi:[1,0,1]
	v_sub_f32_e32 v147, v147, v186
	v_sub_f32_e32 v146, v146, v186
	v_sub_f32_e32 v149, v149, v186
	v_sub_f32_e32 v148, v148, v186
	v_pk_mul_f32 v[148:149], v[186:187], v[148:149] op_sel:[1,0]
	v_pk_mul_f32 v[146:147], v[186:187], v[146:147] op_sel:[1,0]
	v_pk_fma_f32 v[146:147], v[200:201], v[146:147], v[204:205]
	v_pk_fma_f32 v[148:149], v[202:203], v[148:149], v[206:207]
	v_pk_fma_f32 v[62:63], v[148:149], s[34:35], v[62:63] op_sel_hi:[1,0,1]
	v_pk_fma_f32 v[60:61], v[146:147], s[34:35], v[60:61] op_sel_hi:[1,0,1]
	v_sub_f32_e32 v151, v151, v188
	v_sub_f32_e32 v150, v150, v188
	v_sub_f32_e32 v153, v153, v188
	v_sub_f32_e32 v152, v152, v188
	v_pk_mul_f32 v[152:153], v[188:189], v[152:153] op_sel:[1,0]
	v_pk_mul_f32 v[150:151], v[188:189], v[150:151] op_sel:[1,0]
	v_pk_fma_f32 v[150:151], v[200:201], v[150:151], v[204:205]
	v_pk_fma_f32 v[152:153], v[202:203], v[152:153], v[206:207]
	v_pk_fma_f32 v[58:59], v[152:153], s[34:35], v[58:59] op_sel_hi:[1,0,1]
	v_pk_fma_f32 v[56:57], v[150:151], s[34:35], v[56:57] op_sel_hi:[1,0,1]
	v_sub_f32_e32 v155, v155, v190
	v_sub_f32_e32 v154, v154, v190
	v_sub_f32_e32 v157, v157, v190
	v_sub_f32_e32 v156, v156, v190
	v_pk_mul_f32 v[156:157], v[190:191], v[156:157] op_sel:[1,0]
	v_pk_mul_f32 v[154:155], v[190:191], v[154:155] op_sel:[1,0]
	v_pk_fma_f32 v[154:155], v[200:201], v[154:155], v[204:205]
	v_pk_fma_f32 v[156:157], v[202:203], v[156:157], v[206:207]
	v_pk_fma_f32 v[54:55], v[156:157], s[34:35], v[54:55] op_sel_hi:[1,0,1]
	v_pk_fma_f32 v[52:53], v[154:155], s[34:35], v[52:53] op_sel_hi:[1,0,1]
	global_load_dwordx4 v[142:145], v224, s[14:15] offset:576
	v_add_u32_e32 v226, 0x20000, v224
	global_load_dwordx4 v[146:149], v226, s[14:15] offset:576
	v_add_u32_e32 v225, 0x40000, v224
	global_load_dwordx4 v[150:153], v225, s[14:15] offset:576
	v_add_u32_e32 v226, 0x60000, v224
	global_load_dwordx4 v[154:157], v226, s[14:15] offset:576
	global_store_dwordx4 v224, v[64:67], s[14:15] offset:512
	v_add_u32_e32 v226, 0x20000, v224
	global_store_dwordx4 v226, v[60:63], s[14:15] offset:512
	v_add_u32_e32 v225, 0x40000, v224
	global_store_dwordx4 v225, v[56:59], s[14:15] offset:512
	v_add_u32_e32 v226, 0x60000, v224
	global_store_dwordx4 v226, v[52:55], s[14:15] offset:512
	s_waitcnt vmcnt(12)
	v_sub_f32_e32 v159, v159, v192
	v_sub_f32_e32 v158, v158, v192
	v_sub_f32_e32 v161, v161, v192
	v_sub_f32_e32 v160, v160, v192
	v_pk_mul_f32 v[160:161], v[192:193], v[160:161] op_sel:[1,0]
	v_pk_mul_f32 v[158:159], v[192:193], v[158:159] op_sel:[1,0]
	v_pk_fma_f32 v[158:159], v[200:201], v[158:159], v[204:205]
	v_pk_fma_f32 v[160:161], v[202:203], v[160:161], v[206:207]
	v_pk_fma_f32 v[50:51], v[160:161], s[34:35], v[50:51] op_sel_hi:[1,0,1]
	v_pk_fma_f32 v[48:49], v[158:159], s[34:35], v[48:49] op_sel_hi:[1,0,1]
	v_sub_f32_e32 v175, v175, v194
	v_sub_f32_e32 v174, v174, v194
	v_sub_f32_e32 v177, v177, v194
	v_sub_f32_e32 v176, v176, v194
	v_pk_mul_f32 v[176:177], v[194:195], v[176:177] op_sel:[1,0]
	v_pk_mul_f32 v[174:175], v[194:195], v[174:175] op_sel:[1,0]
	v_pk_fma_f32 v[174:175], v[200:201], v[174:175], v[204:205]
	v_pk_fma_f32 v[176:177], v[202:203], v[176:177], v[206:207]
	v_pk_fma_f32 v[46:47], v[176:177], s[34:35], v[46:47] op_sel_hi:[1,0,1]
	v_pk_fma_f32 v[44:45], v[174:175], s[34:35], v[44:45] op_sel_hi:[1,0,1]
	v_sub_f32_e32 v179, v179, v196
	v_sub_f32_e32 v178, v178, v196
	v_sub_f32_e32 v181, v181, v196
	v_sub_f32_e32 v180, v180, v196
	v_pk_mul_f32 v[180:181], v[196:197], v[180:181] op_sel:[1,0]
	v_pk_mul_f32 v[178:179], v[196:197], v[178:179] op_sel:[1,0]
	v_pk_fma_f32 v[178:179], v[200:201], v[178:179], v[204:205]
	v_pk_fma_f32 v[180:181], v[202:203], v[180:181], v[206:207]
	v_pk_fma_f32 v[42:43], v[180:181], s[34:35], v[42:43] op_sel_hi:[1,0,1]
	v_pk_fma_f32 v[40:41], v[178:179], s[34:35], v[40:41] op_sel_hi:[1,0,1]
	v_sub_f32_e32 v183, v183, v198
	v_sub_f32_e32 v182, v182, v198
	v_sub_f32_e32 v185, v185, v198
	v_sub_f32_e32 v184, v184, v198
	v_pk_mul_f32 v[184:185], v[198:199], v[184:185] op_sel:[1,0]
	v_pk_mul_f32 v[182:183], v[198:199], v[182:183] op_sel:[1,0]
	v_pk_fma_f32 v[182:183], v[200:201], v[182:183], v[204:205]
	v_pk_fma_f32 v[184:185], v[202:203], v[184:185], v[206:207]
	v_pk_fma_f32 v[38:39], v[184:185], s[34:35], v[38:39] op_sel_hi:[1,0,1]
	v_pk_fma_f32 v[36:37], v[182:183], s[34:35], v[36:37] op_sel_hi:[1,0,1]
	v_add_u32_e32 v225, 0x100000, v224
	global_load_dwordx4 v[158:161], v225, s[14:15] offset:576
	v_add_u32_e32 v226, 0x120000, v224
	global_load_dwordx4 v[174:177], v226, s[14:15] offset:576
	v_add_u32_e32 v225, 0x140000, v224
	global_load_dwordx4 v[178:181], v225, s[14:15] offset:576
	v_add_u32_e32 v226, 0x160000, v224
	global_load_dwordx4 v[182:185], v226, s[14:15] offset:576
	v_add_u32_e32 v225, 0x100000, v224
	global_store_dwordx4 v225, v[48:51], s[14:15] offset:512
	v_add_u32_e32 v226, 0x120000, v224
	global_store_dwordx4 v226, v[44:47], s[14:15] offset:512
	v_add_u32_e32 v225, 0x140000, v224
	global_store_dwordx4 v225, v[40:43], s[14:15] offset:512
	v_add_u32_e32 v226, 0x160000, v224
	global_store_dwordx4 v226, v[36:39], s[14:15] offset:512
	s_waitcnt vmcnt(12)
; #define PG8_BAR __builtin_amdgcn_s_barrier()
; template <class Epi, class Sched>
; __device__ __forceinline__ void gemm_phase(LAS unsigned char* lds, const Gemm g, const Sched& S, const Epi& E, const int tid) {
;     ...
;         if (!has_next) break;
; #pragma unroll
;         for (int a = 0; a < 2; ++a)
; #pragma unroll
;             for (int b = 0; b < 2; ++b)
; #pragma unroll
;                 for (int m = 0; m < 4; ++m)
; #pragma unroll
;                     for (int n = 0; n < 2; ++n) acc[a][b][m][n] = (f32x4){0.f, 0.f, 0.f, 0.f};
;         cur = nxt; cA = nA; cB = nB; ++ui;
;         if (wr == 1) PG8_BAR;
;     __device__ __forceinline__ void operator()(const f32x4 (&acc)[2][2][4][2], const Unit& u, int wr, int wc, int fr, int fq) const {
;     ...
;         for (int bj = 0; bj < 2; ++bj)
; #pragma unroll
;             for (int n = 0; n < 2; ++n) {
;                 const int col = col0 + bj * HALF + n * 16;
;                 f32x4 gg = {1.f, 1.f, 1.f, 1.f}, bb = {0.f, 0.f, 0.f, 0.f};
;                 if (NORM) { gg = *(const f32x4*)(gam + col); bb = *(const f32x4*)(bet + col); }
; #pragma unroll
;                 for (int ai = 0; ai < 2; ++ai) {
;                     f32x4 xv[4]; f32x2 st[4];
; #pragma unroll
;                     for (int m = 0; m < 4; ++m) { xv[m] = *(const f32x4*)(X + (size_t)(row0 + ai * HALF + m * 16) * D + col);
;                         if (NORM) st[m] = *(const f32x2*)(stats + 2 * (row0 + ai * HALF + m * 16)); }
; #pragma unroll
;                     for (int m = 0; m < 4; ++m) {
;                         f32x4 x = xv[m];
;                         if (NORM) x = (x - st[m].x) * st[m].y * gg + bb;
;                         if (!dry) *(f32x4*)(X + (size_t)(row0 + ai * HALF + m * 16) * D + col) = x * ALPHA + acc[ai][bj][m][n];
;                     }
;                 }
	v_sub_f32_e32 v143, v143, v162
	v_sub_f32_e32 v142, v142, v162
	v_sub_f32_e32 v145, v145, v162
	v_sub_f32_e32 v144, v144, v162
	v_pk_mul_f32 v[144:145], v[162:163], v[144:145] op_sel:[1,0]
	v_pk_mul_f32 v[142:143], v[162:163], v[142:143] op_sel:[1,0]
	v_pk_fma_f32 v[142:143], v[210:211], v[142:143], v[220:221]
	v_pk_fma_f32 v[144:145], v[212:213], v[144:145], v[222:223]
	v_pk_fma_f32 v[34:35], v[144:145], s[34:35], v[34:35] op_sel_hi:[1,0,1]
	v_pk_fma_f32 v[32:33], v[142:143], s[34:35], v[32:33] op_sel_hi:[1,0,1]
	v_sub_f32_e32 v147, v147, v186
	v_sub_f32_e32 v146, v146, v186
	v_sub_f32_e32 v149, v149, v186
	v_sub_f32_e32 v148, v148, v186
	v_pk_mul_f32 v[148:149], v[186:187], v[148:149] op_sel:[1,0]
	v_pk_mul_f32 v[146:147], v[186:187], v[146:147] op_sel:[1,0]
	v_pk_fma_f32 v[146:147], v[210:211], v[146:147], v[220:221]
	v_pk_fma_f32 v[148:149], v[212:213], v[148:149], v[222:223]
	v_pk_fma_f32 v[30:31], v[148:149], s[34:35], v[30:31] op_sel_hi:[1,0,1]
	v_pk_fma_f32 v[28:29], v[146:147], s[34:35], v[28:29] op_sel_hi:[1,0,1]
	v_sub_f32_e32 v151, v151, v188
	v_sub_f32_e32 v150, v150, v188
	v_sub_f32_e32 v153, v153, v188
	v_sub_f32_e32 v152, v152, v188
	v_pk_mul_f32 v[152:153], v[188:189], v[152:153] op_sel:[1,0]
	v_pk_mul_f32 v[150:151], v[188:189], v[150:151] op_sel:[1,0]
	v_pk_fma_f32 v[150:151], v[210:211], v[150:151], v[220:221]
	v_pk_fma_f32 v[152:153], v[212:213], v[152:153], v[222:223]
	v_pk_fma_f32 v[26:27], v[152:153], s[34:35], v[26:27] op_sel_hi:[1,0,1]
	v_pk_fma_f32 v[24:25], v[150:151], s[34:35], v[24:25] op_sel_hi:[1,0,1]
	v_sub_f32_e32 v155, v155, v190
	v_sub_f32_e32 v154, v154, v190
	v_sub_f32_e32 v157, v157, v190
	v_sub_f32_e32 v156, v156, v190
	v_pk_mul_f32 v[156:157], v[190:191], v[156:157] op_sel:[1,0]
	v_pk_mul_f32 v[154:155], v[190:191], v[154:155] op_sel:[1,0]
	v_pk_fma_f32 v[154:155], v[210:211], v[154:155], v[220:221]
	v_pk_fma_f32 v[156:157], v[212:213], v[156:157], v[222:223]
	v_pk_fma_f32 v[22:23], v[156:157], s[34:35], v[22:23] op_sel_hi:[1,0,1]
	v_pk_fma_f32 v[20:21], v[154:155], s[34:35], v[20:21] op_sel_hi:[1,0,1]
	global_store_dwordx4 v224, v[32:35], s[14:15] offset:576
	v_add_u32_e32 v226, 0x20000, v224
	global_store_dwordx4 v226, v[28:31], s[14:15] offset:576
	v_add_u32_e32 v225, 0x40000, v224
	global_store_dwordx4 v225, v[24:27], s[14:15] offset:576
	v_add_u32_e32 v226, 0x60000, v224
	global_store_dwordx4 v226, v[20:23], s[14:15] offset:576
	s_waitcnt vmcnt(8)
	v_sub_f32_e32 v159, v159, v192
	v_sub_f32_e32 v158, v158, v192
	v_sub_f32_e32 v161, v161, v192
	v_sub_f32_e32 v160, v160, v192
	v_pk_mul_f32 v[160:161], v[192:193], v[160:161] op_sel:[1,0]
	v_pk_mul_f32 v[158:159], v[192:193], v[158:159] op_sel:[1,0]
	v_pk_fma_f32 v[158:159], v[210:211], v[158:159], v[220:221]
	v_pk_fma_f32 v[160:161], v[212:213], v[160:161], v[222:223]
	v_pk_fma_f32 v[18:19], v[160:161], s[34:35], v[18:19] op_sel_hi:[1,0,1]
	v_pk_fma_f32 v[16:17], v[158:159], s[34:35], v[16:17] op_sel_hi:[1,0,1]
	v_sub_f32_e32 v175, v175, v194
	v_sub_f32_e32 v174, v174, v194
	v_sub_f32_e32 v177, v177, v194
	v_sub_f32_e32 v176, v176, v194
	v_pk_mul_f32 v[176:177], v[194:195], v[176:177] op_sel:[1,0]
	v_pk_mul_f32 v[174:175], v[194:195], v[174:175] op_sel:[1,0]
	v_pk_fma_f32 v[174:175], v[210:211], v[174:175], v[220:221]
	v_pk_fma_f32 v[176:177], v[212:213], v[176:177], v[222:223]
	v_pk_fma_f32 v[14:15], v[176:177], s[34:35], v[14:15] op_sel_hi:[1,0,1]
	v_pk_fma_f32 v[12:13], v[174:175], s[34:35], v[12:13] op_sel_hi:[1,0,1]
	v_sub_f32_e32 v179, v179, v196
	v_sub_f32_e32 v178, v178, v196
	v_sub_f32_e32 v181, v181, v196
	v_sub_f32_e32 v180, v180, v196
	v_pk_mul_f32 v[180:181], v[196:197], v[180:181] op_sel:[1,0]
	v_pk_mul_f32 v[178:179], v[196:197], v[178:179] op_sel:[1,0]
	v_pk_fma_f32 v[178:179], v[210:211], v[178:179], v[220:221]
	v_pk_fma_f32 v[180:181], v[212:213], v[180:181], v[222:223]
	v_pk_fma_f32 v[10:11], v[180:181], s[34:35], v[10:11] op_sel_hi:[1,0,1]
	v_pk_fma_f32 v[8:9], v[178:179], s[34:35], v[8:9] op_sel_hi:[1,0,1]
	v_sub_f32_e32 v183, v183, v198
	v_sub_f32_e32 v182, v182, v198
	v_sub_f32_e32 v185, v185, v198
	v_sub_f32_e32 v184, v184, v198
	v_pk_mul_f32 v[184:185], v[198:199], v[184:185] op_sel:[1,0]
	v_pk_mul_f32 v[182:183], v[198:199], v[182:183] op_sel:[1,0]
	v_pk_fma_f32 v[182:183], v[210:211], v[182:183], v[220:221]
	v_pk_fma_f32 v[184:185], v[212:213], v[184:185], v[222:223]
	v_pk_fma_f32 v[6:7], v[184:185], s[34:35], v[6:7] op_sel_hi:[1,0,1]
	v_pk_fma_f32 v[4:5], v[182:183], s[34:35], v[4:5] op_sel_hi:[1,0,1]
	v_add_u32_e32 v225, 0x100000, v224
	global_store_dwordx4 v225, v[16:19], s[14:15] offset:576
	v_add_u32_e32 v226, 0x120000, v224
	global_store_dwordx4 v226, v[12:15], s[14:15] offset:576
	v_add_u32_e32 v225, 0x140000, v224
	global_store_dwordx4 v225, v[8:11], s[14:15] offset:576
	v_add_u32_e32 v226, 0x160000, v224
	global_store_dwordx4 v226, v[4:7], s[14:15] offset:576
	s_and_b64 vcc, exec, s[6:7]
	s_mov_b64 s[6:7], -1
	s_cbranch_vccnz .LBB0_241
	s_andn2_b64 vcc, exec, s[30:31]
	s_cbranch_vccnz .LBB0_240
	s_barrier
	s_branch .LBB0_240

; #define PG8_STAGE(bufoff, gbase, voff) do { _Pragma("unroll") for (int _i = 0; _i < 2; ++_i) \
;         __builtin_amdgcn_global_load_lds((const unsigned*)((const char*)(gbase) + (voff)[_i]), (LAS unsigned*)(lds + (bufoff) + ldsw + _i * 8192), 16, 0, 0); } while (0)
; #define PG8_LDA(dst, b, h) do { _Pragma("unroll") for (int m = 0; m < 4; ++m) _Pragma("unroll") for (int k = 0; k < 2; ++k) dst[m][k] = *(const LAS bf16x8*)(lds + PG8_SA(b, h) + aoff + m * 2048 + k * 1024); } while (0)
; #define PG8_LDB(dst, b, h) do { _Pragma("unroll") for (int n = 0; n < 2; ++n) _Pragma("unroll") for (int k = 0; k < 2; ++k) dst[n][k] = *(const LAS bf16x8*)(lds + PG8_SB(b, h) + boff + n * 2048 + k * 1024); } while (0)
; #define PG8_WAIT_V(n) asm volatile("s_waitcnt vmcnt(" #n ")" ::: "memory")
; #define PG8_BAR __builtin_amdgcn_s_barrier()
; template <class Epi, class Sched>
; __device__ __forceinline__ void gemm_phase(LAS unsigned char* lds, const Gemm g, const Sched& S, const Epi& E, const int tid) {
;     ...
;         for (int t = 0; t < nt; t += 2) {
;             const bool last = (t == nt - 2);
;             const char* a1 = cA + (size_t)(t + 1) * kstep;
;             const char* a2 = last ? nA : cA + (size_t)(t + 2) * kstep; const char* b2 = last ? nB : cB + (size_t)(t + 2) * kstep;
;             const char* a3 = a2 + kstep; const char* b3 = b2 + kstep;
;             PG8_LDB(B0, 0, 0); PG8_LDB(B1, 0, 1); PG8_SCHED; PG8_LDA(At, 0, 0); PG8_STAGE(PG8_SA(1, 1), a1 + hstepA, voffA);
;             PG8_WAIT_V(8); PG8_WAIT_L(0); PG8_BAR; PG8_MMA(0, 0, At, B0); PG8_MMA(0, 1, At, B1); PG8_BAR; PG8_SCHED;
;             PG8_LDA(At, 0, 1); PG8_STAGE(PG8_SB(0, 0), b2, voffB); PG8_STAGE(PG8_SB(0, 1), b2 + hstepB, voffB); PG8_STAGE(PG8_SA(0, 0), a2, voffA);
;             PG8_WAIT_V(8); PG8_WAIT_L(0); PG8_BAR; PG8_MMA(1, 0, At, B0); PG8_MMA(1, 1, At, B1); PG8_BAR; PG8_SCHED;
;             PG8_LDB(B0, 1, 0); PG8_LDB(B1, 1, 1); PG8_SCHED; PG8_LDA(At, 1, 0); PG8_STAGE(PG8_SA(0, 1), a2 + hstepA, voffA);
;             PG8_WAIT_V(8); PG8_WAIT_L(0); PG8_BAR; PG8_MMA(0, 0, At, B0); PG8_MMA(0, 1, At, B1); PG8_BAR; PG8_SCHED;
;             PG8_LDA(At, 1, 1); PG8_STAGE(PG8_SB(1, 0), b3, voffB); PG8_STAGE(PG8_SB(1, 1), b3 + hstepB, voffB); PG8_STAGE(PG8_SA(1, 0), a3, voffA);
;             PG8_WAIT_V(8); PG8_WAIT_L(0); PG8_BAR; PG8_MMA(1, 0, At, B0); PG8_MMA(1, 1, At, B1); PG8_BAR; PG8_SCHED;
.LBB0_279:
	s_add_u32 s8, s44, 0x100
	s_addc_u32 s9, s45, 0
	s_add_i32 s12, 0, 0x10000
	s_cmp_eq_u32 s94, 28
	s_cselect_b32 s55, s39, s9
	s_cselect_b32 s54, s38, s8
	s_cselect_b32 s47, s16, s93
	s_cselect_b32 s46, s17, s31
	s_add_i32 s95, 0, 0x14000
	v_add_u32_e32 v158, s12, v155
	v_add_u32_e32 v162, s95, v155
	ds_read_b128 v[142:145], v158
	ds_read_b128 v[146:149], v158 offset:1024
	ds_read_b128 v[150:153], v158 offset:2048
	ds_read_b128 v[158:161], v158 offset:3072
	ds_read_b128 v[174:177], v162
	ds_read_b128 v[178:181], v162 offset:1024
	ds_read_b128 v[182:185], v162 offset:2048
	ds_read_b128 v[186:189], v162 offset:3072
	v_lshl_add_u64 v[162:163], s[44:45], 0, v[138:139]
	s_add_i32 m0, s79, 0xc000
	ds_read_b128 v[190:193], v157
	ds_read_b128 v[194:197], v157 offset:1024
	ds_read_b128 v[198:201], v157 offset:2048
	ds_read_b128 v[202:205], v157 offset:3072
	ds_read_b128 v[210:213], v157 offset:4096
	ds_read_b128 v[220:223], v157 offset:5120
	ds_read_b128 v[234:237], v157 offset:6144
	ds_read_b128 v[238:241], v157 offset:7168
	global_load_lds_dwordx4 v[162:163], off
	v_lshl_add_u64 v[162:163], s[44:45], 0, v[140:141]
	s_add_i32 m0, s79, 0xe000
	s_nop 0
	global_load_lds_dwordx4 v[162:163], off
	s_waitcnt vmcnt(8)
	s_waitcnt lgkmcnt(0)
	s_barrier
	s_waitcnt lgkmcnt(0)
	v_mfma_f32_16x16x32_bf16 v[128:131], v[142:145], v[190:193], v[128:131]
	v_mfma_f32_16x16x32_bf16 v[96:99], v[150:153], v[190:193], v[96:99]
	v_mfma_f32_16x16x32_bf16 v[124:127], v[142:145], v[198:201], v[124:127]
	v_mfma_f32_16x16x32_bf16 v[92:95], v[150:153], v[198:201], v[92:95]
	v_mfma_f32_16x16x32_bf16 v[120:123], v[142:145], v[210:213], v[120:123]
	v_mfma_f32_16x16x32_bf16 v[88:91], v[150:153], v[210:213], v[88:91]
	v_mfma_f32_16x16x32_bf16 v[116:119], v[142:145], v[234:237], v[116:119]
	v_mfma_f32_16x16x32_bf16 v[84:87], v[150:153], v[234:237], v[84:87]
	v_mfma_f32_16x16x32_bf16 v[128:131], v[146:149], v[194:197], v[128:131]
	v_mfma_f32_16x16x32_bf16 v[96:99], v[158:161], v[194:197], v[96:99]
	v_mfma_f32_16x16x32_bf16 v[124:127], v[146:149], v[202:205], v[124:127]
	v_mfma_f32_16x16x32_bf16 v[92:95], v[158:161], v[202:205], v[92:95]
	v_mfma_f32_16x16x32_bf16 v[120:123], v[146:149], v[220:223], v[120:123]
	v_mfma_f32_16x16x32_bf16 v[88:91], v[158:161], v[220:223], v[88:91]
	v_mfma_f32_16x16x32_bf16 v[116:119], v[146:149], v[238:241], v[116:119]
	v_mfma_f32_16x16x32_bf16 v[84:87], v[158:161], v[238:241], v[84:87]
	v_mfma_f32_16x16x32_bf16 v[64:67], v[174:177], v[190:193], v[64:67]
	v_mfma_f32_16x16x32_bf16 v[32:35], v[182:185], v[190:193], v[32:35]
	v_mfma_f32_16x16x32_bf16 v[60:63], v[174:177], v[198:201], v[60:63]
	v_mfma_f32_16x16x32_bf16 v[28:31], v[182:185], v[198:201], v[28:31]
	v_mfma_f32_16x16x32_bf16 v[56:59], v[174:177], v[210:213], v[56:59]
	v_mfma_f32_16x16x32_bf16 v[24:27], v[182:185], v[210:213], v[24:27]
	v_mfma_f32_16x16x32_bf16 v[52:55], v[174:177], v[234:237], v[52:55]
	v_mfma_f32_16x16x32_bf16 v[20:23], v[182:185], v[234:237], v[20:23]
	v_mfma_f32_16x16x32_bf16 v[64:67], v[178:181], v[194:197], v[64:67]
	v_mfma_f32_16x16x32_bf16 v[32:35], v[186:189], v[194:197], v[32:35]
	v_mfma_f32_16x16x32_bf16 v[60:63], v[178:181], v[202:205], v[60:63]
	v_mfma_f32_16x16x32_bf16 v[28:31], v[186:189], v[202:205], v[28:31]
	v_mfma_f32_16x16x32_bf16 v[56:59], v[178:181], v[220:223], v[56:59]
	v_mfma_f32_16x16x32_bf16 v[24:27], v[186:189], v[220:223], v[24:27]
	v_mfma_f32_16x16x32_bf16 v[52:55], v[178:181], v[238:241], v[52:55]
	v_mfma_f32_16x16x32_bf16 v[20:23], v[186:189], v[238:241], v[20:23]
	s_barrier
	s_add_i32 s12, s12, s59
	v_lshl_add_u64 v[162:163], s[46:47], 0, v[164:165]
	s_mov_b32 m0, s12
	ds_read_b128 v[190:193], v157 offset:16384
	ds_read_b128 v[194:197], v157 offset:17408
	ds_read_b128 v[198:201], v157 offset:18432
	ds_read_b128 v[202:205], v157 offset:19456
	ds_read_b128 v[210:213], v157 offset:20480
	ds_read_b128 v[220:223], v157 offset:21504
	ds_read_b128 v[234:237], v157 offset:22528
	ds_read_b128 v[238:241], v157 offset:23552
	global_load_lds_dwordx4 v[162:163], off
	s_add_i32 m0, s12, 0x2000
	s_add_u32 s12, s46, 0x80000
	v_lshl_add_u64 v[206:207], s[46:47], 0, v[136:137]
	s_addc_u32 s13, s47, 0
	s_add_i32 s44, s95, s59
	global_load_lds_dwordx4 v[206:207], off
	v_lshl_add_u64 v[224:225], s[12:13], 0, v[164:165]
	s_mov_b32 m0, s44
	v_lshl_add_u64 v[226:227], s[54:55], 0, v[134:135]
	global_load_lds_dwordx4 v[224:225], off
	v_lshl_add_u64 v[224:225], s[12:13], 0, v[136:137]
	s_add_i32 m0, s44, 0x2000
	s_nop 0
	global_load_lds_dwordx4 v[224:225], off
	v_lshl_add_u64 v[224:225], s[54:55], 0, v[132:133]
	s_mov_b32 m0, s79
	s_nop 0
	global_load_lds_dwordx4 v[224:225], off
	s_mov_b32 m0, s84
	s_nop 0
	global_load_lds_dwordx4 v[226:227], off
	s_waitcnt vmcnt(8)
	s_waitcnt lgkmcnt(0)
	s_barrier
; #define PG8_STAGE(bufoff, gbase, voff) do { _Pragma("unroll") for (int _i = 0; _i < 2; ++_i) \
;         __builtin_amdgcn_global_load_lds((const unsigned*)((const char*)(gbase) + (voff)[_i]), (LAS unsigned*)(lds + (bufoff) + ldsw + _i * 8192), 16, 0, 0); } while (0)
; #define PG8_LDA(dst, b, h) do { _Pragma("unroll") for (int m = 0; m < 4; ++m) _Pragma("unroll") for (int k = 0; k < 2; ++k) dst[m][k] = *(const LAS bf16x8*)(lds + PG8_SA(b, h) + aoff + m * 2048 + k * 1024); } while (0)
; #define PG8_LDB(dst, b, h) do { _Pragma("unroll") for (int n = 0; n < 2; ++n) _Pragma("unroll") for (int k = 0; k < 2; ++k) dst[n][k] = *(const LAS bf16x8*)(lds + PG8_SB(b, h) + boff + n * 2048 + k * 1024); } while (0)
; #define PG8_MMA(ai, bj, At, Bt) do { __builtin_amdgcn_s_setprio(1); _Pragma("unroll") for (int m = 0; m < 4; ++m) _Pragma("unroll") for (int n = 0; n < 2; ++n) _Pragma("unroll") for (int k = 0; k < 2; ++k) \
;         acc[ai][bj][m][n] = __builtin_amdgcn_mfma_f32_16x16x32_bf16(Bt[n][k], At[m][k], acc[ai][bj][m][n], 0, 0, 0); __builtin_amdgcn_s_setprio(0); } while (0)
; #define PG8_WAIT_V(n) asm volatile("s_waitcnt vmcnt(" #n ")" ::: "memory")
; template <class Epi, class Sched>
; __device__ __forceinline__ void gemm_phase(LAS unsigned char* lds, const Gemm g, const Sched& S, const Epi& E, const int tid) {
;     ...
;             PG8_LDB(B0, 0, 0); PG8_LDB(B1, 0, 1); PG8_SCHED; PG8_LDA(At, 0, 0); PG8_STAGE(PG8_SA(1, 1), a1 + hstepA, voffA);
;             PG8_WAIT_V(8); PG8_WAIT_L(0); PG8_BAR; PG8_MMA(0, 0, At, B0); PG8_MMA(0, 1, At, B1); PG8_BAR; PG8_SCHED;
;             PG8_LDA(At, 0, 1); PG8_STAGE(PG8_SB(0, 0), b2, voffB); PG8_STAGE(PG8_SB(0, 1), b2 + hstepB, voffB); PG8_STAGE(PG8_SA(0, 0), a2, voffA);
;             PG8_WAIT_V(8); PG8_WAIT_L(0); PG8_BAR; PG8_MMA(1, 0, At, B0); PG8_MMA(1, 1, At, B1); PG8_BAR; PG8_SCHED;
;             PG8_LDB(B0, 1, 0); PG8_LDB(B1, 1, 1); PG8_SCHED; PG8_LDA(At, 1, 0); PG8_STAGE(PG8_SA(0, 1), a2 + hstepA, voffA);
;             PG8_WAIT_V(8); PG8_WAIT_L(0); PG8_BAR; PG8_MMA(0, 0, At, B0); PG8_MMA(0, 1, At, B1); PG8_BAR; PG8_SCHED;
;             PG8_LDA(At, 1, 1); PG8_STAGE(PG8_SB(1, 0), b3, voffB); PG8_STAGE(PG8_SB(1, 1), b3 + hstepB, voffB); PG8_STAGE(PG8_SA(1, 0), a3, voffA);
;             PG8_WAIT_V(8); PG8_WAIT_L(0); PG8_BAR; PG8_MMA(1, 0, At, B0); PG8_MMA(1, 1, At, B1); PG8_BAR; PG8_SCHED;
	s_waitcnt lgkmcnt(0)
	v_mfma_f32_16x16x32_bf16 v[112:115], v[142:145], v[190:193], v[112:115]
	v_mfma_f32_16x16x32_bf16 v[80:83], v[150:153], v[190:193], v[80:83]
	v_mfma_f32_16x16x32_bf16 v[108:111], v[142:145], v[198:201], v[108:111]
	v_mfma_f32_16x16x32_bf16 v[76:79], v[150:153], v[198:201], v[76:79]
	v_mfma_f32_16x16x32_bf16 v[104:107], v[142:145], v[210:213], v[104:107]
	v_mfma_f32_16x16x32_bf16 v[72:75], v[150:153], v[210:213], v[72:75]
	v_mfma_f32_16x16x32_bf16 v[100:103], v[142:145], v[234:237], v[100:103]
	v_mfma_f32_16x16x32_bf16 v[68:71], v[150:153], v[234:237], v[68:71]
	v_mfma_f32_16x16x32_bf16 v[112:115], v[146:149], v[194:197], v[112:115]
	v_mfma_f32_16x16x32_bf16 v[80:83], v[158:161], v[194:197], v[80:83]
	v_mfma_f32_16x16x32_bf16 v[108:111], v[146:149], v[202:205], v[108:111]
	v_mfma_f32_16x16x32_bf16 v[76:79], v[158:161], v[202:205], v[76:79]
	v_mfma_f32_16x16x32_bf16 v[104:107], v[146:149], v[220:223], v[104:107]
	v_mfma_f32_16x16x32_bf16 v[72:75], v[158:161], v[220:223], v[72:75]
	v_mfma_f32_16x16x32_bf16 v[100:103], v[146:149], v[238:241], v[100:103]
	v_mfma_f32_16x16x32_bf16 v[68:71], v[158:161], v[238:241], v[68:71]
	v_mfma_f32_16x16x32_bf16 v[48:51], v[174:177], v[190:193], v[48:51]
	v_mfma_f32_16x16x32_bf16 v[16:19], v[182:185], v[190:193], v[16:19]
	v_mfma_f32_16x16x32_bf16 v[44:47], v[174:177], v[198:201], v[44:47]
	v_mfma_f32_16x16x32_bf16 v[12:15], v[182:185], v[198:201], v[12:15]
	v_mfma_f32_16x16x32_bf16 v[40:43], v[174:177], v[210:213], v[40:43]
	v_mfma_f32_16x16x32_bf16 v[8:11], v[182:185], v[210:213], v[8:11]
	v_mfma_f32_16x16x32_bf16 v[36:39], v[174:177], v[234:237], v[36:39]
	v_mfma_f32_16x16x32_bf16 v[4:7], v[182:185], v[234:237], v[4:7]
	v_mfma_f32_16x16x32_bf16 v[48:51], v[178:181], v[194:197], v[48:51]
	v_mfma_f32_16x16x32_bf16 v[16:19], v[186:189], v[194:197], v[16:19]
	v_mfma_f32_16x16x32_bf16 v[44:47], v[178:181], v[202:205], v[44:47]
	v_mfma_f32_16x16x32_bf16 v[12:15], v[186:189], v[202:205], v[12:15]
	v_mfma_f32_16x16x32_bf16 v[40:43], v[178:181], v[220:223], v[40:43]
	v_mfma_f32_16x16x32_bf16 v[8:11], v[186:189], v[220:223], v[8:11]
	v_mfma_f32_16x16x32_bf16 v[36:39], v[178:181], v[238:241], v[36:39]
	v_mfma_f32_16x16x32_bf16 v[4:7], v[186:189], v[238:241], v[4:7]
	s_barrier
	s_add_i32 s44, 0, 0x18000
	s_add_i32 s45, 0, 0x1c000
	v_add_u32_e32 v158, s44, v155
	v_add_u32_e32 v171, s45, v155
	ds_read_b128 v[142:145], v158
	ds_read_b128 v[146:149], v158 offset:1024
	ds_read_b128 v[150:153], v158 offset:2048
	ds_read_b128 v[158:161], v158 offset:3072
	ds_read_b128 v[174:177], v171
	ds_read_b128 v[178:181], v171 offset:1024
	ds_read_b128 v[182:185], v171 offset:2048
	ds_read_b128 v[186:189], v171 offset:3072
	s_add_u32 s12, s54, 0x242000
	s_addc_u32 s13, s55, 0
	s_mov_b32 m0, s85
	v_lshl_add_u64 v[242:243], s[12:13], 0, v[132:133]
	ds_read_b128 v[190:193], v157 offset:32768
	ds_read_b128 v[194:197], v157 offset:33792
	ds_read_b128 v[198:201], v157 offset:34816
	ds_read_b128 v[202:205], v157 offset:35840
	ds_read_b128 v[210:213], v157 offset:36864
	ds_read_b128 v[220:223], v157 offset:37888
	ds_read_b128 v[234:237], v157 offset:38912
	ds_read_b128 v[238:241], v157 offset:39936
	global_load_lds_dwordx4 v[242:243], off
	v_lshl_add_u64 v[242:243], s[12:13], 0, v[134:135]
	s_mov_b32 m0, s86
	s_nop 0
	global_load_lds_dwordx4 v[242:243], off
	s_waitcnt vmcnt(8)
	s_waitcnt lgkmcnt(0)
	s_barrier
	s_waitcnt lgkmcnt(0)
	v_mfma_f32_16x16x32_bf16 v[128:131], v[142:145], v[190:193], v[128:131]
	v_mfma_f32_16x16x32_bf16 v[96:99], v[150:153], v[190:193], v[96:99]
	v_mfma_f32_16x16x32_bf16 v[124:127], v[142:145], v[198:201], v[124:127]
	v_mfma_f32_16x16x32_bf16 v[92:95], v[150:153], v[198:201], v[92:95]
	v_mfma_f32_16x16x32_bf16 v[120:123], v[142:145], v[210:213], v[120:123]
	v_mfma_f32_16x16x32_bf16 v[88:91], v[150:153], v[210:213], v[88:91]
	v_mfma_f32_16x16x32_bf16 v[116:119], v[142:145], v[234:237], v[116:119]
	v_mfma_f32_16x16x32_bf16 v[84:87], v[150:153], v[234:237], v[84:87]
	v_mfma_f32_16x16x32_bf16 v[128:131], v[146:149], v[194:197], v[128:131]
	v_mfma_f32_16x16x32_bf16 v[96:99], v[158:161], v[194:197], v[96:99]
	v_mfma_f32_16x16x32_bf16 v[124:127], v[146:149], v[202:205], v[124:127]
	v_mfma_f32_16x16x32_bf16 v[92:95], v[158:161], v[202:205], v[92:95]
	v_mfma_f32_16x16x32_bf16 v[120:123], v[146:149], v[220:223], v[120:123]
	v_mfma_f32_16x16x32_bf16 v[88:91], v[158:161], v[220:223], v[88:91]
	v_mfma_f32_16x16x32_bf16 v[116:119], v[146:149], v[238:241], v[116:119]
	v_mfma_f32_16x16x32_bf16 v[84:87], v[158:161], v[238:241], v[84:87]
	v_mfma_f32_16x16x32_bf16 v[64:67], v[174:177], v[190:193], v[64:67]
	v_mfma_f32_16x16x32_bf16 v[32:35], v[182:185], v[190:193], v[32:35]
	v_mfma_f32_16x16x32_bf16 v[60:63], v[174:177], v[198:201], v[60:63]
	v_mfma_f32_16x16x32_bf16 v[28:31], v[182:185], v[198:201], v[28:31]
	v_mfma_f32_16x16x32_bf16 v[56:59], v[174:177], v[210:213], v[56:59]
	v_mfma_f32_16x16x32_bf16 v[24:27], v[182:185], v[210:213], v[24:27]
	v_mfma_f32_16x16x32_bf16 v[52:55], v[174:177], v[234:237], v[52:55]
	v_mfma_f32_16x16x32_bf16 v[20:23], v[182:185], v[234:237], v[20:23]
	v_mfma_f32_16x16x32_bf16 v[64:67], v[178:181], v[194:197], v[64:67]
	v_mfma_f32_16x16x32_bf16 v[32:35], v[186:189], v[194:197], v[32:35]
	v_mfma_f32_16x16x32_bf16 v[60:63], v[178:181], v[202:205], v[60:63]
	v_mfma_f32_16x16x32_bf16 v[28:31], v[186:189], v[202:205], v[28:31]
	v_mfma_f32_16x16x32_bf16 v[56:59], v[178:181], v[220:223], v[56:59]
	v_mfma_f32_16x16x32_bf16 v[24:27], v[186:189], v[220:223], v[24:27]
	v_mfma_f32_16x16x32_bf16 v[52:55], v[178:181], v[238:241], v[52:55]
	v_mfma_f32_16x16x32_bf16 v[20:23], v[186:189], v[238:241], v[20:23]
	s_barrier
; #define PG8_STAGE(bufoff, gbase, voff) do { _Pragma("unroll") for (int _i = 0; _i < 2; ++_i) \
;         __builtin_amdgcn_global_load_lds((const unsigned*)((const char*)(gbase) + (voff)[_i]), (LAS unsigned*)(lds + (bufoff) + ldsw + _i * 8192), 16, 0, 0); } while (0)
; #define PG8_LDA(dst, b, h) do { _Pragma("unroll") for (int m = 0; m < 4; ++m) _Pragma("unroll") for (int k = 0; k < 2; ++k) dst[m][k] = *(const LAS bf16x8*)(lds + PG8_SA(b, h) + aoff + m * 2048 + k * 1024); } while (0)
; #define PG8_LDB(dst, b, h) do { _Pragma("unroll") for (int n = 0; n < 2; ++n) _Pragma("unroll") for (int k = 0; k < 2; ++k) dst[n][k] = *(const LAS bf16x8*)(lds + PG8_SB(b, h) + boff + n * 2048 + k * 1024); } while (0)
; #define PG8_MMA(ai, bj, At, Bt) do { __builtin_amdgcn_s_setprio(1); _Pragma("unroll") for (int m = 0; m < 4; ++m) _Pragma("unroll") for (int n = 0; n < 2; ++n) _Pragma("unroll") for (int k = 0; k < 2; ++k) \
;         acc[ai][bj][m][n] = __builtin_amdgcn_mfma_f32_16x16x32_bf16(Bt[n][k], At[m][k], acc[ai][bj][m][n], 0, 0, 0); __builtin_amdgcn_s_setprio(0); } while (0)
; #define PG8_WAIT_V(n) asm volatile("s_waitcnt vmcnt(" #n ")" ::: "memory")
; #define PG8_WAIT_L(n) asm volatile("s_waitcnt lgkmcnt(" #n ")" ::: "memory")
; #define PG8_BAR __builtin_amdgcn_s_barrier()
; #define PG8_SCHED __builtin_amdgcn_sched_barrier(0)
; template <class Epi, class Sched>
; __device__ __forceinline__ void gemm_phase(LAS unsigned char* lds, const Gemm g, const Sched& S, const Epi& E, const int tid) {
;     ...
;             PG8_LDB(B0, 1, 0); PG8_LDB(B1, 1, 1); PG8_SCHED; PG8_LDA(At, 1, 0); PG8_STAGE(PG8_SA(0, 1), a2 + hstepA, voffA);
;             PG8_WAIT_V(8); PG8_WAIT_L(0); PG8_BAR; PG8_MMA(0, 0, At, B0); PG8_MMA(0, 1, At, B1); PG8_BAR; PG8_SCHED;
;             PG8_LDA(At, 1, 1); PG8_STAGE(PG8_SB(1, 0), b3, voffB); PG8_STAGE(PG8_SB(1, 1), b3 + hstepB, voffB); PG8_STAGE(PG8_SA(1, 0), a3, voffA);
;             PG8_WAIT_V(8); PG8_WAIT_L(0); PG8_BAR; PG8_MMA(1, 0, At, B0); PG8_MMA(1, 1, At, B1); PG8_BAR; PG8_SCHED;
;         }
;         if (wr == 0) PG8_BAR;
	s_add_i32 s12, s44, s59
	v_lshl_add_u64 v[162:163], v[162:163], 0, s[28:29]
	s_mov_b32 m0, s12
	ds_read_b128 v[190:193], v157 offset:49152
	ds_read_b128 v[194:197], v157 offset:50176
	ds_read_b128 v[198:201], v157 offset:51200
	ds_read_b128 v[202:205], v157 offset:52224
	ds_read_b128 v[210:213], v157 offset:53248
	ds_read_b128 v[220:223], v157 offset:54272
	ds_read_b128 v[234:237], v157 offset:55296
	ds_read_b128 v[238:241], v157 offset:56320
	global_load_lds_dwordx4 v[162:163], off
	s_add_i32 m0, s12, 0x2000
	s_add_u32 s12, s46, 0x80080
	v_lshl_add_u64 v[162:163], v[206:207], 0, s[28:29]
	s_addc_u32 s13, s47, 0
	s_add_i32 s44, s45, s59
	global_load_lds_dwordx4 v[162:163], off
	v_lshl_add_u64 v[162:163], s[12:13], 0, v[164:165]
	s_mov_b32 m0, s44
	s_nop 0
	global_load_lds_dwordx4 v[162:163], off
	v_lshl_add_u64 v[162:163], s[12:13], 0, v[136:137]
	s_add_i32 m0, s44, 0x2000
	s_nop 0
	global_load_lds_dwordx4 v[162:163], off
	v_lshl_add_u64 v[162:163], v[224:225], 0, s[28:29]
	s_mov_b32 m0, s87
	s_nop 0
	global_load_lds_dwordx4 v[162:163], off
	v_lshl_add_u64 v[162:163], v[226:227], 0, s[28:29]
	s_mov_b32 m0, s88
	s_nop 0
	global_load_lds_dwordx4 v[162:163], off
	s_waitcnt vmcnt(8)
	s_waitcnt lgkmcnt(0)
	s_barrier
	s_waitcnt lgkmcnt(0)
	v_mfma_f32_16x16x32_bf16 v[112:115], v[142:145], v[190:193], v[112:115]
	v_mfma_f32_16x16x32_bf16 v[80:83], v[150:153], v[190:193], v[80:83]
	v_mfma_f32_16x16x32_bf16 v[108:111], v[142:145], v[198:201], v[108:111]
	v_mfma_f32_16x16x32_bf16 v[76:79], v[150:153], v[198:201], v[76:79]
	v_mfma_f32_16x16x32_bf16 v[104:107], v[142:145], v[210:213], v[104:107]
	v_mfma_f32_16x16x32_bf16 v[72:75], v[150:153], v[210:213], v[72:75]
	v_mfma_f32_16x16x32_bf16 v[100:103], v[142:145], v[234:237], v[100:103]
	v_mfma_f32_16x16x32_bf16 v[68:71], v[150:153], v[234:237], v[68:71]
	v_mfma_f32_16x16x32_bf16 v[112:115], v[146:149], v[194:197], v[112:115]
	v_mfma_f32_16x16x32_bf16 v[80:83], v[158:161], v[194:197], v[80:83]
	v_mfma_f32_16x16x32_bf16 v[108:111], v[146:149], v[202:205], v[108:111]
	v_mfma_f32_16x16x32_bf16 v[76:79], v[158:161], v[202:205], v[76:79]
	v_mfma_f32_16x16x32_bf16 v[104:107], v[146:149], v[220:223], v[104:107]
	v_mfma_f32_16x16x32_bf16 v[72:75], v[158:161], v[220:223], v[72:75]
	v_mfma_f32_16x16x32_bf16 v[100:103], v[146:149], v[238:241], v[100:103]
	v_mfma_f32_16x16x32_bf16 v[68:71], v[158:161], v[238:241], v[68:71]
	v_mfma_f32_16x16x32_bf16 v[48:51], v[174:177], v[190:193], v[48:51]
	v_mfma_f32_16x16x32_bf16 v[16:19], v[182:185], v[190:193], v[16:19]
	v_mfma_f32_16x16x32_bf16 v[44:47], v[174:177], v[198:201], v[44:47]
	v_mfma_f32_16x16x32_bf16 v[12:15], v[182:185], v[198:201], v[12:15]
	v_mfma_f32_16x16x32_bf16 v[40:43], v[174:177], v[210:213], v[40:43]
	v_mfma_f32_16x16x32_bf16 v[8:11], v[182:185], v[210:213], v[8:11]
	v_mfma_f32_16x16x32_bf16 v[36:39], v[174:177], v[234:237], v[36:39]
	v_mfma_f32_16x16x32_bf16 v[4:7], v[182:185], v[234:237], v[4:7]
	v_mfma_f32_16x16x32_bf16 v[48:51], v[178:181], v[194:197], v[48:51]
	v_mfma_f32_16x16x32_bf16 v[16:19], v[186:189], v[194:197], v[16:19]
	v_mfma_f32_16x16x32_bf16 v[44:47], v[178:181], v[202:205], v[44:47]
	v_mfma_f32_16x16x32_bf16 v[12:15], v[186:189], v[202:205], v[12:15]
	v_mfma_f32_16x16x32_bf16 v[40:43], v[178:181], v[220:223], v[40:43]
	v_mfma_f32_16x16x32_bf16 v[8:11], v[186:189], v[220:223], v[8:11]
	v_mfma_f32_16x16x32_bf16 v[36:39], v[178:181], v[238:241], v[36:39]
	v_mfma_f32_16x16x32_bf16 v[4:7], v[186:189], v[238:241], v[4:7]
	s_barrier
	s_add_i32 s94, s94, 2
	s_add_u32 s31, s31, 0x100
	s_addc_u32 s93, s93, 0
	s_cmp_gt_u32 s94, 29
	s_mov_b64 s[44:45], s[8:9]
	s_cbranch_scc0 .LBB0_279
	s_and_b64 vcc, exec, s[20:21]
	s_cbranch_vccz .LBB0_282
	s_barrier

; #define PG8_STAGE(bufoff, gbase, voff) do { _Pragma("unroll") for (int _i = 0; _i < 2; ++_i) \
;         __builtin_amdgcn_global_load_lds((const unsigned*)((const char*)(gbase) + (voff)[_i]), (LAS unsigned*)(lds + (bufoff) + ldsw + _i * 8192), 16, 0, 0); } while (0)
; #define PG8_LDA(dst, b, h) do { _Pragma("unroll") for (int m = 0; m < 4; ++m) _Pragma("unroll") for (int k = 0; k < 2; ++k) dst[m][k] = *(const LAS bf16x8*)(lds + PG8_SA(b, h) + aoff + m * 2048 + k * 1024); } while (0)
; #define PG8_LDB(dst, b, h) do { _Pragma("unroll") for (int n = 0; n < 2; ++n) _Pragma("unroll") for (int k = 0; k < 2; ++k) dst[n][k] = *(const LAS bf16x8*)(lds + PG8_SB(b, h) + boff + n * 2048 + k * 1024); } while (0)
; #define PG8_MMA(ai, bj, At, Bt) do { __builtin_amdgcn_s_setprio(1); _Pragma("unroll") for (int m = 0; m < 4; ++m) _Pragma("unroll") for (int n = 0; n < 2; ++n) _Pragma("unroll") for (int k = 0; k < 2; ++k) \
;         acc[ai][bj][m][n] = __builtin_amdgcn_mfma_f32_16x16x32_bf16(Bt[n][k], At[m][k], acc[ai][bj][m][n], 0, 0, 0); __builtin_amdgcn_s_setprio(0); } while (0)
; #define PG8_WAIT_V(n) asm volatile("s_waitcnt vmcnt(" #n ")" ::: "memory")
; #define PG8_WAIT_L(n) asm volatile("s_waitcnt lgkmcnt(" #n ")" ::: "memory")
; #define PG8_BAR __builtin_amdgcn_s_barrier()
; #define PG8_SCHED __builtin_amdgcn_sched_barrier(0)
; template <class Epi, class Sched>
; __device__ __forceinline__ void gemm_phase(LAS unsigned char* lds, const Gemm g, const Sched& S, const Epi& E, const int tid) {
;     ...
;         for (int t = 0; t < nt; t += 2) {
;             const bool last = (t == nt - 2);
;             const char* a1 = cA + (size_t)(t + 1) * kstep;
;             const char* a2 = last ? nA : cA + (size_t)(t + 2) * kstep; const char* b2 = last ? nB : cB + (size_t)(t + 2) * kstep;
;             const char* a3 = a2 + kstep; const char* b3 = b2 + kstep;
;             PG8_LDB(B0, 0, 0); PG8_LDB(B1, 0, 1); PG8_SCHED; PG8_LDA(At, 0, 0); PG8_STAGE(PG8_SA(1, 1), a1 + hstepA, voffA);
;             PG8_WAIT_V(8); PG8_WAIT_L(0); PG8_BAR; PG8_MMA(0, 0, At, B0); PG8_MMA(0, 1, At, B1); PG8_BAR; PG8_SCHED;
;             PG8_LDA(At, 0, 1); PG8_STAGE(PG8_SB(0, 0), b2, voffB); PG8_STAGE(PG8_SB(0, 1), b2 + hstepB, voffB); PG8_STAGE(PG8_SA(0, 0), a2, voffA);
;             PG8_WAIT_V(8); PG8_WAIT_L(0); PG8_BAR; PG8_MMA(1, 0, At, B0); PG8_MMA(1, 1, At, B1); PG8_BAR; PG8_SCHED;
.LBB0_308:
	s_add_u32 s12, s54, 0xfffc0080
	s_addc_u32 s13, s55, -1
	s_add_i32 vcc_lo, 0, 0x10000
	s_cmp_eq_u32 s97, 12
	s_cselect_b32 s93, s16, s13
	s_cselect_b32 s92, s17, s12
	v_add_u32_e32 v154, vcc_lo, v151
	s_cselect_b32 s91, s31, s96
	s_cselect_b32 s90, s39, s47
	s_add_i32 vcc_hi, 0, 0x14000
	ds_read_b128 v[136:139], v154
	ds_read_b128 v[174:177], v154 offset:1024
	ds_read_b128 v[178:181], v154 offset:2048
	ds_read_b128 v[182:185], v154 offset:3072
	v_add_u32_e32 v154, vcc_hi, v151
	ds_read_b128 v[186:189], v154
	ds_read_b128 v[190:193], v154 offset:1024
	ds_read_b128 v[194:197], v154 offset:2048
	ds_read_b128 v[198:201], v154 offset:3072
	v_lshl_add_u64 v[154:155], s[54:55], 0, v[132:133]
	s_add_i32 m0, s79, 0xc000
	ds_read_b128 v[202:205], v153
	ds_read_b128 v[220:223], v153 offset:1024
	ds_read_b128 v[234:237], v153 offset:2048
	ds_read_b128 v[238:241], v153 offset:3072
	ds_read_b128 v[242:245], v153 offset:4096
	ds_read_b128 v[246:249], v153 offset:5120
	ds_read_b128 v[250:253], v153 offset:6144
	ds_read_b128 v[210:213], v153 offset:7168
	global_load_lds_dwordx4 v[154:155], off
	v_lshl_add_u64 v[154:155], s[54:55], 0, v[134:135]
	s_add_i32 m0, s79, 0xe000
	s_nop 0
	global_load_lds_dwordx4 v[154:155], off
	s_waitcnt vmcnt(8)
	s_waitcnt lgkmcnt(0)
	s_barrier
	s_waitcnt lgkmcnt(0)
	v_mfma_f32_16x16x32_bf16 v[128:131], v[136:139], v[202:205], v[128:131]
	v_mfma_f32_16x16x32_bf16 v[124:127], v[178:181], v[202:205], v[124:127]
	v_mfma_f32_16x16x32_bf16 v[120:123], v[136:139], v[234:237], v[120:123]
	v_mfma_f32_16x16x32_bf16 v[112:115], v[178:181], v[234:237], v[112:115]
	v_mfma_f32_16x16x32_bf16 v[96:99], v[136:139], v[242:245], v[96:99]
	v_mfma_f32_16x16x32_bf16 v[92:95], v[178:181], v[242:245], v[92:95]
	v_mfma_f32_16x16x32_bf16 v[88:91], v[136:139], v[250:253], v[88:91]
	v_mfma_f32_16x16x32_bf16 v[80:83], v[178:181], v[250:253], v[80:83]
	v_mfma_f32_16x16x32_bf16 v[128:131], v[174:177], v[220:223], v[128:131]
	v_mfma_f32_16x16x32_bf16 v[124:127], v[182:185], v[220:223], v[124:127]
	v_mfma_f32_16x16x32_bf16 v[120:123], v[174:177], v[238:241], v[120:123]
	v_mfma_f32_16x16x32_bf16 v[112:115], v[182:185], v[238:241], v[112:115]
	v_mfma_f32_16x16x32_bf16 v[96:99], v[174:177], v[246:249], v[96:99]
	v_mfma_f32_16x16x32_bf16 v[92:95], v[182:185], v[246:249], v[92:95]
	v_mfma_f32_16x16x32_bf16 v[88:91], v[174:177], v[210:213], v[88:91]
	v_mfma_f32_16x16x32_bf16 v[80:83], v[182:185], v[210:213], v[80:83]
	v_mfma_f32_16x16x32_bf16 v[116:119], v[186:189], v[202:205], v[116:119]
	v_mfma_f32_16x16x32_bf16 v[108:111], v[194:197], v[202:205], v[108:111]
	v_mfma_f32_16x16x32_bf16 v[104:107], v[186:189], v[234:237], v[104:107]
	v_mfma_f32_16x16x32_bf16 v[100:103], v[194:197], v[234:237], v[100:103]
	v_mfma_f32_16x16x32_bf16 v[84:87], v[186:189], v[242:245], v[84:87]
	v_mfma_f32_16x16x32_bf16 v[76:79], v[194:197], v[242:245], v[76:79]
	v_mfma_f32_16x16x32_bf16 v[72:75], v[186:189], v[250:253], v[72:75]
	v_mfma_f32_16x16x32_bf16 v[68:71], v[194:197], v[250:253], v[68:71]
	v_mfma_f32_16x16x32_bf16 v[116:119], v[190:193], v[220:223], v[116:119]
	v_mfma_f32_16x16x32_bf16 v[108:111], v[198:201], v[220:223], v[108:111]
	v_mfma_f32_16x16x32_bf16 v[104:107], v[190:193], v[238:241], v[104:107]
	v_mfma_f32_16x16x32_bf16 v[100:103], v[198:201], v[238:241], v[100:103]
	v_mfma_f32_16x16x32_bf16 v[84:87], v[190:193], v[246:249], v[84:87]
	v_mfma_f32_16x16x32_bf16 v[76:79], v[198:201], v[246:249], v[76:79]
	v_mfma_f32_16x16x32_bf16 v[72:75], v[190:193], v[210:213], v[72:75]
	v_mfma_f32_16x16x32_bf16 v[68:71], v[198:201], v[210:213], v[68:71]
	s_barrier
	s_add_i32 s12, vcc_lo, s59
	v_lshl_add_u64 v[154:155], s[90:91], 0, v[164:165]
	s_mov_b32 m0, s12
	ds_read_b128 v[202:205], v153 offset:16384
	ds_read_b128 v[210:213], v153 offset:17408
	ds_read_b128 v[220:223], v153 offset:18432
	ds_read_b128 v[234:237], v153 offset:19456
	ds_read_b128 v[238:241], v153 offset:20480
	ds_read_b128 v[242:245], v153 offset:21504
	ds_read_b128 v[246:249], v153 offset:22528
	ds_read_b128 v[250:253], v153 offset:23552
	global_load_lds_dwordx4 v[154:155], off
	s_add_i32 m0, s12, 0x2000
	s_add_u32 s12, s90, 0x40000
	v_lshl_add_u64 v[162:163], s[90:91], 0, v[160:161]
	s_addc_u32 s13, s91, 0
	s_add_i32 vcc_lo, vcc_hi, s59
	global_load_lds_dwordx4 v[162:163], off
	v_lshl_add_u64 v[206:207], s[12:13], 0, v[164:165]
	s_mov_b32 m0, vcc_lo
	v_lshl_add_u64 v[224:225], s[92:93], 0, v[158:159]
	global_load_lds_dwordx4 v[206:207], off
	v_lshl_add_u64 v[206:207], s[12:13], 0, v[160:161]
	s_add_i32 m0, vcc_lo, 0x2000
	s_nop 0
	global_load_lds_dwordx4 v[206:207], off
	v_lshl_add_u64 v[206:207], s[92:93], 0, v[156:157]
	s_mov_b32 m0, s79
	s_nop 0
	global_load_lds_dwordx4 v[206:207], off
	s_mov_b32 m0, s85
	s_nop 0
	global_load_lds_dwordx4 v[224:225], off
	s_waitcnt vmcnt(8)
	s_waitcnt lgkmcnt(0)
	s_barrier
; #define PG8_STAGE(bufoff, gbase, voff) do { _Pragma("unroll") for (int _i = 0; _i < 2; ++_i) \
;         __builtin_amdgcn_global_load_lds((const unsigned*)((const char*)(gbase) + (voff)[_i]), (LAS unsigned*)(lds + (bufoff) + ldsw + _i * 8192), 16, 0, 0); } while (0)
; #define PG8_LDA(dst, b, h) do { _Pragma("unroll") for (int m = 0; m < 4; ++m) _Pragma("unroll") for (int k = 0; k < 2; ++k) dst[m][k] = *(const LAS bf16x8*)(lds + PG8_SA(b, h) + aoff + m * 2048 + k * 1024); } while (0)
; #define PG8_LDB(dst, b, h) do { _Pragma("unroll") for (int n = 0; n < 2; ++n) _Pragma("unroll") for (int k = 0; k < 2; ++k) dst[n][k] = *(const LAS bf16x8*)(lds + PG8_SB(b, h) + boff + n * 2048 + k * 1024); } while (0)
; #define PG8_MMA(ai, bj, At, Bt) do { __builtin_amdgcn_s_setprio(1); _Pragma("unroll") for (int m = 0; m < 4; ++m) _Pragma("unroll") for (int n = 0; n < 2; ++n) _Pragma("unroll") for (int k = 0; k < 2; ++k) \
;         acc[ai][bj][m][n] = __builtin_amdgcn_mfma_f32_16x16x32_bf16(Bt[n][k], At[m][k], acc[ai][bj][m][n], 0, 0, 0); __builtin_amdgcn_s_setprio(0); } while (0)
; #define PG8_WAIT_V(n) asm volatile("s_waitcnt vmcnt(" #n ")" ::: "memory")
; #define PG8_WAIT_L(n) asm volatile("s_waitcnt lgkmcnt(" #n ")" ::: "memory")
; #define PG8_BAR __builtin_amdgcn_s_barrier()
; #define PG8_SCHED __builtin_amdgcn_sched_barrier(0)
; template <class Epi, class Sched>
; __device__ __forceinline__ void gemm_phase(LAS unsigned char* lds, const Gemm g, const Sched& S, const Epi& E, const int tid) {
;     ...
;             PG8_WAIT_V(8); PG8_WAIT_L(0); PG8_BAR; PG8_MMA(1, 0, At, B0); PG8_MMA(1, 1, At, B1); PG8_BAR; PG8_SCHED;
;             PG8_LDB(B0, 1, 0); PG8_LDB(B1, 1, 1); PG8_SCHED; PG8_LDA(At, 1, 0); PG8_STAGE(PG8_SA(0, 1), a2 + hstepA, voffA);
;             PG8_WAIT_V(8); PG8_WAIT_L(0); PG8_BAR; PG8_MMA(0, 0, At, B0); PG8_MMA(0, 1, At, B1); PG8_BAR; PG8_SCHED;
	s_waitcnt lgkmcnt(0)
	v_mfma_f32_16x16x32_bf16 v[64:67], v[136:139], v[202:205], v[64:67]
	v_mfma_f32_16x16x32_bf16 v[60:63], v[178:181], v[202:205], v[60:63]
	v_mfma_f32_16x16x32_bf16 v[56:59], v[136:139], v[220:223], v[56:59]
	v_mfma_f32_16x16x32_bf16 v[48:51], v[178:181], v[220:223], v[48:51]
	v_mfma_f32_16x16x32_bf16 v[32:35], v[136:139], v[238:241], v[32:35]
	v_mfma_f32_16x16x32_bf16 v[28:31], v[178:181], v[238:241], v[28:31]
	v_mfma_f32_16x16x32_bf16 v[20:23], v[136:139], v[246:249], v[20:23]
	v_mfma_f32_16x16x32_bf16 v[12:15], v[178:181], v[246:249], v[12:15]
	v_mfma_f32_16x16x32_bf16 v[64:67], v[174:177], v[210:213], v[64:67]
	v_mfma_f32_16x16x32_bf16 v[60:63], v[182:185], v[210:213], v[60:63]
	v_mfma_f32_16x16x32_bf16 v[56:59], v[174:177], v[234:237], v[56:59]
	v_mfma_f32_16x16x32_bf16 v[48:51], v[182:185], v[234:237], v[48:51]
	v_mfma_f32_16x16x32_bf16 v[32:35], v[174:177], v[242:245], v[32:35]
	v_mfma_f32_16x16x32_bf16 v[28:31], v[182:185], v[242:245], v[28:31]
	v_mfma_f32_16x16x32_bf16 v[20:23], v[174:177], v[250:253], v[20:23]
	v_mfma_f32_16x16x32_bf16 v[12:15], v[182:185], v[250:253], v[12:15]
	v_mfma_f32_16x16x32_bf16 v[52:55], v[186:189], v[202:205], v[52:55]
	v_mfma_f32_16x16x32_bf16 v[44:47], v[194:197], v[202:205], v[44:47]
	v_mfma_f32_16x16x32_bf16 v[40:43], v[186:189], v[220:223], v[40:43]
	v_mfma_f32_16x16x32_bf16 v[36:39], v[194:197], v[220:223], v[36:39]
	v_mfma_f32_16x16x32_bf16 v[24:27], v[186:189], v[238:241], v[24:27]
	v_mfma_f32_16x16x32_bf16 v[16:19], v[194:197], v[238:241], v[16:19]
	v_mfma_f32_16x16x32_bf16 v[8:11], v[186:189], v[246:249], v[8:11]
	v_mfma_f32_16x16x32_bf16 v[4:7], v[194:197], v[246:249], v[4:7]
	v_mfma_f32_16x16x32_bf16 v[52:55], v[190:193], v[210:213], v[52:55]
	v_mfma_f32_16x16x32_bf16 v[44:47], v[198:201], v[210:213], v[44:47]
	v_mfma_f32_16x16x32_bf16 v[40:43], v[190:193], v[234:237], v[40:43]
	v_mfma_f32_16x16x32_bf16 v[36:39], v[198:201], v[234:237], v[36:39]
	v_mfma_f32_16x16x32_bf16 v[24:27], v[190:193], v[242:245], v[24:27]
	v_mfma_f32_16x16x32_bf16 v[16:19], v[198:201], v[242:245], v[16:19]
	v_mfma_f32_16x16x32_bf16 v[8:11], v[190:193], v[250:253], v[8:11]
	v_mfma_f32_16x16x32_bf16 v[4:7], v[198:201], v[250:253], v[4:7]
	s_barrier
	s_add_i32 vcc_lo, 0, 0x18000
	v_add_u32_e32 v171, vcc_lo, v151
	s_add_i32 vcc_hi, 0, 0x1c000
	ds_read_b128 v[136:139], v171
	ds_read_b128 v[174:177], v171 offset:1024
	ds_read_b128 v[178:181], v171 offset:2048
	ds_read_b128 v[182:185], v171 offset:3072
	v_add_u32_e32 v171, vcc_hi, v151
	ds_read_b128 v[186:189], v171
	ds_read_b128 v[190:193], v171 offset:1024
	ds_read_b128 v[194:197], v171 offset:2048
	ds_read_b128 v[198:201], v171 offset:3072
	s_add_u32 s12, s92, 0x40000
	s_addc_u32 s13, s93, 0
	s_mov_b32 m0, s86
	v_lshl_add_u64 v[226:227], s[12:13], 0, v[156:157]
	ds_read_b128 v[202:205], v153 offset:32768
	ds_read_b128 v[210:213], v153 offset:33792
	ds_read_b128 v[220:223], v153 offset:34816
	ds_read_b128 v[234:237], v153 offset:35840
	ds_read_b128 v[238:241], v153 offset:36864
	ds_read_b128 v[242:245], v153 offset:37888
	ds_read_b128 v[246:249], v153 offset:38912
	ds_read_b128 v[250:253], v153 offset:39936
	global_load_lds_dwordx4 v[226:227], off
	v_lshl_add_u64 v[226:227], s[12:13], 0, v[158:159]
	s_mov_b32 m0, s87
	s_nop 0
	global_load_lds_dwordx4 v[226:227], off
	s_waitcnt vmcnt(8)
	s_waitcnt lgkmcnt(0)
	s_barrier
	s_waitcnt lgkmcnt(0)
	v_mfma_f32_16x16x32_bf16 v[128:131], v[136:139], v[202:205], v[128:131]
	v_mfma_f32_16x16x32_bf16 v[124:127], v[178:181], v[202:205], v[124:127]
	v_mfma_f32_16x16x32_bf16 v[120:123], v[136:139], v[220:223], v[120:123]
	v_mfma_f32_16x16x32_bf16 v[112:115], v[178:181], v[220:223], v[112:115]
	v_mfma_f32_16x16x32_bf16 v[96:99], v[136:139], v[238:241], v[96:99]
	v_mfma_f32_16x16x32_bf16 v[92:95], v[178:181], v[238:241], v[92:95]
	v_mfma_f32_16x16x32_bf16 v[88:91], v[136:139], v[246:249], v[88:91]
	v_mfma_f32_16x16x32_bf16 v[80:83], v[178:181], v[246:249], v[80:83]
	v_mfma_f32_16x16x32_bf16 v[128:131], v[174:177], v[210:213], v[128:131]
	v_mfma_f32_16x16x32_bf16 v[124:127], v[182:185], v[210:213], v[124:127]
	v_mfma_f32_16x16x32_bf16 v[120:123], v[174:177], v[234:237], v[120:123]
	v_mfma_f32_16x16x32_bf16 v[112:115], v[182:185], v[234:237], v[112:115]
	v_mfma_f32_16x16x32_bf16 v[96:99], v[174:177], v[242:245], v[96:99]
	v_mfma_f32_16x16x32_bf16 v[92:95], v[182:185], v[242:245], v[92:95]
	v_mfma_f32_16x16x32_bf16 v[88:91], v[174:177], v[250:253], v[88:91]
	v_mfma_f32_16x16x32_bf16 v[80:83], v[182:185], v[250:253], v[80:83]
	v_mfma_f32_16x16x32_bf16 v[116:119], v[186:189], v[202:205], v[116:119]
	v_mfma_f32_16x16x32_bf16 v[108:111], v[194:197], v[202:205], v[108:111]
	v_mfma_f32_16x16x32_bf16 v[104:107], v[186:189], v[220:223], v[104:107]
	v_mfma_f32_16x16x32_bf16 v[100:103], v[194:197], v[220:223], v[100:103]
	v_mfma_f32_16x16x32_bf16 v[84:87], v[186:189], v[238:241], v[84:87]
	v_mfma_f32_16x16x32_bf16 v[76:79], v[194:197], v[238:241], v[76:79]
	v_mfma_f32_16x16x32_bf16 v[72:75], v[186:189], v[246:249], v[72:75]
	v_mfma_f32_16x16x32_bf16 v[68:71], v[194:197], v[246:249], v[68:71]
	v_mfma_f32_16x16x32_bf16 v[116:119], v[190:193], v[210:213], v[116:119]
	v_mfma_f32_16x16x32_bf16 v[108:111], v[198:201], v[210:213], v[108:111]
	v_mfma_f32_16x16x32_bf16 v[104:107], v[190:193], v[234:237], v[104:107]
	v_mfma_f32_16x16x32_bf16 v[100:103], v[198:201], v[234:237], v[100:103]
	v_mfma_f32_16x16x32_bf16 v[84:87], v[190:193], v[242:245], v[84:87]
	v_mfma_f32_16x16x32_bf16 v[76:79], v[198:201], v[242:245], v[76:79]
	v_mfma_f32_16x16x32_bf16 v[72:75], v[190:193], v[250:253], v[72:75]
	v_mfma_f32_16x16x32_bf16 v[68:71], v[198:201], v[250:253], v[68:71]
	s_barrier
; #define PG8_STAGE(bufoff, gbase, voff) do { _Pragma("unroll") for (int _i = 0; _i < 2; ++_i) \
;         __builtin_amdgcn_global_load_lds((const unsigned*)((const char*)(gbase) + (voff)[_i]), (LAS unsigned*)(lds + (bufoff) + ldsw + _i * 8192), 16, 0, 0); } while (0)
; #define PG8_LDA(dst, b, h) do { _Pragma("unroll") for (int m = 0; m < 4; ++m) _Pragma("unroll") for (int k = 0; k < 2; ++k) dst[m][k] = *(const LAS bf16x8*)(lds + PG8_SA(b, h) + aoff + m * 2048 + k * 1024); } while (0)
; #define PG8_MMA(ai, bj, At, Bt) do { __builtin_amdgcn_s_setprio(1); _Pragma("unroll") for (int m = 0; m < 4; ++m) _Pragma("unroll") for (int n = 0; n < 2; ++n) _Pragma("unroll") for (int k = 0; k < 2; ++k) \
;         acc[ai][bj][m][n] = __builtin_amdgcn_mfma_f32_16x16x32_bf16(Bt[n][k], At[m][k], acc[ai][bj][m][n], 0, 0, 0); __builtin_amdgcn_s_setprio(0); } while (0)
; #define PG8_WAIT_V(n) asm volatile("s_waitcnt vmcnt(" #n ")" ::: "memory")
; #define PG8_WAIT_L(n) asm volatile("s_waitcnt lgkmcnt(" #n ")" ::: "memory")
; #define PG8_BAR __builtin_amdgcn_s_barrier()
; #define PG8_SCHED __builtin_amdgcn_sched_barrier(0)
; template <class Epi, class Sched>
; __device__ __forceinline__ void gemm_phase(LAS unsigned char* lds, const Gemm g, const Sched& S, const Epi& E, const int tid) {
;     ...
;             PG8_LDA(At, 1, 1); PG8_STAGE(PG8_SB(1, 0), b3, voffB); PG8_STAGE(PG8_SB(1, 1), b3 + hstepB, voffB); PG8_STAGE(PG8_SA(1, 0), a3, voffA);
;             PG8_WAIT_V(8); PG8_WAIT_L(0); PG8_BAR; PG8_MMA(1, 0, At, B0); PG8_MMA(1, 1, At, B1); PG8_BAR; PG8_SCHED;
;         }
;         if (wr == 0) PG8_BAR;
	s_add_i32 s12, vcc_lo, s59
	v_lshl_add_u64 v[154:155], v[154:155], 0, s[28:29]
	s_mov_b32 m0, s12
	ds_read_b128 v[202:205], v153 offset:49152
	ds_read_b128 v[210:213], v153 offset:50176
	ds_read_b128 v[220:223], v153 offset:51200
	ds_read_b128 v[234:237], v153 offset:52224
	ds_read_b128 v[238:241], v153 offset:53248
	ds_read_b128 v[242:245], v153 offset:54272
	ds_read_b128 v[246:249], v153 offset:55296
	ds_read_b128 v[250:253], v153 offset:56320
	global_load_lds_dwordx4 v[154:155], off
	s_add_i32 m0, s12, 0x2000
	s_add_u32 s12, s90, 0x40080
	v_lshl_add_u64 v[154:155], v[162:163], 0, s[28:29]
	s_addc_u32 s13, s91, 0
	s_add_i32 s90, vcc_hi, s59
	global_load_lds_dwordx4 v[154:155], off
	v_lshl_add_u64 v[154:155], s[12:13], 0, v[164:165]
	s_mov_b32 m0, s90
	s_nop 0
	global_load_lds_dwordx4 v[154:155], off
	v_lshl_add_u64 v[154:155], s[12:13], 0, v[160:161]
	s_add_i32 m0, s90, 0x2000
	s_nop 0
	global_load_lds_dwordx4 v[154:155], off
	v_lshl_add_u64 v[154:155], v[206:207], 0, s[28:29]
	s_mov_b32 m0, s88
	s_nop 0
	global_load_lds_dwordx4 v[154:155], off
	v_lshl_add_u64 v[154:155], v[224:225], 0, s[28:29]
	s_mov_b32 m0, s89
	s_nop 0
	global_load_lds_dwordx4 v[154:155], off
	s_waitcnt vmcnt(8)
	s_waitcnt lgkmcnt(0)
	s_barrier
	s_waitcnt lgkmcnt(0)
	v_mfma_f32_16x16x32_bf16 v[64:67], v[136:139], v[202:205], v[64:67]
	v_mfma_f32_16x16x32_bf16 v[60:63], v[178:181], v[202:205], v[60:63]
	v_mfma_f32_16x16x32_bf16 v[56:59], v[136:139], v[220:223], v[56:59]
	v_mfma_f32_16x16x32_bf16 v[48:51], v[178:181], v[220:223], v[48:51]
	v_mfma_f32_16x16x32_bf16 v[32:35], v[136:139], v[238:241], v[32:35]
	v_mfma_f32_16x16x32_bf16 v[28:31], v[178:181], v[238:241], v[28:31]
	v_mfma_f32_16x16x32_bf16 v[20:23], v[136:139], v[246:249], v[20:23]
	v_mfma_f32_16x16x32_bf16 v[12:15], v[178:181], v[246:249], v[12:15]
	v_mfma_f32_16x16x32_bf16 v[64:67], v[174:177], v[210:213], v[64:67]
	v_mfma_f32_16x16x32_bf16 v[60:63], v[182:185], v[210:213], v[60:63]
	v_mfma_f32_16x16x32_bf16 v[56:59], v[174:177], v[234:237], v[56:59]
	v_mfma_f32_16x16x32_bf16 v[48:51], v[182:185], v[234:237], v[48:51]
	v_mfma_f32_16x16x32_bf16 v[32:35], v[174:177], v[242:245], v[32:35]
	v_mfma_f32_16x16x32_bf16 v[28:31], v[182:185], v[242:245], v[28:31]
	v_mfma_f32_16x16x32_bf16 v[20:23], v[174:177], v[250:253], v[20:23]
	v_mfma_f32_16x16x32_bf16 v[12:15], v[182:185], v[250:253], v[12:15]
	v_mfma_f32_16x16x32_bf16 v[52:55], v[186:189], v[202:205], v[52:55]
	v_mfma_f32_16x16x32_bf16 v[44:47], v[194:197], v[202:205], v[44:47]
	v_mfma_f32_16x16x32_bf16 v[40:43], v[186:189], v[220:223], v[40:43]
	v_mfma_f32_16x16x32_bf16 v[36:39], v[194:197], v[220:223], v[36:39]
	v_mfma_f32_16x16x32_bf16 v[24:27], v[186:189], v[238:241], v[24:27]
	v_mfma_f32_16x16x32_bf16 v[16:19], v[194:197], v[238:241], v[16:19]
	v_mfma_f32_16x16x32_bf16 v[8:11], v[186:189], v[246:249], v[8:11]
	v_mfma_f32_16x16x32_bf16 v[4:7], v[194:197], v[246:249], v[4:7]
	v_mfma_f32_16x16x32_bf16 v[52:55], v[190:193], v[210:213], v[52:55]
	v_mfma_f32_16x16x32_bf16 v[44:47], v[198:201], v[210:213], v[44:47]
	v_mfma_f32_16x16x32_bf16 v[40:43], v[190:193], v[234:237], v[40:43]
	v_mfma_f32_16x16x32_bf16 v[36:39], v[198:201], v[234:237], v[36:39]
	v_mfma_f32_16x16x32_bf16 v[24:27], v[190:193], v[242:245], v[24:27]
	v_mfma_f32_16x16x32_bf16 v[16:19], v[198:201], v[242:245], v[16:19]
	v_mfma_f32_16x16x32_bf16 v[8:11], v[190:193], v[250:253], v[8:11]
	v_mfma_f32_16x16x32_bf16 v[4:7], v[198:201], v[250:253], v[4:7]
	s_barrier
	s_add_i32 s97, s97, 2
	s_add_u32 s54, s54, 0x100
	s_addc_u32 s55, s55, 0
	s_add_u32 s47, s47, 0x100
	s_addc_u32 s96, s96, 0
	s_cmp_gt_u32 s97, 13
	s_cbranch_scc0 .LBB0_308
	s_and_b64 vcc, exec, s[20:21]
	s_cbranch_vccz .LBB0_311
	s_barrier

; #define PG8_STAGE(bufoff, gbase, voff) do { _Pragma("unroll") for (int _i = 0; _i < 2; ++_i) \
;         __builtin_amdgcn_global_load_lds((const unsigned*)((const char*)(gbase) + (voff)[_i]), (LAS unsigned*)(lds + (bufoff) + ldsw + _i * 8192), 16, 0, 0); } while (0)
; #define PG8_LDA(dst, b, h) do { _Pragma("unroll") for (int m = 0; m < 4; ++m) _Pragma("unroll") for (int k = 0; k < 2; ++k) dst[m][k] = *(const LAS bf16x8*)(lds + PG8_SA(b, h) + aoff + m * 2048 + k * 1024); } while (0)
; #define PG8_LDB(dst, b, h) do { _Pragma("unroll") for (int n = 0; n < 2; ++n) _Pragma("unroll") for (int k = 0; k < 2; ++k) dst[n][k] = *(const LAS bf16x8*)(lds + PG8_SB(b, h) + boff + n * 2048 + k * 1024); } while (0)
; #define PG8_MMA(ai, bj, At, Bt) do { __builtin_amdgcn_s_setprio(1); _Pragma("unroll") for (int m = 0; m < 4; ++m) _Pragma("unroll") for (int n = 0; n < 2; ++n) _Pragma("unroll") for (int k = 0; k < 2; ++k) \
;         acc[ai][bj][m][n] = __builtin_amdgcn_mfma_f32_16x16x32_bf16(Bt[n][k], At[m][k], acc[ai][bj][m][n], 0, 0, 0); __builtin_amdgcn_s_setprio(0); } while (0)
; #define PG8_WAIT_V(n) asm volatile("s_waitcnt vmcnt(" #n ")" ::: "memory")
; #define PG8_WAIT_L(n) asm volatile("s_waitcnt lgkmcnt(" #n ")" ::: "memory")
; #define PG8_BAR __builtin_amdgcn_s_barrier()
; #define PG8_SCHED __builtin_amdgcn_sched_barrier(0)
; template <class Epi, class Sched>
; __device__ __forceinline__ void gemm_phase(LAS unsigned char* lds, const Gemm g, const Sched& S, const Epi& E, const int tid) {
;     ...
;             const bool last = (t == nt - 2);
;             const char* a1 = cA + (size_t)(t + 1) * kstep;
;             const char* a2 = last ? nA : cA + (size_t)(t + 2) * kstep; const char* b2 = last ? nB : cB + (size_t)(t + 2) * kstep;
;             const char* a3 = a2 + kstep; const char* b3 = b2 + kstep;
;             PG8_LDB(B0, 0, 0); PG8_LDB(B1, 0, 1); PG8_SCHED; PG8_LDA(At, 0, 0); PG8_STAGE(PG8_SA(1, 1), a1 + hstepA, voffA);
;             PG8_WAIT_V(8); PG8_WAIT_L(0); PG8_BAR; PG8_MMA(0, 0, At, B0); PG8_MMA(0, 1, At, B1); PG8_BAR; PG8_SCHED;
;             PG8_LDA(At, 0, 1); PG8_STAGE(PG8_SB(0, 0), b2, voffB); PG8_STAGE(PG8_SB(0, 1), b2 + hstepB, voffB); PG8_STAGE(PG8_SA(0, 0), a2, voffA);
.LBB0_332:
	s_add_u32 s12, s54, 0xfffc0080
	s_addc_u32 s13, s55, -1
	s_add_i32 vcc_lo, 0, 0x10000
	s_cmp_eq_u32 s97, 12
	s_cselect_b32 s93, s16, s13
	s_cselect_b32 s92, s17, s12
	s_cselect_b32 s91, s31, s96
	s_cselect_b32 s90, s39, s47
	s_add_i32 vcc_hi, 0, 0x14000
	v_add_u32_e32 v144, vcc_lo, v178
	v_add_u32_e32 v176, vcc_hi, v178
	ds_read_b128 v[132:135], v144
	ds_read_b128 v[136:139], v144 offset:1024
	ds_read_b128 v[140:143], v144 offset:2048
	ds_read_b128 v[144:147], v144 offset:3072
	ds_read_b128 v[148:151], v176
	ds_read_b128 v[152:155], v176 offset:1024
	ds_read_b128 v[182:185], v176 offset:2048
	ds_read_b128 v[186:189], v176 offset:3072
	v_lshl_add_u64 v[176:177], s[54:55], 0, v[162:163]
	s_add_i32 m0, s79, 0xc000
	ds_read_b128 v[190:193], v180
	ds_read_b128 v[194:197], v180 offset:1024
	ds_read_b128 v[198:201], v180 offset:2048
	ds_read_b128 v[202:205], v180 offset:3072
	ds_read_b128 v[210:213], v180 offset:4096
	ds_read_b128 v[220:223], v180 offset:5120
	ds_read_b128 v[234:237], v180 offset:6144
	ds_read_b128 v[238:241], v180 offset:7168
	global_load_lds_dwordx4 v[176:177], off
	v_lshl_add_u64 v[176:177], s[54:55], 0, v[174:175]
	s_add_i32 m0, s79, 0xe000
	s_nop 0
	global_load_lds_dwordx4 v[176:177], off
	s_waitcnt vmcnt(8)
	s_waitcnt lgkmcnt(0)
	s_barrier
	s_waitcnt lgkmcnt(0)
	v_mfma_f32_16x16x32_bf16 v[128:131], v[132:135], v[190:193], v[128:131]
	v_mfma_f32_16x16x32_bf16 v[124:127], v[140:143], v[190:193], v[124:127]
	v_mfma_f32_16x16x32_bf16 v[112:115], v[132:135], v[198:201], v[112:115]
	v_mfma_f32_16x16x32_bf16 v[108:111], v[140:143], v[198:201], v[108:111]
	v_mfma_f32_16x16x32_bf16 v[96:99], v[132:135], v[210:213], v[96:99]
	v_mfma_f32_16x16x32_bf16 v[92:95], v[140:143], v[210:213], v[92:95]
	v_mfma_f32_16x16x32_bf16 v[80:83], v[132:135], v[234:237], v[80:83]
	v_mfma_f32_16x16x32_bf16 v[76:79], v[140:143], v[234:237], v[76:79]
	v_mfma_f32_16x16x32_bf16 v[128:131], v[136:139], v[194:197], v[128:131]
	v_mfma_f32_16x16x32_bf16 v[124:127], v[144:147], v[194:197], v[124:127]
	v_mfma_f32_16x16x32_bf16 v[112:115], v[136:139], v[202:205], v[112:115]
	v_mfma_f32_16x16x32_bf16 v[108:111], v[144:147], v[202:205], v[108:111]
	v_mfma_f32_16x16x32_bf16 v[96:99], v[136:139], v[220:223], v[96:99]
	v_mfma_f32_16x16x32_bf16 v[92:95], v[144:147], v[220:223], v[92:95]
	v_mfma_f32_16x16x32_bf16 v[80:83], v[136:139], v[238:241], v[80:83]
	v_mfma_f32_16x16x32_bf16 v[76:79], v[144:147], v[238:241], v[76:79]
	v_mfma_f32_16x16x32_bf16 v[120:123], v[148:151], v[190:193], v[120:123]
	v_mfma_f32_16x16x32_bf16 v[116:119], v[182:185], v[190:193], v[116:119]
	v_mfma_f32_16x16x32_bf16 v[104:107], v[148:151], v[198:201], v[104:107]
	v_mfma_f32_16x16x32_bf16 v[100:103], v[182:185], v[198:201], v[100:103]
	v_mfma_f32_16x16x32_bf16 v[88:91], v[148:151], v[210:213], v[88:91]
	v_mfma_f32_16x16x32_bf16 v[84:87], v[182:185], v[210:213], v[84:87]
	v_mfma_f32_16x16x32_bf16 v[72:75], v[148:151], v[234:237], v[72:75]
	v_mfma_f32_16x16x32_bf16 v[68:71], v[182:185], v[234:237], v[68:71]
	v_mfma_f32_16x16x32_bf16 v[120:123], v[152:155], v[194:197], v[120:123]
	v_mfma_f32_16x16x32_bf16 v[116:119], v[186:189], v[194:197], v[116:119]
	v_mfma_f32_16x16x32_bf16 v[104:107], v[152:155], v[202:205], v[104:107]
	v_mfma_f32_16x16x32_bf16 v[100:103], v[186:189], v[202:205], v[100:103]
	v_mfma_f32_16x16x32_bf16 v[88:91], v[152:155], v[220:223], v[88:91]
	v_mfma_f32_16x16x32_bf16 v[84:87], v[186:189], v[220:223], v[84:87]
	v_mfma_f32_16x16x32_bf16 v[72:75], v[152:155], v[238:241], v[72:75]
	v_mfma_f32_16x16x32_bf16 v[68:71], v[186:189], v[238:241], v[68:71]
	s_barrier
	s_add_i32 s12, vcc_lo, s59
	v_lshl_add_u64 v[176:177], s[90:91], 0, v[164:165]
	s_mov_b32 m0, s12
	ds_read_b128 v[190:193], v180 offset:16384
	ds_read_b128 v[194:197], v180 offset:17408
	ds_read_b128 v[198:201], v180 offset:18432
	ds_read_b128 v[202:205], v180 offset:19456
	ds_read_b128 v[210:213], v180 offset:20480
	ds_read_b128 v[220:223], v180 offset:21504
	ds_read_b128 v[234:237], v180 offset:22528
	ds_read_b128 v[238:241], v180 offset:23552
	global_load_lds_dwordx4 v[176:177], off
	s_add_i32 m0, s12, 0x2000
	s_add_u32 s12, s90, 0x40000
	v_lshl_add_u64 v[206:207], s[90:91], 0, v[160:161]
	s_addc_u32 s13, s91, 0
	s_add_i32 vcc_lo, vcc_hi, s59
	global_load_lds_dwordx4 v[206:207], off
	v_lshl_add_u64 v[224:225], s[12:13], 0, v[164:165]
	s_mov_b32 m0, vcc_lo
	v_lshl_add_u64 v[226:227], s[92:93], 0, v[158:159]
	global_load_lds_dwordx4 v[224:225], off
	v_lshl_add_u64 v[224:225], s[12:13], 0, v[160:161]
	s_add_i32 m0, vcc_lo, 0x2000
	s_nop 0
	global_load_lds_dwordx4 v[224:225], off
	v_lshl_add_u64 v[224:225], s[92:93], 0, v[156:157]
	s_mov_b32 m0, s79
	s_nop 0
	global_load_lds_dwordx4 v[224:225], off
	s_mov_b32 m0, s85
	s_nop 0
	global_load_lds_dwordx4 v[226:227], off
	s_waitcnt vmcnt(8)
	s_waitcnt lgkmcnt(0)
	s_barrier
; #define PG8_STAGE(bufoff, gbase, voff) do { _Pragma("unroll") for (int _i = 0; _i < 2; ++_i) \
;         __builtin_amdgcn_global_load_lds((const unsigned*)((const char*)(gbase) + (voff)[_i]), (LAS unsigned*)(lds + (bufoff) + ldsw + _i * 8192), 16, 0, 0); } while (0)
; #define PG8_LDA(dst, b, h) do { _Pragma("unroll") for (int m = 0; m < 4; ++m) _Pragma("unroll") for (int k = 0; k < 2; ++k) dst[m][k] = *(const LAS bf16x8*)(lds + PG8_SA(b, h) + aoff + m * 2048 + k * 1024); } while (0)
; #define PG8_LDB(dst, b, h) do { _Pragma("unroll") for (int n = 0; n < 2; ++n) _Pragma("unroll") for (int k = 0; k < 2; ++k) dst[n][k] = *(const LAS bf16x8*)(lds + PG8_SB(b, h) + boff + n * 2048 + k * 1024); } while (0)
; #define PG8_MMA(ai, bj, At, Bt) do { __builtin_amdgcn_s_setprio(1); _Pragma("unroll") for (int m = 0; m < 4; ++m) _Pragma("unroll") for (int n = 0; n < 2; ++n) _Pragma("unroll") for (int k = 0; k < 2; ++k) \
;         acc[ai][bj][m][n] = __builtin_amdgcn_mfma_f32_16x16x32_bf16(Bt[n][k], At[m][k], acc[ai][bj][m][n], 0, 0, 0); __builtin_amdgcn_s_setprio(0); } while (0)
; #define PG8_WAIT_V(n) asm volatile("s_waitcnt vmcnt(" #n ")" ::: "memory")
; #define PG8_WAIT_L(n) asm volatile("s_waitcnt lgkmcnt(" #n ")" ::: "memory")
; #define PG8_BAR __builtin_amdgcn_s_barrier()
; #define PG8_SCHED __builtin_amdgcn_sched_barrier(0)
; template <class Epi, class Sched>
; __device__ __forceinline__ void gemm_phase(LAS unsigned char* lds, const Gemm g, const Sched& S, const Epi& E, const int tid) {
;     ...
;             PG8_WAIT_V(8); PG8_WAIT_L(0); PG8_BAR; PG8_MMA(1, 0, At, B0); PG8_MMA(1, 1, At, B1); PG8_BAR; PG8_SCHED;
;             PG8_LDB(B0, 1, 0); PG8_LDB(B1, 1, 1); PG8_SCHED; PG8_LDA(At, 1, 0); PG8_STAGE(PG8_SA(0, 1), a2 + hstepA, voffA);
;             PG8_WAIT_V(8); PG8_WAIT_L(0); PG8_BAR; PG8_MMA(0, 0, At, B0); PG8_MMA(0, 1, At, B1); PG8_BAR; PG8_SCHED;
	s_waitcnt lgkmcnt(0)
	v_mfma_f32_16x16x32_bf16 v[64:67], v[132:135], v[190:193], v[64:67]
	v_mfma_f32_16x16x32_bf16 v[60:63], v[140:143], v[190:193], v[60:63]
	v_mfma_f32_16x16x32_bf16 v[48:51], v[132:135], v[198:201], v[48:51]
	v_mfma_f32_16x16x32_bf16 v[44:47], v[140:143], v[198:201], v[44:47]
	v_mfma_f32_16x16x32_bf16 v[32:35], v[132:135], v[210:213], v[32:35]
	v_mfma_f32_16x16x32_bf16 v[28:31], v[140:143], v[210:213], v[28:31]
	v_mfma_f32_16x16x32_bf16 v[16:19], v[132:135], v[234:237], v[16:19]
	v_mfma_f32_16x16x32_bf16 v[12:15], v[140:143], v[234:237], v[12:15]
	v_mfma_f32_16x16x32_bf16 v[64:67], v[136:139], v[194:197], v[64:67]
	v_mfma_f32_16x16x32_bf16 v[60:63], v[144:147], v[194:197], v[60:63]
	v_mfma_f32_16x16x32_bf16 v[48:51], v[136:139], v[202:205], v[48:51]
	v_mfma_f32_16x16x32_bf16 v[44:47], v[144:147], v[202:205], v[44:47]
	v_mfma_f32_16x16x32_bf16 v[32:35], v[136:139], v[220:223], v[32:35]
	v_mfma_f32_16x16x32_bf16 v[28:31], v[144:147], v[220:223], v[28:31]
	v_mfma_f32_16x16x32_bf16 v[16:19], v[136:139], v[238:241], v[16:19]
	v_mfma_f32_16x16x32_bf16 v[12:15], v[144:147], v[238:241], v[12:15]
	v_mfma_f32_16x16x32_bf16 v[56:59], v[148:151], v[190:193], v[56:59]
	v_mfma_f32_16x16x32_bf16 v[52:55], v[182:185], v[190:193], v[52:55]
	v_mfma_f32_16x16x32_bf16 v[40:43], v[148:151], v[198:201], v[40:43]
	v_mfma_f32_16x16x32_bf16 v[36:39], v[182:185], v[198:201], v[36:39]
	v_mfma_f32_16x16x32_bf16 v[24:27], v[148:151], v[210:213], v[24:27]
	v_mfma_f32_16x16x32_bf16 v[20:23], v[182:185], v[210:213], v[20:23]
	v_mfma_f32_16x16x32_bf16 v[8:11], v[148:151], v[234:237], v[8:11]
	v_mfma_f32_16x16x32_bf16 v[4:7], v[182:185], v[234:237], v[4:7]
	v_mfma_f32_16x16x32_bf16 v[56:59], v[152:155], v[194:197], v[56:59]
	v_mfma_f32_16x16x32_bf16 v[52:55], v[186:189], v[194:197], v[52:55]
	v_mfma_f32_16x16x32_bf16 v[40:43], v[152:155], v[202:205], v[40:43]
	v_mfma_f32_16x16x32_bf16 v[36:39], v[186:189], v[202:205], v[36:39]
	v_mfma_f32_16x16x32_bf16 v[24:27], v[152:155], v[220:223], v[24:27]
	v_mfma_f32_16x16x32_bf16 v[20:23], v[186:189], v[220:223], v[20:23]
	v_mfma_f32_16x16x32_bf16 v[8:11], v[152:155], v[238:241], v[8:11]
	v_mfma_f32_16x16x32_bf16 v[4:7], v[186:189], v[238:241], v[4:7]
	s_barrier
	s_add_i32 vcc_lo, 0, 0x18000
	s_add_i32 vcc_hi, 0, 0x1c000
	v_add_u32_e32 v144, vcc_lo, v178
	v_add_u32_e32 v181, vcc_hi, v178
	ds_read_b128 v[132:135], v144
	ds_read_b128 v[136:139], v144 offset:1024
	ds_read_b128 v[140:143], v144 offset:2048
	ds_read_b128 v[144:147], v144 offset:3072
	ds_read_b128 v[148:151], v181
	ds_read_b128 v[152:155], v181 offset:1024
	ds_read_b128 v[182:185], v181 offset:2048
	ds_read_b128 v[186:189], v181 offset:3072
	s_add_u32 s12, s92, 0x40000
	s_addc_u32 s13, s93, 0
	s_mov_b32 m0, s86
	v_lshl_add_u64 v[242:243], s[12:13], 0, v[156:157]
	ds_read_b128 v[190:193], v180 offset:32768
	ds_read_b128 v[194:197], v180 offset:33792
	ds_read_b128 v[198:201], v180 offset:34816
	ds_read_b128 v[202:205], v180 offset:35840
	ds_read_b128 v[210:213], v180 offset:36864
	ds_read_b128 v[220:223], v180 offset:37888
	ds_read_b128 v[234:237], v180 offset:38912
	ds_read_b128 v[238:241], v180 offset:39936
	global_load_lds_dwordx4 v[242:243], off
	v_lshl_add_u64 v[242:243], s[12:13], 0, v[158:159]
	s_mov_b32 m0, s87
	s_nop 0
	global_load_lds_dwordx4 v[242:243], off
	s_waitcnt vmcnt(8)
	s_waitcnt lgkmcnt(0)
	s_barrier
	s_waitcnt lgkmcnt(0)
	v_mfma_f32_16x16x32_bf16 v[128:131], v[132:135], v[190:193], v[128:131]
	v_mfma_f32_16x16x32_bf16 v[124:127], v[140:143], v[190:193], v[124:127]
	v_mfma_f32_16x16x32_bf16 v[112:115], v[132:135], v[198:201], v[112:115]
	v_mfma_f32_16x16x32_bf16 v[108:111], v[140:143], v[198:201], v[108:111]
	v_mfma_f32_16x16x32_bf16 v[96:99], v[132:135], v[210:213], v[96:99]
	v_mfma_f32_16x16x32_bf16 v[92:95], v[140:143], v[210:213], v[92:95]
	v_mfma_f32_16x16x32_bf16 v[80:83], v[132:135], v[234:237], v[80:83]
	v_mfma_f32_16x16x32_bf16 v[76:79], v[140:143], v[234:237], v[76:79]
	v_mfma_f32_16x16x32_bf16 v[128:131], v[136:139], v[194:197], v[128:131]
	v_mfma_f32_16x16x32_bf16 v[124:127], v[144:147], v[194:197], v[124:127]
	v_mfma_f32_16x16x32_bf16 v[112:115], v[136:139], v[202:205], v[112:115]
	v_mfma_f32_16x16x32_bf16 v[108:111], v[144:147], v[202:205], v[108:111]
	v_mfma_f32_16x16x32_bf16 v[96:99], v[136:139], v[220:223], v[96:99]
	v_mfma_f32_16x16x32_bf16 v[92:95], v[144:147], v[220:223], v[92:95]
	v_mfma_f32_16x16x32_bf16 v[80:83], v[136:139], v[238:241], v[80:83]
	v_mfma_f32_16x16x32_bf16 v[76:79], v[144:147], v[238:241], v[76:79]
	v_mfma_f32_16x16x32_bf16 v[120:123], v[148:151], v[190:193], v[120:123]
	v_mfma_f32_16x16x32_bf16 v[116:119], v[182:185], v[190:193], v[116:119]
	v_mfma_f32_16x16x32_bf16 v[104:107], v[148:151], v[198:201], v[104:107]
	v_mfma_f32_16x16x32_bf16 v[100:103], v[182:185], v[198:201], v[100:103]
	v_mfma_f32_16x16x32_bf16 v[88:91], v[148:151], v[210:213], v[88:91]
	v_mfma_f32_16x16x32_bf16 v[84:87], v[182:185], v[210:213], v[84:87]
	v_mfma_f32_16x16x32_bf16 v[72:75], v[148:151], v[234:237], v[72:75]
	v_mfma_f32_16x16x32_bf16 v[68:71], v[182:185], v[234:237], v[68:71]
	v_mfma_f32_16x16x32_bf16 v[120:123], v[152:155], v[194:197], v[120:123]
	v_mfma_f32_16x16x32_bf16 v[116:119], v[186:189], v[194:197], v[116:119]
	v_mfma_f32_16x16x32_bf16 v[104:107], v[152:155], v[202:205], v[104:107]
	v_mfma_f32_16x16x32_bf16 v[100:103], v[186:189], v[202:205], v[100:103]
	v_mfma_f32_16x16x32_bf16 v[88:91], v[152:155], v[220:223], v[88:91]
	v_mfma_f32_16x16x32_bf16 v[84:87], v[186:189], v[220:223], v[84:87]
	v_mfma_f32_16x16x32_bf16 v[72:75], v[152:155], v[238:241], v[72:75]
	v_mfma_f32_16x16x32_bf16 v[68:71], v[186:189], v[238:241], v[68:71]
	s_barrier
; #define PG8_STAGE(bufoff, gbase, voff) do { _Pragma("unroll") for (int _i = 0; _i < 2; ++_i) \
;         __builtin_amdgcn_global_load_lds((const unsigned*)((const char*)(gbase) + (voff)[_i]), (LAS unsigned*)(lds + (bufoff) + ldsw + _i * 8192), 16, 0, 0); } while (0)
; #define PG8_LDA(dst, b, h) do { _Pragma("unroll") for (int m = 0; m < 4; ++m) _Pragma("unroll") for (int k = 0; k < 2; ++k) dst[m][k] = *(const LAS bf16x8*)(lds + PG8_SA(b, h) + aoff + m * 2048 + k * 1024); } while (0)
; #define PG8_MMA(ai, bj, At, Bt) do { __builtin_amdgcn_s_setprio(1); _Pragma("unroll") for (int m = 0; m < 4; ++m) _Pragma("unroll") for (int n = 0; n < 2; ++n) _Pragma("unroll") for (int k = 0; k < 2; ++k) \
;         acc[ai][bj][m][n] = __builtin_amdgcn_mfma_f32_16x16x32_bf16(Bt[n][k], At[m][k], acc[ai][bj][m][n], 0, 0, 0); __builtin_amdgcn_s_setprio(0); } while (0)
; #define PG8_WAIT_V(n) asm volatile("s_waitcnt vmcnt(" #n ")" ::: "memory")
; #define PG8_WAIT_L(n) asm volatile("s_waitcnt lgkmcnt(" #n ")" ::: "memory")
; #define PG8_BAR __builtin_amdgcn_s_barrier()
; #define PG8_SCHED __builtin_amdgcn_sched_barrier(0)
; template <class Epi, class Sched>
; __device__ __forceinline__ void gemm_phase(LAS unsigned char* lds, const Gemm g, const Sched& S, const Epi& E, const int tid) {
;     ...
;             PG8_LDA(At, 1, 1); PG8_STAGE(PG8_SB(1, 0), b3, voffB); PG8_STAGE(PG8_SB(1, 1), b3 + hstepB, voffB); PG8_STAGE(PG8_SA(1, 0), a3, voffA);
;             PG8_WAIT_V(8); PG8_WAIT_L(0); PG8_BAR; PG8_MMA(1, 0, At, B0); PG8_MMA(1, 1, At, B1); PG8_BAR; PG8_SCHED;
;         }
;         if (wr == 0) PG8_BAR;
	s_add_i32 s12, vcc_lo, s59
	v_lshl_add_u64 v[176:177], v[176:177], 0, s[28:29]
	s_mov_b32 m0, s12
	ds_read_b128 v[190:193], v180 offset:49152
	ds_read_b128 v[194:197], v180 offset:50176
	ds_read_b128 v[198:201], v180 offset:51200
	ds_read_b128 v[202:205], v180 offset:52224
	ds_read_b128 v[210:213], v180 offset:53248
	ds_read_b128 v[220:223], v180 offset:54272
	ds_read_b128 v[234:237], v180 offset:55296
	ds_read_b128 v[238:241], v180 offset:56320
	global_load_lds_dwordx4 v[176:177], off
	s_add_i32 m0, s12, 0x2000
	s_add_u32 s12, s90, 0x40080
	v_lshl_add_u64 v[176:177], v[206:207], 0, s[28:29]
	s_addc_u32 s13, s91, 0
	s_add_i32 s90, vcc_hi, s59
	global_load_lds_dwordx4 v[176:177], off
	v_lshl_add_u64 v[176:177], s[12:13], 0, v[164:165]
	s_mov_b32 m0, s90
	s_nop 0
	global_load_lds_dwordx4 v[176:177], off
	v_lshl_add_u64 v[176:177], s[12:13], 0, v[160:161]
	s_add_i32 m0, s90, 0x2000
	s_nop 0
	global_load_lds_dwordx4 v[176:177], off
	v_lshl_add_u64 v[176:177], v[224:225], 0, s[28:29]
	s_mov_b32 m0, s88
	s_nop 0
	global_load_lds_dwordx4 v[176:177], off
	v_lshl_add_u64 v[176:177], v[226:227], 0, s[28:29]
	s_mov_b32 m0, s89
	s_nop 0
	global_load_lds_dwordx4 v[176:177], off
	s_waitcnt vmcnt(8)
	s_waitcnt lgkmcnt(0)
	s_barrier
	s_waitcnt lgkmcnt(0)
	v_mfma_f32_16x16x32_bf16 v[64:67], v[132:135], v[190:193], v[64:67]
	v_mfma_f32_16x16x32_bf16 v[60:63], v[140:143], v[190:193], v[60:63]
	v_mfma_f32_16x16x32_bf16 v[48:51], v[132:135], v[198:201], v[48:51]
	v_mfma_f32_16x16x32_bf16 v[44:47], v[140:143], v[198:201], v[44:47]
	v_mfma_f32_16x16x32_bf16 v[32:35], v[132:135], v[210:213], v[32:35]
	v_mfma_f32_16x16x32_bf16 v[28:31], v[140:143], v[210:213], v[28:31]
	v_mfma_f32_16x16x32_bf16 v[16:19], v[132:135], v[234:237], v[16:19]
	v_mfma_f32_16x16x32_bf16 v[12:15], v[140:143], v[234:237], v[12:15]
	v_mfma_f32_16x16x32_bf16 v[64:67], v[136:139], v[194:197], v[64:67]
	v_mfma_f32_16x16x32_bf16 v[60:63], v[144:147], v[194:197], v[60:63]
	v_mfma_f32_16x16x32_bf16 v[48:51], v[136:139], v[202:205], v[48:51]
	v_mfma_f32_16x16x32_bf16 v[44:47], v[144:147], v[202:205], v[44:47]
	v_mfma_f32_16x16x32_bf16 v[32:35], v[136:139], v[220:223], v[32:35]
	v_mfma_f32_16x16x32_bf16 v[28:31], v[144:147], v[220:223], v[28:31]
	v_mfma_f32_16x16x32_bf16 v[16:19], v[136:139], v[238:241], v[16:19]
	v_mfma_f32_16x16x32_bf16 v[12:15], v[144:147], v[238:241], v[12:15]
	v_mfma_f32_16x16x32_bf16 v[56:59], v[148:151], v[190:193], v[56:59]
	v_mfma_f32_16x16x32_bf16 v[52:55], v[182:185], v[190:193], v[52:55]
	v_mfma_f32_16x16x32_bf16 v[40:43], v[148:151], v[198:201], v[40:43]
	v_mfma_f32_16x16x32_bf16 v[36:39], v[182:185], v[198:201], v[36:39]
	v_mfma_f32_16x16x32_bf16 v[24:27], v[148:151], v[210:213], v[24:27]
	v_mfma_f32_16x16x32_bf16 v[20:23], v[182:185], v[210:213], v[20:23]
	v_mfma_f32_16x16x32_bf16 v[8:11], v[148:151], v[234:237], v[8:11]
	v_mfma_f32_16x16x32_bf16 v[4:7], v[182:185], v[234:237], v[4:7]
	v_mfma_f32_16x16x32_bf16 v[56:59], v[152:155], v[194:197], v[56:59]
	v_mfma_f32_16x16x32_bf16 v[52:55], v[186:189], v[194:197], v[52:55]
	v_mfma_f32_16x16x32_bf16 v[40:43], v[152:155], v[202:205], v[40:43]
	v_mfma_f32_16x16x32_bf16 v[36:39], v[186:189], v[202:205], v[36:39]
	v_mfma_f32_16x16x32_bf16 v[24:27], v[152:155], v[220:223], v[24:27]
	v_mfma_f32_16x16x32_bf16 v[20:23], v[186:189], v[220:223], v[20:23]
	v_mfma_f32_16x16x32_bf16 v[8:11], v[152:155], v[238:241], v[8:11]
	v_mfma_f32_16x16x32_bf16 v[4:7], v[186:189], v[238:241], v[4:7]
	s_barrier
	s_add_i32 s97, s97, 2
	s_add_u32 s54, s54, 0x100
	s_addc_u32 s55, s55, 0
	s_add_u32 s47, s47, 0x100
	s_addc_u32 s96, s96, 0
	s_cmp_gt_u32 s97, 13
	s_cbranch_scc0 .LBB0_332
	s_and_b64 vcc, exec, s[20:21]
	s_cbranch_vccz .LBB0_335
	s_barrier

; #define PG8_STAGE(bufoff, gbase, voff) do { _Pragma("unroll") for (int _i = 0; _i < 2; ++_i) \
;         __builtin_amdgcn_global_load_lds((const unsigned*)((const char*)(gbase) + (voff)[_i]), (LAS unsigned*)(lds + (bufoff) + ldsw + _i * 8192), 16, 0, 0); } while (0)
; #define PG8_LDA(dst, b, h) do { _Pragma("unroll") for (int m = 0; m < 4; ++m) _Pragma("unroll") for (int k = 0; k < 2; ++k) dst[m][k] = *(const LAS bf16x8*)(lds + PG8_SA(b, h) + aoff + m * 2048 + k * 1024); } while (0)
; #define PG8_LDB(dst, b, h) do { _Pragma("unroll") for (int n = 0; n < 2; ++n) _Pragma("unroll") for (int k = 0; k < 2; ++k) dst[n][k] = *(const LAS bf16x8*)(lds + PG8_SB(b, h) + boff + n * 2048 + k * 1024); } while (0)
; #define PG8_MMA(ai, bj, At, Bt) do { __builtin_amdgcn_s_setprio(1); _Pragma("unroll") for (int m = 0; m < 4; ++m) _Pragma("unroll") for (int n = 0; n < 2; ++n) _Pragma("unroll") for (int k = 0; k < 2; ++k) \
;         acc[ai][bj][m][n] = __builtin_amdgcn_mfma_f32_16x16x32_bf16(Bt[n][k], At[m][k], acc[ai][bj][m][n], 0, 0, 0); __builtin_amdgcn_s_setprio(0); } while (0)
; #define PG8_WAIT_V(n) asm volatile("s_waitcnt vmcnt(" #n ")" ::: "memory")
; #define PG8_WAIT_L(n) asm volatile("s_waitcnt lgkmcnt(" #n ")" ::: "memory")
; #define PG8_BAR __builtin_amdgcn_s_barrier()
; #define PG8_SCHED __builtin_amdgcn_sched_barrier(0)
; template <class Epi, class Sched>
; __device__ __forceinline__ void gemm_phase(LAS unsigned char* lds, const Gemm g, const Sched& S, const Epi& E, const int tid) {
;     ...
;             const bool last = (t == nt - 2);
;             const char* a1 = cA + (size_t)(t + 1) * kstep;
;             const char* a2 = last ? nA : cA + (size_t)(t + 2) * kstep; const char* b2 = last ? nB : cB + (size_t)(t + 2) * kstep;
;             const char* a3 = a2 + kstep; const char* b3 = b2 + kstep;
;             PG8_LDB(B0, 0, 0); PG8_LDB(B1, 0, 1); PG8_SCHED; PG8_LDA(At, 0, 0); PG8_STAGE(PG8_SA(1, 1), a1 + hstepA, voffA);
;             PG8_WAIT_V(8); PG8_WAIT_L(0); PG8_BAR; PG8_MMA(0, 0, At, B0); PG8_MMA(0, 1, At, B1); PG8_BAR; PG8_SCHED;
;             PG8_LDA(At, 0, 1); PG8_STAGE(PG8_SB(0, 0), b2, voffB); PG8_STAGE(PG8_SB(0, 1), b2 + hstepB, voffB); PG8_STAGE(PG8_SA(0, 0), a2, voffA);
.LBB0_589:
	s_add_u32 s54, s46, 0xfff80080
	s_addc_u32 s55, s47, -1
	s_add_i32 s88, 0, 0x10000
	s_cmp_eq_u32 s87, 28
	s_cselect_b32 s85, s0, s55
	s_cselect_b32 s84, s9, s54
	s_cselect_b32 s55, s11, s86
	s_cselect_b32 s54, s31, s39
	s_add_i32 s90, 0, 0x14000
	v_add_u32_e32 v154, s88, v163
	v_add_u32_e32 v175, s90, v163
	ds_read_b128 v[100:103], v154
	ds_read_b128 v[104:107], v154 offset:1024
	ds_read_b128 v[150:153], v154 offset:2048
	ds_read_b128 v[154:157], v154 offset:3072
	ds_read_b128 v[158:161], v175
	ds_read_b128 v[176:179], v175 offset:1024
	ds_read_b128 v[180:183], v175 offset:2048
	ds_read_b128 v[184:187], v175 offset:3072
	v_lshl_add_u64 v[210:211], s[46:47], 0, v[146:147]
	s_add_i32 m0, s5, 0xc000
	ds_read_b128 v[188:191], v174
	ds_read_b128 v[192:195], v174 offset:1024
	ds_read_b128 v[196:199], v174 offset:2048
	ds_read_b128 v[200:203], v174 offset:3072
	ds_read_b128 v[204:207], v174 offset:4096
	ds_read_b128 v[234:237], v174 offset:5120
	ds_read_b128 v[238:241], v174 offset:6144
	ds_read_b128 v[242:245], v174 offset:7168
	global_load_lds_dwordx4 v[210:211], off
	v_lshl_add_u64 v[210:211], s[46:47], 0, v[148:149]
	s_add_i32 m0, s5, 0xe000
	s_nop 0
	global_load_lds_dwordx4 v[210:211], off
	s_waitcnt vmcnt(8)
	s_waitcnt lgkmcnt(0)
	s_barrier
	s_waitcnt lgkmcnt(0)
	v_mfma_f32_16x16x32_bf16 v[136:139], v[100:103], v[188:191], v[136:139]
	v_mfma_f32_16x16x32_bf16 v[132:135], v[150:153], v[188:191], v[132:135]
	v_mfma_f32_16x16x32_bf16 v[128:131], v[100:103], v[196:199], v[128:131]
	v_mfma_f32_16x16x32_bf16 v[124:127], v[150:153], v[196:199], v[124:127]
	v_mfma_f32_16x16x32_bf16 v[120:123], v[100:103], v[204:207], v[120:123]
	v_mfma_f32_16x16x32_bf16 v[116:119], v[150:153], v[204:207], v[116:119]
	v_mfma_f32_16x16x32_bf16 v[112:115], v[100:103], v[238:241], v[112:115]
	v_mfma_f32_16x16x32_bf16 v[108:111], v[150:153], v[238:241], v[108:111]
	v_mfma_f32_16x16x32_bf16 v[136:139], v[104:107], v[192:195], v[136:139]
	v_mfma_f32_16x16x32_bf16 v[132:135], v[154:157], v[192:195], v[132:135]
	v_mfma_f32_16x16x32_bf16 v[128:131], v[104:107], v[200:203], v[128:131]
	v_mfma_f32_16x16x32_bf16 v[124:127], v[154:157], v[200:203], v[124:127]
	v_mfma_f32_16x16x32_bf16 v[120:123], v[104:107], v[234:237], v[120:123]
	v_mfma_f32_16x16x32_bf16 v[116:119], v[154:157], v[234:237], v[116:119]
	v_mfma_f32_16x16x32_bf16 v[112:115], v[104:107], v[242:245], v[112:115]
	v_mfma_f32_16x16x32_bf16 v[108:111], v[154:157], v[242:245], v[108:111]
	v_mfma_f32_16x16x32_bf16 v[64:67], v[158:161], v[188:191], v[64:67]
	v_mfma_f32_16x16x32_bf16 v[60:63], v[180:183], v[188:191], v[60:63]
	v_mfma_f32_16x16x32_bf16 v[56:59], v[158:161], v[196:199], v[56:59]
	v_mfma_f32_16x16x32_bf16 v[52:55], v[180:183], v[196:199], v[52:55]
	v_mfma_f32_16x16x32_bf16 v[48:51], v[158:161], v[204:207], v[48:51]
	v_mfma_f32_16x16x32_bf16 v[44:47], v[180:183], v[204:207], v[44:47]
	v_mfma_f32_16x16x32_bf16 v[40:43], v[158:161], v[238:241], v[40:43]
	v_mfma_f32_16x16x32_bf16 v[36:39], v[180:183], v[238:241], v[36:39]
	v_mfma_f32_16x16x32_bf16 v[64:67], v[176:179], v[192:195], v[64:67]
	v_mfma_f32_16x16x32_bf16 v[60:63], v[184:187], v[192:195], v[60:63]
	v_mfma_f32_16x16x32_bf16 v[56:59], v[176:179], v[200:203], v[56:59]
	v_mfma_f32_16x16x32_bf16 v[52:55], v[184:187], v[200:203], v[52:55]
	v_mfma_f32_16x16x32_bf16 v[48:51], v[176:179], v[234:237], v[48:51]
	v_mfma_f32_16x16x32_bf16 v[44:47], v[184:187], v[234:237], v[44:47]
	v_mfma_f32_16x16x32_bf16 v[40:43], v[176:179], v[242:245], v[40:43]
	v_mfma_f32_16x16x32_bf16 v[36:39], v[184:187], v[242:245], v[36:39]
	s_barrier
	s_add_i32 s88, s88, s1
	v_lshl_add_u64 v[210:211], s[54:55], 0, v[164:165]
	s_mov_b32 m0, s88
	ds_read_b128 v[188:191], v174 offset:16384
	ds_read_b128 v[192:195], v174 offset:17408
	ds_read_b128 v[196:199], v174 offset:18432
	ds_read_b128 v[200:203], v174 offset:19456
	ds_read_b128 v[204:207], v174 offset:20480
	ds_read_b128 v[234:237], v174 offset:21504
	ds_read_b128 v[238:241], v174 offset:22528
	ds_read_b128 v[242:245], v174 offset:23552
	global_load_lds_dwordx4 v[210:211], off
	s_add_i32 m0, s88, 0x2000
	s_add_u32 s88, s54, 0x80000
	v_lshl_add_u64 v[212:213], s[54:55], 0, v[144:145]
	s_addc_u32 s89, s55, 0
	s_add_i32 s90, s90, s1
	global_load_lds_dwordx4 v[212:213], off
	v_lshl_add_u64 v[220:221], s[88:89], 0, v[164:165]
	s_mov_b32 m0, s90
	v_lshl_add_u64 v[222:223], s[84:85], 0, v[142:143]
	global_load_lds_dwordx4 v[220:221], off
	v_lshl_add_u64 v[220:221], s[88:89], 0, v[144:145]
	s_add_i32 m0, s90, 0x2000
	s_nop 0
	global_load_lds_dwordx4 v[220:221], off
	v_lshl_add_u64 v[220:221], s[84:85], 0, v[140:141]
	s_mov_b32 m0, s5
	s_nop 0
	global_load_lds_dwordx4 v[220:221], off
	s_mov_b32 m0, s26
	s_nop 0
	global_load_lds_dwordx4 v[222:223], off
	s_waitcnt vmcnt(8)
	s_waitcnt lgkmcnt(0)
	s_barrier
; #define PG8_STAGE(bufoff, gbase, voff) do { _Pragma("unroll") for (int _i = 0; _i < 2; ++_i) \
;         __builtin_amdgcn_global_load_lds((const unsigned*)((const char*)(gbase) + (voff)[_i]), (LAS unsigned*)(lds + (bufoff) + ldsw + _i * 8192), 16, 0, 0); } while (0)
; #define PG8_LDA(dst, b, h) do { _Pragma("unroll") for (int m = 0; m < 4; ++m) _Pragma("unroll") for (int k = 0; k < 2; ++k) dst[m][k] = *(const LAS bf16x8*)(lds + PG8_SA(b, h) + aoff + m * 2048 + k * 1024); } while (0)
; #define PG8_LDB(dst, b, h) do { _Pragma("unroll") for (int n = 0; n < 2; ++n) _Pragma("unroll") for (int k = 0; k < 2; ++k) dst[n][k] = *(const LAS bf16x8*)(lds + PG8_SB(b, h) + boff + n * 2048 + k * 1024); } while (0)
; #define PG8_MMA(ai, bj, At, Bt) do { __builtin_amdgcn_s_setprio(1); _Pragma("unroll") for (int m = 0; m < 4; ++m) _Pragma("unroll") for (int n = 0; n < 2; ++n) _Pragma("unroll") for (int k = 0; k < 2; ++k) \
;         acc[ai][bj][m][n] = __builtin_amdgcn_mfma_f32_16x16x32_bf16(Bt[n][k], At[m][k], acc[ai][bj][m][n], 0, 0, 0); __builtin_amdgcn_s_setprio(0); } while (0)
; #define PG8_WAIT_V(n) asm volatile("s_waitcnt vmcnt(" #n ")" ::: "memory")
; #define PG8_WAIT_L(n) asm volatile("s_waitcnt lgkmcnt(" #n ")" ::: "memory")
; #define PG8_BAR __builtin_amdgcn_s_barrier()
; #define PG8_SCHED __builtin_amdgcn_sched_barrier(0)
; template <class Epi, class Sched>
; __device__ __forceinline__ void gemm_phase(LAS unsigned char* lds, const Gemm g, const Sched& S, const Epi& E, const int tid) {
;     ...
;             PG8_WAIT_V(8); PG8_WAIT_L(0); PG8_BAR; PG8_MMA(1, 0, At, B0); PG8_MMA(1, 1, At, B1); PG8_BAR; PG8_SCHED;
;             PG8_LDB(B0, 1, 0); PG8_LDB(B1, 1, 1); PG8_SCHED; PG8_LDA(At, 1, 0); PG8_STAGE(PG8_SA(0, 1), a2 + hstepA, voffA);
;             PG8_WAIT_V(8); PG8_WAIT_L(0); PG8_BAR; PG8_MMA(0, 0, At, B0); PG8_MMA(0, 1, At, B1); PG8_BAR; PG8_SCHED;
	s_waitcnt lgkmcnt(0)
	v_mfma_f32_16x16x32_bf16 v[96:99], v[100:103], v[188:191], v[96:99]
	v_mfma_f32_16x16x32_bf16 v[92:95], v[150:153], v[188:191], v[92:95]
	v_mfma_f32_16x16x32_bf16 v[88:91], v[100:103], v[196:199], v[88:91]
	v_mfma_f32_16x16x32_bf16 v[84:87], v[150:153], v[196:199], v[84:87]
	v_mfma_f32_16x16x32_bf16 v[80:83], v[100:103], v[204:207], v[80:83]
	v_mfma_f32_16x16x32_bf16 v[76:79], v[150:153], v[204:207], v[76:79]
	v_mfma_f32_16x16x32_bf16 v[72:75], v[100:103], v[238:241], v[72:75]
	v_mfma_f32_16x16x32_bf16 v[68:71], v[150:153], v[238:241], v[68:71]
	v_mfma_f32_16x16x32_bf16 v[96:99], v[104:107], v[192:195], v[96:99]
	v_mfma_f32_16x16x32_bf16 v[92:95], v[154:157], v[192:195], v[92:95]
	v_mfma_f32_16x16x32_bf16 v[88:91], v[104:107], v[200:203], v[88:91]
	v_mfma_f32_16x16x32_bf16 v[84:87], v[154:157], v[200:203], v[84:87]
	v_mfma_f32_16x16x32_bf16 v[80:83], v[104:107], v[234:237], v[80:83]
	v_mfma_f32_16x16x32_bf16 v[76:79], v[154:157], v[234:237], v[76:79]
	v_mfma_f32_16x16x32_bf16 v[72:75], v[104:107], v[242:245], v[72:75]
	v_mfma_f32_16x16x32_bf16 v[68:71], v[154:157], v[242:245], v[68:71]
	v_mfma_f32_16x16x32_bf16 v[32:35], v[158:161], v[188:191], v[32:35]
	v_mfma_f32_16x16x32_bf16 v[28:31], v[180:183], v[188:191], v[28:31]
	v_mfma_f32_16x16x32_bf16 v[24:27], v[158:161], v[196:199], v[24:27]
	v_mfma_f32_16x16x32_bf16 v[20:23], v[180:183], v[196:199], v[20:23]
	v_mfma_f32_16x16x32_bf16 v[16:19], v[158:161], v[204:207], v[16:19]
	v_mfma_f32_16x16x32_bf16 v[12:15], v[180:183], v[204:207], v[12:15]
	v_mfma_f32_16x16x32_bf16 v[8:11], v[158:161], v[238:241], v[8:11]
	v_mfma_f32_16x16x32_bf16 v[4:7], v[180:183], v[238:241], v[4:7]
	v_mfma_f32_16x16x32_bf16 v[32:35], v[176:179], v[192:195], v[32:35]
	v_mfma_f32_16x16x32_bf16 v[28:31], v[184:187], v[192:195], v[28:31]
	v_mfma_f32_16x16x32_bf16 v[24:27], v[176:179], v[200:203], v[24:27]
	v_mfma_f32_16x16x32_bf16 v[20:23], v[184:187], v[200:203], v[20:23]
	v_mfma_f32_16x16x32_bf16 v[16:19], v[176:179], v[234:237], v[16:19]
	v_mfma_f32_16x16x32_bf16 v[12:15], v[184:187], v[234:237], v[12:15]
	v_mfma_f32_16x16x32_bf16 v[8:11], v[176:179], v[242:245], v[8:11]
	v_mfma_f32_16x16x32_bf16 v[4:7], v[184:187], v[242:245], v[4:7]
	s_barrier
	s_add_i32 s88, 0, 0x18000
	s_add_i32 s89, 0, 0x1c000
	v_add_u32_e32 v154, s88, v163
	v_add_u32_e32 v175, s89, v163
	ds_read_b128 v[100:103], v154
	ds_read_b128 v[104:107], v154 offset:1024
	ds_read_b128 v[150:153], v154 offset:2048
	ds_read_b128 v[154:157], v154 offset:3072
	ds_read_b128 v[158:161], v175
	ds_read_b128 v[176:179], v175 offset:1024
	ds_read_b128 v[180:183], v175 offset:2048
	ds_read_b128 v[184:187], v175 offset:3072
	s_add_u32 s84, s84, 0x80000
	s_addc_u32 s85, s85, 0
	s_mov_b32 m0, s56
	v_lshl_add_u64 v[246:247], s[84:85], 0, v[140:141]
	ds_read_b128 v[188:191], v174 offset:32768
	ds_read_b128 v[192:195], v174 offset:33792
	ds_read_b128 v[196:199], v174 offset:34816
	ds_read_b128 v[200:203], v174 offset:35840
	ds_read_b128 v[204:207], v174 offset:36864
	ds_read_b128 v[234:237], v174 offset:37888
	ds_read_b128 v[238:241], v174 offset:38912
	ds_read_b128 v[242:245], v174 offset:39936
	global_load_lds_dwordx4 v[246:247], off
	v_lshl_add_u64 v[246:247], s[84:85], 0, v[142:143]
	s_mov_b32 m0, s57
	s_nop 0
	global_load_lds_dwordx4 v[246:247], off
	s_waitcnt vmcnt(8)
	s_waitcnt lgkmcnt(0)
	s_barrier
	s_waitcnt lgkmcnt(0)
	v_mfma_f32_16x16x32_bf16 v[136:139], v[100:103], v[188:191], v[136:139]
	v_mfma_f32_16x16x32_bf16 v[132:135], v[150:153], v[188:191], v[132:135]
	v_mfma_f32_16x16x32_bf16 v[128:131], v[100:103], v[196:199], v[128:131]
	v_mfma_f32_16x16x32_bf16 v[124:127], v[150:153], v[196:199], v[124:127]
	v_mfma_f32_16x16x32_bf16 v[120:123], v[100:103], v[204:207], v[120:123]
	v_mfma_f32_16x16x32_bf16 v[116:119], v[150:153], v[204:207], v[116:119]
	v_mfma_f32_16x16x32_bf16 v[112:115], v[100:103], v[238:241], v[112:115]
	v_mfma_f32_16x16x32_bf16 v[108:111], v[150:153], v[238:241], v[108:111]
	v_mfma_f32_16x16x32_bf16 v[136:139], v[104:107], v[192:195], v[136:139]
	v_mfma_f32_16x16x32_bf16 v[132:135], v[154:157], v[192:195], v[132:135]
	v_mfma_f32_16x16x32_bf16 v[128:131], v[104:107], v[200:203], v[128:131]
	v_mfma_f32_16x16x32_bf16 v[124:127], v[154:157], v[200:203], v[124:127]
	v_mfma_f32_16x16x32_bf16 v[120:123], v[104:107], v[234:237], v[120:123]
	v_mfma_f32_16x16x32_bf16 v[116:119], v[154:157], v[234:237], v[116:119]
	v_mfma_f32_16x16x32_bf16 v[112:115], v[104:107], v[242:245], v[112:115]
	v_mfma_f32_16x16x32_bf16 v[108:111], v[154:157], v[242:245], v[108:111]
	v_mfma_f32_16x16x32_bf16 v[64:67], v[158:161], v[188:191], v[64:67]
	v_mfma_f32_16x16x32_bf16 v[60:63], v[180:183], v[188:191], v[60:63]
	v_mfma_f32_16x16x32_bf16 v[56:59], v[158:161], v[196:199], v[56:59]
	v_mfma_f32_16x16x32_bf16 v[52:55], v[180:183], v[196:199], v[52:55]
	v_mfma_f32_16x16x32_bf16 v[48:51], v[158:161], v[204:207], v[48:51]
	v_mfma_f32_16x16x32_bf16 v[44:47], v[180:183], v[204:207], v[44:47]
	v_mfma_f32_16x16x32_bf16 v[40:43], v[158:161], v[238:241], v[40:43]
	v_mfma_f32_16x16x32_bf16 v[36:39], v[180:183], v[238:241], v[36:39]
	v_mfma_f32_16x16x32_bf16 v[64:67], v[176:179], v[192:195], v[64:67]
	v_mfma_f32_16x16x32_bf16 v[60:63], v[184:187], v[192:195], v[60:63]
	v_mfma_f32_16x16x32_bf16 v[56:59], v[176:179], v[200:203], v[56:59]
	v_mfma_f32_16x16x32_bf16 v[52:55], v[184:187], v[200:203], v[52:55]
	v_mfma_f32_16x16x32_bf16 v[48:51], v[176:179], v[234:237], v[48:51]
	v_mfma_f32_16x16x32_bf16 v[44:47], v[184:187], v[234:237], v[44:47]
	v_mfma_f32_16x16x32_bf16 v[40:43], v[176:179], v[242:245], v[40:43]
	v_mfma_f32_16x16x32_bf16 v[36:39], v[184:187], v[242:245], v[36:39]
	s_barrier
; #define PG8_STAGE(bufoff, gbase, voff) do { _Pragma("unroll") for (int _i = 0; _i < 2; ++_i) \
;         __builtin_amdgcn_global_load_lds((const unsigned*)((const char*)(gbase) + (voff)[_i]), (LAS unsigned*)(lds + (bufoff) + ldsw + _i * 8192), 16, 0, 0); } while (0)
; #define PG8_LDA(dst, b, h) do { _Pragma("unroll") for (int m = 0; m < 4; ++m) _Pragma("unroll") for (int k = 0; k < 2; ++k) dst[m][k] = *(const LAS bf16x8*)(lds + PG8_SA(b, h) + aoff + m * 2048 + k * 1024); } while (0)
; #define PG8_MMA(ai, bj, At, Bt) do { __builtin_amdgcn_s_setprio(1); _Pragma("unroll") for (int m = 0; m < 4; ++m) _Pragma("unroll") for (int n = 0; n < 2; ++n) _Pragma("unroll") for (int k = 0; k < 2; ++k) \
;         acc[ai][bj][m][n] = __builtin_amdgcn_mfma_f32_16x16x32_bf16(Bt[n][k], At[m][k], acc[ai][bj][m][n], 0, 0, 0); __builtin_amdgcn_s_setprio(0); } while (0)
; #define PG8_WAIT_V(n) asm volatile("s_waitcnt vmcnt(" #n ")" ::: "memory")
; #define PG8_WAIT_L(n) asm volatile("s_waitcnt lgkmcnt(" #n ")" ::: "memory")
; #define PG8_BAR __builtin_amdgcn_s_barrier()
; #define PG8_SCHED __builtin_amdgcn_sched_barrier(0)
; template <class Epi, class Sched>
; __device__ __forceinline__ void gemm_phase(LAS unsigned char* lds, const Gemm g, const Sched& S, const Epi& E, const int tid) {
;     ...
;             PG8_LDA(At, 1, 1); PG8_STAGE(PG8_SB(1, 0), b3, voffB); PG8_STAGE(PG8_SB(1, 1), b3 + hstepB, voffB); PG8_STAGE(PG8_SA(1, 0), a3, voffA);
;             PG8_WAIT_V(8); PG8_WAIT_L(0); PG8_BAR; PG8_MMA(1, 0, At, B0); PG8_MMA(1, 1, At, B1); PG8_BAR; PG8_SCHED;
;         }
;         if (wr == 0) PG8_BAR;
	s_add_i32 s84, s88, s1
	v_lshl_add_u64 v[210:211], v[210:211], 0, s[28:29]
	s_mov_b32 m0, s84
	ds_read_b128 v[188:191], v174 offset:49152
	ds_read_b128 v[192:195], v174 offset:50176
	ds_read_b128 v[196:199], v174 offset:51200
	ds_read_b128 v[200:203], v174 offset:52224
	ds_read_b128 v[204:207], v174 offset:53248
	ds_read_b128 v[234:237], v174 offset:54272
	ds_read_b128 v[238:241], v174 offset:55296
	ds_read_b128 v[242:245], v174 offset:56320
	global_load_lds_dwordx4 v[210:211], off
	s_add_i32 m0, s84, 0x2000
	s_add_u32 s54, s54, 0x80080
	v_lshl_add_u64 v[210:211], v[212:213], 0, s[28:29]
	s_addc_u32 s55, s55, 0
	s_add_i32 s84, s89, s1
	global_load_lds_dwordx4 v[210:211], off
	v_lshl_add_u64 v[210:211], s[54:55], 0, v[164:165]
	s_mov_b32 m0, s84
	s_nop 0
	global_load_lds_dwordx4 v[210:211], off
	v_lshl_add_u64 v[210:211], s[54:55], 0, v[144:145]
	s_add_i32 m0, s84, 0x2000
	s_nop 0
	global_load_lds_dwordx4 v[210:211], off
	v_lshl_add_u64 v[210:211], v[220:221], 0, s[28:29]
	s_mov_b32 m0, s58
	s_nop 0
	global_load_lds_dwordx4 v[210:211], off
	v_lshl_add_u64 v[210:211], v[222:223], 0, s[28:29]
	s_mov_b32 m0, s59
	s_nop 0
	global_load_lds_dwordx4 v[210:211], off
	s_waitcnt vmcnt(8)
	s_waitcnt lgkmcnt(0)
	s_barrier
	s_waitcnt lgkmcnt(0)
	v_mfma_f32_16x16x32_bf16 v[96:99], v[100:103], v[188:191], v[96:99]
	v_mfma_f32_16x16x32_bf16 v[92:95], v[150:153], v[188:191], v[92:95]
	v_mfma_f32_16x16x32_bf16 v[88:91], v[100:103], v[196:199], v[88:91]
	v_mfma_f32_16x16x32_bf16 v[84:87], v[150:153], v[196:199], v[84:87]
	v_mfma_f32_16x16x32_bf16 v[80:83], v[100:103], v[204:207], v[80:83]
	v_mfma_f32_16x16x32_bf16 v[76:79], v[150:153], v[204:207], v[76:79]
	v_mfma_f32_16x16x32_bf16 v[72:75], v[100:103], v[238:241], v[72:75]
	v_mfma_f32_16x16x32_bf16 v[68:71], v[150:153], v[238:241], v[68:71]
	v_mfma_f32_16x16x32_bf16 v[96:99], v[104:107], v[192:195], v[96:99]
	v_mfma_f32_16x16x32_bf16 v[92:95], v[154:157], v[192:195], v[92:95]
	v_mfma_f32_16x16x32_bf16 v[88:91], v[104:107], v[200:203], v[88:91]
	v_mfma_f32_16x16x32_bf16 v[84:87], v[154:157], v[200:203], v[84:87]
	v_mfma_f32_16x16x32_bf16 v[80:83], v[104:107], v[234:237], v[80:83]
	v_mfma_f32_16x16x32_bf16 v[76:79], v[154:157], v[234:237], v[76:79]
	v_mfma_f32_16x16x32_bf16 v[72:75], v[104:107], v[242:245], v[72:75]
	v_mfma_f32_16x16x32_bf16 v[68:71], v[154:157], v[242:245], v[68:71]
	v_mfma_f32_16x16x32_bf16 v[32:35], v[158:161], v[188:191], v[32:35]
	v_mfma_f32_16x16x32_bf16 v[28:31], v[180:183], v[188:191], v[28:31]
	v_mfma_f32_16x16x32_bf16 v[24:27], v[158:161], v[196:199], v[24:27]
	v_mfma_f32_16x16x32_bf16 v[20:23], v[180:183], v[196:199], v[20:23]
	v_mfma_f32_16x16x32_bf16 v[16:19], v[158:161], v[204:207], v[16:19]
	v_mfma_f32_16x16x32_bf16 v[12:15], v[180:183], v[204:207], v[12:15]
	v_mfma_f32_16x16x32_bf16 v[8:11], v[158:161], v[238:241], v[8:11]
	v_mfma_f32_16x16x32_bf16 v[4:7], v[180:183], v[238:241], v[4:7]
	v_mfma_f32_16x16x32_bf16 v[32:35], v[176:179], v[192:195], v[32:35]
	v_mfma_f32_16x16x32_bf16 v[28:31], v[184:187], v[192:195], v[28:31]
	v_mfma_f32_16x16x32_bf16 v[24:27], v[176:179], v[200:203], v[24:27]
	v_mfma_f32_16x16x32_bf16 v[20:23], v[184:187], v[200:203], v[20:23]
	v_mfma_f32_16x16x32_bf16 v[16:19], v[176:179], v[234:237], v[16:19]
	v_mfma_f32_16x16x32_bf16 v[12:15], v[184:187], v[234:237], v[12:15]
	v_mfma_f32_16x16x32_bf16 v[8:11], v[176:179], v[242:245], v[8:11]
	v_mfma_f32_16x16x32_bf16 v[4:7], v[184:187], v[242:245], v[4:7]
	s_barrier
	s_add_i32 s87, s87, 2
	s_add_u32 s46, s46, 0x100
	s_addc_u32 s47, s47, 0
	s_add_u32 s39, s39, 0x100
	s_addc_u32 s86, s86, 0
	s_cmp_gt_u32 s87, 29
	s_cbranch_scc0 .LBB0_589
	s_and_b64 vcc, exec, s[16:17]
	s_cbranch_vccz .LBB0_592
	s_barrier
